# RG-LRU gate weights stored fragment-major by the convert phase: each wave fragment load is one contiguous 1 KiB block
# speedup vs baseline: 1.0225x; 1.0111x over previous
.LBB0_211:
	v_bfe_u32 v13, v7, 5, 1
	v_bfe_u32 v14, v7, 3, 2
	v_lshlrev_b32_e32 v13, 9, v13
	v_lshl_or_b32 v13, v14, 7, v13
	v_bfe_u32 v14, v7, 6, 4
	v_lshl_or_b32 v13, v14, 3, v13
	v_and_b32_e32 v14, 0xfffffc07, v7
	v_or_b32_e32 v13, v13, v14
	v_sub_u32_e32 v13, v13, v7
	v_lshlrev_b32_e32 v14, 1, v13
	v_ashrrev_i32_e32 v15, 31, v14
	v_bfe_u32 v8, v7, 6, 6
	v_and_b32_e32 v10, 0xfffff000, v7
	v_and_b32_e32 v11, 0xfc0, v6
	v_ashrrev_i32_e32 v9, 31, v10
	v_or3_b32 v8, v10, v11, v8
	s_mov_b64 s[26:27], s[38:39]
	v_lshl_add_u64 v[8:9], v[8:9], 2, v[252:253]
	v_readlane_b32 s44, v254, 6
	v_lshl_add_u64 v[10:11], s[26:27], 0, v[8:9]
	flat_load_dword v10, v[10:11]
	s_mov_b64 s[26:27], s[42:43]
	v_readlane_b32 s52, v254, 14
	v_readlane_b32 s53, v254, 15
	v_add_u32_e32 v7, s6, v7
	v_add_u32_e32 v6, s2, v6
	v_readlane_b32 s45, v254, 7
	v_readlane_b32 s46, v254, 8
	v_readlane_b32 s47, v254, 9
	v_readlane_b32 s48, v254, 10
	v_readlane_b32 s49, v254, 11
	v_readlane_b32 s50, v254, 12
	v_readlane_b32 s51, v254, 13
	v_readlane_b32 s54, v254, 16
	v_readlane_b32 s55, v254, 17
	v_readlane_b32 s56, v254, 18
	v_readlane_b32 s57, v254, 19
	v_readlane_b32 s58, v254, 20
	v_readlane_b32 s59, v254, 21
	s_waitcnt vmcnt(0) lgkmcnt(0)
	v_bfe_u32 v11, v10, 16, 1
	v_add3_u32 v12, v10, v11, s83
	v_add_co_u32_e32 v10, vcc, s69, v4
	s_nop 1
	v_addc_co_u32_e32 v11, vcc, -1, v5, vcc
	v_lshl_add_u64 v[10:11], v[10:11], 0, v[14:15]
	flat_store_short_d16_hi v[10:11], v12
	s_nop 0
	v_lshl_add_u64 v[8:9], s[26:27], 0, v[8:9]
	flat_load_dword v8, v[8:9]
	s_mov_b64 s[26:27], s[52:53]
	s_waitcnt vmcnt(0) lgkmcnt(0)
	v_bfe_u32 v9, v8, 16, 1
	v_add3_u32 v10, v8, v9, s83
	v_add_co_u32_e32 v8, vcc, s28, v4
	s_nop 1
	v_addc_co_u32_e32 v9, vcc, -1, v5, vcc
	v_lshl_add_u64 v[8:9], v[8:9], 0, v[14:15]
	flat_store_short_d16_hi v[8:9], v10
	v_cmp_lt_i32_e32 vcc, s29, v7
	v_lshl_add_u64 v[8:9], s[26:27], 0, v[2:3]
	flat_load_dword v8, v[8:9]
	v_lshl_add_u64 v[2:3], v[2:3], 0, s[22:23]
	s_or_b64 s[24:25], vcc, s[24:25]
	s_waitcnt vmcnt(0) lgkmcnt(0)
	v_bfe_u32 v9, v8, 16, 1
	v_add3_u32 v8, v8, v9, s83
	flat_store_short_d16_hi v[4:5], v8
	v_lshl_add_u64 v[4:5], v[4:5], 0, s[20:21]
	s_andn2_b64 exec, exec, s[24:25]
	s_cbranch_execnz .LBB0_211

.LBB0_355:
	s_or_b64 exec, exec, s[8:9]
	v_mov_b32_e32 v161, v191
	s_waitcnt lgkmcnt(0)
	s_barrier
	v_mov_b32_e32 v162, v191
	v_and_b32_e32 v168, 15, v161
	v_lshrrev_b32_e32 v169, 4, v161
	v_bfe_u32 v170, v161, 4, 2
	s_mov_b64 s[2:3], s[74:75]
	v_bfe_u32 v163, v161, 1, 3
	v_ashrrev_i32_e32 v141, 6, v161
	v_lshlrev_b32_e32 v142, 7, v168
	v_bitop3_b32 v8, v169, v163, 3 bitop3:0x6c
	v_bitop3_b32 v13, v170, v163, 4 bitop3:0x36
	v_lshl_or_b32 v12, v141, 11, v142
	v_lshlrev_b32_e32 v8, 4, v8
	v_lshlrev_b32_e32 v13, 4, v13
	s_add_u32 s2, s2, s29
	v_add3_u32 v8, s60, v8, v12
	v_add3_u32 v12, s60, v13, v12
	s_addc_u32 s3, s3, 0
	v_lshlrev_b32_e32 v144, 4, v170
	ds_read_b128 v[8:11], v8
	ds_read_b128 v[72:75], v12
	v_lshl_add_u64 v[12:13], s[2:3], 0, v[144:145]
	s_mov_b64 s[2:3], 0x3980000
	v_lshl_add_u64 v[164:165], v[12:13], 0, s[2:3]
	s_mov_b64 s[2:3], 0x39a0000
	v_mov_b32_e32 v143, v145
	v_lshl_add_u64 v[166:167], v[12:13], 0, s[2:3]
	v_mul_u32_u24_e32 v184, 0xf0, v170
	v_lshl_add_u32 v184, v168, 4, v184
	v_mov_b32_e32 v185, v145
	v_lshl_add_u64 v[60:61], v[164:165], 0, v[184:185]
	v_lshl_add_u64 v[62:63], v[166:167], 0, v[184:185]
	flat_load_dwordx4 v[12:15], v[60:61]
	flat_load_dwordx4 v[48:51], v[62:63]
	flat_load_dwordx4 v[52:55], v[60:61] offset:1024
	flat_load_dwordx4 v[56:59], v[62:63] offset:1024
	v_lshrrev_b32_e32 v172, 1, v161
	v_readlane_b32 s40, v254, 22
	v_readlane_b32 s44, v254, 26
	v_readlane_b32 s45, v254, 27
	s_mov_b64 s[2:3], s[44:45]
	v_readlane_b32 s48, v254, 30
	v_readlane_b32 s49, v254, 31
	s_mov_b64 s[8:9], s[48:49]
	s_mov_b32 s37, 0x122e6000
	s_mov_b32 s38, 0xc1000000
	v_readlane_b32 s41, v254, 23
	v_readlane_b32 s42, v254, 24
	v_readlane_b32 s43, v254, 25
	v_readlane_b32 s46, v254, 28
	v_readlane_b32 s47, v254, 29
	v_readlane_b32 s50, v254, 32
	v_readlane_b32 s51, v254, 33
	v_readlane_b32 s52, v254, 34
	v_readlane_b32 s53, v254, 35
	v_readlane_b32 s54, v254, 36
	v_readlane_b32 s55, v254, 37
	s_waitcnt vmcnt(0) lgkmcnt(0)
	v_mfma_f32_16x16x32_bf16 v[12:15], v[12:15], v[8:11], 0
	v_mfma_f32_16x16x32_bf16 v[48:51], v[48:51], v[8:11], 0
	v_mfma_f32_16x16x32_bf16 v[68:71], v[52:55], v[72:75], v[12:15]
	v_mfma_f32_16x16x32_bf16 v[64:67], v[56:59], v[72:75], v[48:51]
	s_nop 4
	flat_load_dwordx4 v[12:15], v[60:61] offset:2048
	flat_load_dwordx4 v[48:51], v[62:63] offset:2048
	flat_load_dwordx4 v[52:55], v[60:61] offset:3072
	flat_load_dwordx4 v[56:59], v[62:63] offset:3072
	s_waitcnt vmcnt(0) lgkmcnt(0)
	v_mfma_f32_16x16x32_bf16 v[12:15], v[12:15], v[8:11], 0
	v_mfma_f32_16x16x32_bf16 v[48:51], v[48:51], v[8:11], 0
	v_mfma_f32_16x16x32_bf16 v[60:63], v[52:55], v[72:75], v[12:15]
	s_nop 5
	v_or_b32_e32 v12, 0x1000, v184
	v_mov_b32_e32 v13, v145
	v_lshl_add_u64 v[52:53], v[164:165], 0, v[12:13]
	v_mfma_f32_16x16x32_bf16 v[56:59], v[56:59], v[72:75], v[48:51]
	v_lshl_add_u64 v[146:147], v[166:167], 0, v[12:13]
	flat_load_dwordx4 v[12:15], v[52:53]
	s_nop 0
	flat_load_dwordx4 v[48:51], v[146:147]
	s_nop 0
	flat_load_dwordx4 v[52:55], v[52:53] offset:1024
	s_nop 0
	flat_load_dwordx4 v[146:149], v[146:147] offset:1024
	s_waitcnt vmcnt(0) lgkmcnt(0)
	v_mfma_f32_16x16x32_bf16 v[12:15], v[12:15], v[8:11], 0
	v_mfma_f32_16x16x32_bf16 v[48:51], v[48:51], v[8:11], 0
	v_mfma_f32_16x16x32_bf16 v[52:55], v[52:55], v[72:75], v[12:15]
	s_nop 5
	v_or_b32_e32 v12, 0x1800, v184
	v_mov_b32_e32 v13, v145
	v_lshl_add_u64 v[142:143], v[164:165], 0, v[12:13]
	v_mfma_f32_16x16x32_bf16 v[48:51], v[146:149], v[72:75], v[48:51]
	v_lshl_add_u64 v[164:165], v[166:167], 0, v[12:13]
	flat_load_dwordx4 v[12:15], v[142:143]
	flat_load_dwordx4 v[146:149], v[164:165]
	s_waitcnt vmcnt(0) lgkmcnt(0)
	v_mfma_f32_16x16x32_bf16 v[12:15], v[12:15], v[8:11], 0
	v_mfma_f32_16x16x32_bf16 v[8:11], v[146:149], v[8:11], 0
	flat_load_dwordx4 v[146:149], v[142:143] offset:1024
	s_nop 0
	flat_load_dwordx4 v[164:167], v[164:165] offset:1024
	v_lshlrev_b32_e32 v142, 2, v170
	v_mov_b32_e32 v143, v145
	v_or_b32_e32 v180, s22, v142
	v_ashrrev_i32_e32 v181, 31, v180
	v_lshlrev_b64 v[180:181], 2, v[180:181]
	s_add_u32 s98, s74, s30
	s_addc_u32 s99, s75, 0
	s_add_u32 s98, s98, 0x122e6000
	s_addc_u32 s99, s99, 0
	v_lshl_add_u64 v[184:185], s[98:99], 0, v[144:145]
	v_lshl_add_u64 v[178:179], s[44:45], 0, v[180:181]
	v_lshl_add_u64 v[182:183], s[48:49], 0, v[180:181]
	global_load_dwordx4 v[216:219], v[178:179], off
	global_load_dwordx4 v[220:223], v[182:183], off
	global_load_dwordx4 v[224:227], v[184:185], off
	global_load_dwordx4 v[228:231], v[178:179], off offset:64
	global_load_dwordx4 v[232:235], v[182:183], off offset:64
	global_load_dwordx4 v[236:239], v[184:185], off offset:64
	global_load_dwordx4 v[240:243], v[178:179], off offset:128
	global_load_dwordx4 v[244:247], v[182:183], off offset:128
	global_load_dwordx4 v[248:251], v[184:185], off offset:128
	global_load_dwordx4 v[178:181], v[178:179], off offset:192
	global_load_dwordx4 v[182:185], v[182:183], off offset:192
	s_waitcnt vmcnt(0) lgkmcnt(0)
	v_mfma_f32_16x16x32_bf16 v[12:15], v[146:149], v[72:75], v[12:15]
	v_mfma_f32_16x16x32_bf16 v[8:11], v[164:167], v[72:75], v[8:11]
	v_lshl_or_b32 v72, v141, 4, v168
	v_lshlrev_b32_e32 v164, 7, v72
	v_and_b32_e32 v73, 8, v172
	v_lshlrev_b32_e32 v167, 8, v72
	v_or_b32_e32 v72, s22, v142
	v_add_u32_e32 v166, s60, v73
	v_ashrrev_i32_e32 v73, 31, v72
	v_lshlrev_b64 v[146:147], 2, v[72:73]
	v_lshl_add_u64 v[72:73], s[2:3], 0, v[146:147]
	s_mov_b64 s[2:3], s[74:75]
	v_lshl_add_u64 v[146:147], s[8:9], 0, v[146:147]
	s_add_u32 s2, s2, s30
	s_addc_u32 s3, s3, 0
	v_bfe_u32 v165, v169, 1, 1
	v_lshl_add_u64 v[168:169], s[2:3], 0, v[144:145]
	v_add_co_u32_e64 v168, s[8:9], s37, v168
	v_bitop3_b32 v172, v165, v172, 7 bitop3:0x78
	s_nop 0
	v_addc_co_u32_e64 v169, s[8:9], 0, v169, s[8:9]
	v_lshlrev_b32_e32 v172, 4, v172
	v_add3_u32 v172, v166, v172, v164
	ds_read_b64 v[172:173], v172
	s_mov_b64 s[2:3], s[44:45]
	s_waitcnt lgkmcnt(0)
	v_lshlrev_b32_e32 v174, 16, v172
	v_and_b32_e32 v175, 0xffff0000, v172
	v_lshlrev_b32_e32 v172, 16, v173
	v_and_b32_e32 v173, 0xffff0000, v173
	v_add_f32_e32 v68, v68, v216
	v_add_f32_e32 v69, v69, v217
	v_mul_f32_e32 v68, 0xbfb8aa3b, v68
	v_mul_f32_e32 v69, 0xbfb8aa3b, v69
	v_exp_f32_e32 v68, v68
	v_exp_f32_e32 v69, v69
	v_add_f32_e32 v64, v64, v220
	v_add_f32_e32 v65, v65, v221
	v_add_f32_e32 v68, 1.0, v68
	v_add_f32_e32 v69, 1.0, v69
	v_rcp_f32_e32 v68, v68
	v_rcp_f32_e32 v69, v69
	v_add_f32_e32 v70, v70, v218
	v_add_f32_e32 v71, v71, v219
	v_mul_f32_e32 v70, 0xbfb8aa3b, v70
	v_pk_mul_f32 v[68:69], v[68:69], s[38:39] op_sel_hi:[1,0]
	v_mul_f32_e32 v71, 0xbfb8aa3b, v71
	v_pk_mul_f32 v[72:73], v[224:225], v[68:69]
	v_exp_f32_e32 v70, v70
	v_pk_add_f32 v[146:147], v[72:73], v[72:73]
	v_mul_f32_e32 v68, 0x3fb8aa3b, v72
	v_fmamk_f32 v69, v146, 0x3ab60b61, v195
	v_exp_f32_e32 v68, v68
	v_fmaak_f32 v69, v146, v69, 0x3d2aaaab
	v_fmaak_f32 v69, v146, v69, 0x3e2aaaab
	v_exp_f32_e32 v71, v71
	v_fma_f32 v69, v146, v69, 0.5
	v_fma_f32 v69, v146, v69, 1.0
	v_mul_f32_e64 v69, v69, -v146
	v_fma_f32 v72, -v68, v68, 1.0
	v_cmp_lt_f32_e64 s[12:13], s84, v146
	v_add_f32_e32 v70, 1.0, v70
	v_add_f32_e32 v71, 1.0, v71
	v_cndmask_b32_e64 v69, v72, v69, s[12:13]
	v_sqrt_f32_e32 v72, v69
	v_mul_f32_e32 v69, 0x3fb8aa3b, v73
	v_fmamk_f32 v73, v147, 0x3ab60b61, v195
	v_rcp_f32_e32 v70, v70
	v_rcp_f32_e32 v71, v71
	v_exp_f32_e32 v69, v69
	v_fmaak_f32 v73, v147, v73, 0x3d2aaaab
	v_fmaak_f32 v73, v147, v73, 0x3e2aaaab
	v_fma_f32 v73, v147, v73, 0.5
	v_fma_f32 v73, v147, v73, 1.0
	v_pk_mul_f32 v[70:71], v[70:71], s[38:39] op_sel_hi:[1,0]
	v_cmp_lt_f32_e64 s[8:9], s84, v147
	v_mul_f32_e64 v73, v73, -v147
	v_fma_f32 v146, -v69, v69, 1.0
	v_pk_mul_f32 v[74:75], v[226:227], v[70:71]
	v_cndmask_b32_e64 v73, v146, v73, s[8:9]
	v_pk_add_f32 v[146:147], v[74:75], v[74:75]
	v_mul_f32_e32 v70, 0x3fb8aa3b, v74
	v_fmamk_f32 v71, v146, 0x3ab60b61, v195
	v_exp_f32_e32 v70, v70
	v_fmaak_f32 v71, v146, v71, 0x3d2aaaab
	v_fmaak_f32 v71, v146, v71, 0x3e2aaaab
	v_fma_f32 v71, v146, v71, 0.5
	v_fma_f32 v71, v146, v71, 1.0
	v_mul_f32_e64 v71, v71, -v146
	v_fma_f32 v74, -v70, v70, 1.0
	v_cmp_lt_f32_e64 s[12:13], s84, v146
	v_add_f32_e32 v66, v66, v222
	v_add_f32_e32 v67, v67, v223
	v_cndmask_b32_e64 v71, v74, v71, s[12:13]
	v_sqrt_f32_e32 v74, v71
	v_mul_f32_e32 v71, 0x3fb8aa3b, v75
	v_fmamk_f32 v75, v147, 0x3ab60b61, v195
	v_mul_f32_e32 v64, 0xbfb8aa3b, v64
	v_mul_f32_e32 v65, 0xbfb8aa3b, v65
	v_mul_f32_e32 v66, 0xbfb8aa3b, v66
	v_mul_f32_e32 v67, 0xbfb8aa3b, v67
	v_exp_f32_e32 v71, v71
	v_fmaak_f32 v75, v147, v75, 0x3d2aaaab
	v_exp_f32_e32 v64, v64
	v_exp_f32_e32 v65, v65
	v_exp_f32_e32 v66, v66
	v_exp_f32_e32 v67, v67
	v_fmaak_f32 v75, v147, v75, 0x3e2aaaab
	v_fma_f32 v75, v147, v75, 0.5
	v_fma_f32 v75, v147, v75, 1.0
	v_cmp_lt_f32_e64 s[8:9], s84, v147
	v_mul_f32_e64 v75, v75, -v147
	v_fma_f32 v146, -v71, v71, 1.0
	v_add_f32_e32 v64, 1.0, v64
	v_add_f32_e32 v65, 1.0, v65
	v_add_f32_e32 v66, 1.0, v66
	v_add_f32_e32 v67, 1.0, v67
	v_cndmask_b32_e64 v75, v146, v75, s[8:9]
	v_rcp_f32_e32 v64, v64
	v_rcp_f32_e32 v65, v65
	v_sqrt_f32_e32 v73, v73
	v_rcp_f32_e32 v66, v66
	v_rcp_f32_e32 v67, v67
	v_sqrt_f32_e32 v75, v75
	v_pk_mul_f32 v[64:65], v[64:65], v[72:73]
	v_pk_mul_f32 v[66:67], v[66:67], v[74:75]
	v_pk_mul_f32 v[72:73], v[64:65], v[174:175]
	v_pk_mul_f32 v[74:75], v[66:67], v[172:173]
	v_add3_u32 v66, s60, v167, v144
	v_lshl_add_u64 v[64:65], v[142:143], 0, s[22:23]
	ds_write_b128 v66, v[68:71] offset:8192
	ds_write_b128 v66, v[72:75] offset:24576
	v_lshlrev_b64 v[64:65], 2, v[64:65]
	v_lshl_add_u64 v[68:69], s[2:3], 0, v[64:65]
	s_mov_b64 s[2:3], s[48:49]
	v_bitop3_b32 v67, v165, v163, 2 bitop3:0x36
	v_lshl_add_u64 v[72:73], s[2:3], 0, v[64:65]
	s_mov_b64 s[2:3], s[74:75]
	s_add_u32 s2, s2, s30
	s_addc_u32 s3, s3, 0
	v_lshl_add_u64 v[142:143], s[2:3], 0, v[144:145]
	v_add_co_u32_e64 v142, s[8:9], s37, v142
	v_lshlrev_b32_e32 v67, 4, v67
	s_nop 0
	v_addc_co_u32_e64 v143, s[8:9], 0, v143, s[8:9]
	v_add3_u32 v67, v166, v67, v164
	ds_read_b64 v[142:143], v67
	s_mov_b64 s[2:3], s[44:45]
	s_waitcnt lgkmcnt(0)
	v_lshlrev_b32_e32 v168, 16, v142
	v_and_b32_e32 v169, 0xffff0000, v142
	v_lshlrev_b32_e32 v142, 16, v143
	v_and_b32_e32 v143, 0xffff0000, v143
	v_add_f32_e32 v60, v60, v228
	v_mul_f32_e32 v60, 0xbfb8aa3b, v60
	v_exp_f32_e32 v60, v60
	v_add_f32_e32 v62, v62, v230
	v_add_f32_e32 v56, v56, v232
	v_mul_f32_e32 v56, 0xbfb8aa3b, v56
	v_exp_f32_e32 v56, v56
	v_add_f32_e32 v58, v58, v234
	v_mul_f32_e32 v58, 0xbfb8aa3b, v58
	v_exp_f32_e32 v58, v58
	v_add_f32_e32 v56, 1.0, v56
	v_rcp_f32_e32 v68, v56
	v_add_f32_e32 v56, v61, v229
	v_mul_f32_e32 v56, 0xbfb8aa3b, v56
	v_exp_f32_e32 v56, v56
	v_add_f32_e32 v60, 1.0, v60
	v_rcp_f32_e32 v60, v60
	v_add_f32_e32 v58, 1.0, v58
	v_add_f32_e32 v56, 1.0, v56
	v_rcp_f32_e32 v61, v56
	v_add_f32_e32 v56, v57, v233
	v_mul_f32_e32 v56, 0xbfb8aa3b, v56
	v_exp_f32_e32 v56, v56
	v_rcp_f32_e32 v70, v58
	v_add_f32_e32 v58, v63, v231
	v_mul_f32_e32 v58, 0xbfb8aa3b, v58
	v_add_f32_e32 v56, 1.0, v56
	v_rcp_f32_e32 v69, v56
	v_pk_mul_f32 v[56:57], v[60:61], s[38:39] op_sel_hi:[1,0]
	v_exp_f32_e32 v58, v58
	v_pk_mul_f32 v[60:61], v[236:237], v[56:57]
	v_mul_f32_e32 v62, 0xbfb8aa3b, v62
	v_pk_add_f32 v[72:73], v[60:61], v[60:61]
	v_mul_f32_e32 v56, 0x3fb8aa3b, v60
	v_fmamk_f32 v57, v72, 0x3ab60b61, v195
	v_exp_f32_e32 v56, v56
	v_fmaak_f32 v57, v72, v57, 0x3d2aaaab
	v_exp_f32_e32 v62, v62
	v_fmaak_f32 v57, v72, v57, 0x3e2aaaab
	v_add_f32_e32 v58, 1.0, v58
	v_fma_f32 v57, v72, v57, 0.5
	v_rcp_f32_e32 v63, v58
	v_add_f32_e32 v58, v59, v235
	v_fma_f32 v57, v72, v57, 1.0
	v_mul_f32_e32 v58, 0xbfb8aa3b, v58
	v_mul_f32_e64 v57, v57, -v72
	v_fma_f32 v60, -v56, v56, 1.0
	v_cmp_lt_f32_e64 s[12:13], s84, v72
	v_add_f32_e32 v62, 1.0, v62
	v_exp_f32_e32 v58, v58
	v_cndmask_b32_e64 v57, v60, v57, s[12:13]
	v_rcp_f32_e32 v62, v62
	v_sqrt_f32_e32 v60, v57
	v_mul_f32_e32 v57, 0x3fb8aa3b, v61
	v_fmamk_f32 v61, v73, 0x3ab60b61, v195
	v_fmaak_f32 v61, v73, v61, 0x3d2aaaab
	v_fmaak_f32 v61, v73, v61, 0x3e2aaaab
	v_add_f32_e32 v58, 1.0, v58
	v_fma_f32 v61, v73, v61, 0.5
	v_rcp_f32_e32 v71, v58
	v_pk_mul_f32 v[58:59], v[62:63], s[38:39] op_sel_hi:[1,0]
	v_fma_f32 v61, v73, v61, 1.0
	v_pk_mul_f32 v[62:63], v[238:239], v[58:59]
	v_cmp_lt_f32_e64 s[8:9], s84, v73
	v_mul_f32_e64 v61, v61, -v73
	v_pk_add_f32 v[72:73], v[62:63], v[62:63]
	v_mul_f32_e32 v58, 0x3fb8aa3b, v62
	v_fmamk_f32 v59, v72, 0x3ab60b61, v195
	v_exp_f32_e32 v58, v58
	v_fmaak_f32 v59, v72, v59, 0x3d2aaaab
	v_fmaak_f32 v59, v72, v59, 0x3e2aaaab
	v_fma_f32 v59, v72, v59, 0.5
	v_fma_f32 v59, v72, v59, 1.0
	v_mul_f32_e64 v59, v59, -v72
	v_fma_f32 v62, -v58, v58, 1.0
	v_cmp_lt_f32_e64 s[12:13], s84, v72
	v_exp_f32_e32 v57, v57
	s_nop 0
	v_cndmask_b32_e64 v59, v62, v59, s[12:13]
	v_sqrt_f32_e32 v62, v59
	v_mul_f32_e32 v59, 0x3fb8aa3b, v63
	v_fmamk_f32 v63, v73, 0x3ab60b61, v195
	v_exp_f32_e32 v59, v59
	v_fmaak_f32 v63, v73, v63, 0x3d2aaaab
	v_fmaak_f32 v63, v73, v63, 0x3e2aaaab
	v_fma_f32 v63, v73, v63, 0.5
	v_fma_f32 v67, -v57, v57, 1.0
	v_fma_f32 v63, v73, v63, 1.0
	v_cndmask_b32_e64 v61, v67, v61, s[8:9]
	v_cmp_lt_f32_e64 s[8:9], s84, v73
	v_mul_f32_e64 v63, v63, -v73
	v_fma_f32 v67, -v59, v59, 1.0
	v_cndmask_b32_e64 v63, v67, v63, s[8:9]
	v_sqrt_f32_e32 v61, v61
	v_sqrt_f32_e32 v63, v63
	v_bitop3_b32 v67, v165, v163, 4 bitop3:0x36
	v_lshlrev_b32_e32 v67, 4, v67
	v_pk_mul_f32 v[60:61], v[68:69], v[60:61]
	v_pk_mul_f32 v[62:63], v[70:71], v[62:63]
	v_pk_mul_f32 v[60:61], v[60:61], v[168:169]
	v_pk_mul_f32 v[62:63], v[62:63], v[142:143]
	ds_write_b128 v66, v[56:59] offset:8256
	ds_write_b128 v66, v[60:63] offset:24640
	v_add3_u32 v67, v166, v67, v164
	v_lshl_add_u64 v[56:57], s[2:3], 0, v[64:65]
	s_mov_b64 s[2:3], s[48:49]
	s_waitcnt vmcnt(0) lgkmcnt(0)
	v_add_f32_e32 v52, v52, v240
	v_lshl_add_u64 v[60:61], s[2:3], 0, v[64:65]
	s_mov_b64 s[2:3], s[74:75]
	s_add_u32 s2, s2, s30
	s_addc_u32 s3, s3, 0
	v_lshl_add_u64 v[68:69], s[2:3], 0, v[144:145]
	v_add_co_u32_e64 v68, s[8:9], s37, v68
	v_mul_f32_e32 v52, 0xbfb8aa3b, v52
	s_nop 0
	v_addc_co_u32_e64 v69, s[8:9], 0, v69, s[8:9]
	v_exp_f32_e32 v52, v52
	v_add_f32_e32 v54, v54, v242
	v_mul_f32_e32 v54, 0xbfb8aa3b, v54
	v_exp_f32_e32 v54, v54
	v_add_f32_e32 v52, 1.0, v52
	v_rcp_f32_e32 v52, v52
	ds_read_b64 v[72:73], v67
	v_add_f32_e32 v54, 1.0, v54
	v_rcp_f32_e32 v54, v54
	s_mov_b64 s[2:3], s[44:45]
	s_waitcnt lgkmcnt(0)
	v_lshlrev_b32_e32 v74, 16, v72
	v_and_b32_e32 v75, 0xffff0000, v72
	v_lshlrev_b32_e32 v72, 16, v73
	v_and_b32_e32 v73, 0xffff0000, v73
	v_add_f32_e32 v48, v48, v244
	v_mul_f32_e32 v48, 0xbfb8aa3b, v48
	v_exp_f32_e32 v48, v48
	v_add_f32_e32 v50, v50, v246
	v_mul_f32_e32 v50, 0xbfb8aa3b, v50
	v_exp_f32_e32 v50, v50
	v_add_f32_e32 v48, 1.0, v48
	v_rcp_f32_e32 v56, v48
	v_add_f32_e32 v48, v53, v241
	v_mul_f32_e32 v48, 0xbfb8aa3b, v48
	v_exp_f32_e32 v48, v48
	v_add_f32_e32 v50, 1.0, v50
	v_rcp_f32_e32 v58, v50
	v_add_f32_e32 v50, v55, v243
	v_add_f32_e32 v48, 1.0, v48
	v_rcp_f32_e32 v53, v48
	v_add_f32_e32 v48, v49, v245
	v_mul_f32_e32 v48, 0xbfb8aa3b, v48
	v_exp_f32_e32 v48, v48
	v_mul_f32_e32 v50, 0xbfb8aa3b, v50
	v_exp_f32_e32 v50, v50
	v_add_f32_e32 v48, 1.0, v48
	v_rcp_f32_e32 v57, v48
	v_pk_mul_f32 v[48:49], v[52:53], s[38:39] op_sel_hi:[1,0]
	v_add_f32_e32 v50, 1.0, v50
	v_pk_mul_f32 v[52:53], v[248:249], v[48:49]
	v_rcp_f32_e32 v55, v50
	v_pk_add_f32 v[60:61], v[52:53], v[52:53]
	v_mul_f32_e32 v48, 0x3fb8aa3b, v52
	v_fmamk_f32 v49, v60, 0x3ab60b61, v195
	v_exp_f32_e32 v48, v48
	v_fmaak_f32 v49, v60, v49, 0x3d2aaaab
	v_fmaak_f32 v49, v60, v49, 0x3e2aaaab
	v_fma_f32 v49, v60, v49, 0.5
	v_fma_f32 v49, v60, v49, 1.0
	v_add_f32_e32 v50, v51, v247
	v_mul_f32_e64 v49, v49, -v60
	v_fma_f32 v52, -v48, v48, 1.0
	v_cmp_lt_f32_e64 s[12:13], s84, v60
	v_mul_f32_e32 v50, 0xbfb8aa3b, v50
	v_exp_f32_e32 v50, v50
	v_cndmask_b32_e64 v49, v52, v49, s[12:13]
	v_sqrt_f32_e32 v52, v49
	v_mul_f32_e32 v49, 0x3fb8aa3b, v53
	v_fmamk_f32 v53, v61, 0x3ab60b61, v195
	v_exp_f32_e32 v49, v49
	v_fmaak_f32 v53, v61, v53, 0x3d2aaaab
	v_fmaak_f32 v53, v61, v53, 0x3e2aaaab
	v_fma_f32 v53, v61, v53, 0.5
	v_add_f32_e32 v50, 1.0, v50
	v_fma_f32 v53, v61, v53, 1.0
	v_rcp_f32_e32 v59, v50
	v_pk_mul_f32 v[50:51], v[54:55], s[38:39] op_sel_hi:[1,0]
	v_cmp_lt_f32_e64 s[8:9], s84, v61
	v_mul_f32_e64 v53, v53, -v61
	v_fma_f32 v60, -v49, v49, 1.0
	v_pk_mul_f32 v[54:55], v[250:251], v[50:51]
	v_cndmask_b32_e64 v53, v60, v53, s[8:9]
	v_pk_add_f32 v[60:61], v[54:55], v[54:55]
	v_mul_f32_e32 v50, 0x3fb8aa3b, v54
	v_fmamk_f32 v51, v60, 0x3ab60b61, v195
	v_exp_f32_e32 v50, v50
	v_fmaak_f32 v51, v60, v51, 0x3d2aaaab
	v_fmaak_f32 v51, v60, v51, 0x3e2aaaab
	v_fma_f32 v51, v60, v51, 0.5
	v_fma_f32 v51, v60, v51, 1.0
	v_mul_f32_e64 v51, v51, -v60
	v_fma_f32 v54, -v50, v50, 1.0
	v_cmp_lt_f32_e64 s[12:13], s84, v60
	v_cmp_lt_f32_e64 s[8:9], s84, v61
	v_sqrt_f32_e32 v53, v53
	v_cndmask_b32_e64 v51, v54, v51, s[12:13]
	v_sqrt_f32_e32 v54, v51
	v_mul_f32_e32 v51, 0x3fb8aa3b, v55
	v_fmamk_f32 v55, v61, 0x3ab60b61, v195
	v_exp_f32_e32 v51, v51
	v_fmaak_f32 v55, v61, v55, 0x3d2aaaab
	v_fmaak_f32 v55, v61, v55, 0x3e2aaaab
	v_fma_f32 v55, v61, v55, 0.5
	v_fma_f32 v55, v61, v55, 1.0
	v_mul_f32_e64 v55, v55, -v61
	v_fma_f32 v60, -v51, v51, 1.0
	v_cndmask_b32_e64 v55, v60, v55, s[8:9]
	v_sqrt_f32_e32 v55, v55
	v_pk_mul_f32 v[52:53], v[56:57], v[52:53]
	v_bitop3_b32 v60, v165, v163, 6 bitop3:0x36
	v_pk_mul_f32 v[52:53], v[52:53], v[74:75]
	v_pk_mul_f32 v[54:55], v[58:59], v[54:55]
	v_lshlrev_b32_e32 v60, 4, v60
	v_pk_mul_f32 v[54:55], v[54:55], v[72:73]
	ds_write_b128 v66, v[48:51] offset:8320
	ds_write_b128 v66, v[52:55] offset:24704
	v_add3_u32 v60, v166, v60, v164
	v_lshl_add_u64 v[48:49], s[2:3], 0, v[64:65]
	s_mov_b64 s[2:3], s[48:49]
	s_waitcnt vmcnt(0) lgkmcnt(0)
	v_add_f32_e32 v12, v12, v178
	v_lshl_add_u64 v[52:53], s[2:3], 0, v[64:65]
	s_mov_b64 s[2:3], s[74:75]
	s_add_u32 s2, s2, s30
	s_addc_u32 s3, s3, 0
	v_lshl_add_u64 v[56:57], s[2:3], 0, v[144:145]
	v_add_co_u32_e64 v56, s[8:9], s37, v56
	v_mul_f32_e32 v12, 0xbfb8aa3b, v12
	s_nop 0
	v_addc_co_u32_e64 v57, s[8:9], 0, v57, s[8:9]
	flat_load_dwordx4 v[56:59], v[56:57] offset:192
	v_exp_f32_e32 v12, v12
	v_add_f32_e32 v14, v14, v180
	v_mul_f32_e32 v14, 0xbfb8aa3b, v14
	v_exp_f32_e32 v14, v14
	v_add_f32_e32 v12, 1.0, v12
	v_rcp_f32_e32 v12, v12
	ds_read_b64 v[60:61], v60
	v_add_f32_e32 v14, 1.0, v14
	v_rcp_f32_e32 v14, v14
	s_waitcnt lgkmcnt(0)
	v_lshlrev_b32_e32 v62, 16, v60
	v_and_b32_e32 v63, 0xffff0000, v60
	v_lshlrev_b32_e32 v60, 16, v61
	v_and_b32_e32 v61, 0xffff0000, v61
	s_waitcnt vmcnt(0)
	v_add_f32_e32 v8, v8, v182
	v_mul_f32_e32 v8, 0xbfb8aa3b, v8
	v_exp_f32_e32 v8, v8
	v_add_f32_e32 v10, v10, v184
	v_mul_f32_e32 v10, 0xbfb8aa3b, v10
	v_exp_f32_e32 v10, v10
	v_add_f32_e32 v8, 1.0, v8
	v_rcp_f32_e32 v48, v8
	v_add_f32_e32 v8, v13, v179
	v_mul_f32_e32 v8, 0xbfb8aa3b, v8
	v_exp_f32_e32 v8, v8
	v_add_f32_e32 v10, 1.0, v10
	v_rcp_f32_e32 v50, v10
	v_add_f32_e32 v10, v15, v181
	v_add_f32_e32 v8, 1.0, v8
	v_rcp_f32_e32 v13, v8
	v_add_f32_e32 v8, v9, v183
	v_mul_f32_e32 v8, 0xbfb8aa3b, v8
	v_exp_f32_e32 v8, v8
	v_mul_f32_e32 v10, 0xbfb8aa3b, v10
	v_exp_f32_e32 v10, v10
	v_add_f32_e32 v8, 1.0, v8
	v_rcp_f32_e32 v49, v8
	v_pk_mul_f32 v[8:9], v[12:13], s[38:39] op_sel_hi:[1,0]
	v_add_f32_e32 v10, 1.0, v10
	v_pk_mul_f32 v[12:13], v[56:57], v[8:9]
	v_rcp_f32_e32 v15, v10
	v_pk_add_f32 v[52:53], v[12:13], v[12:13]
	v_mul_f32_e32 v8, 0x3fb8aa3b, v12
	v_fmamk_f32 v9, v52, 0x3ab60b61, v195
	v_exp_f32_e32 v8, v8
	v_fmaak_f32 v9, v52, v9, 0x3d2aaaab
	v_fmaak_f32 v9, v52, v9, 0x3e2aaaab
	v_fma_f32 v9, v52, v9, 0.5
	v_fma_f32 v9, v52, v9, 1.0
	v_add_f32_e32 v10, v11, v185
	v_mul_f32_e64 v9, v9, -v52
	v_fma_f32 v12, -v8, v8, 1.0
	v_cmp_lt_f32_e64 s[12:13], s84, v52
	v_mul_f32_e32 v10, 0xbfb8aa3b, v10
	v_exp_f32_e32 v10, v10
	v_cndmask_b32_e64 v9, v12, v9, s[12:13]
	v_sqrt_f32_e32 v12, v9
	v_mul_f32_e32 v9, 0x3fb8aa3b, v13
	v_fmamk_f32 v13, v53, 0x3ab60b61, v195
	v_exp_f32_e32 v9, v9
	v_fmaak_f32 v13, v53, v13, 0x3d2aaaab
	v_fmaak_f32 v13, v53, v13, 0x3e2aaaab
	v_fma_f32 v13, v53, v13, 0.5
	v_add_f32_e32 v10, 1.0, v10
	v_fma_f32 v13, v53, v13, 1.0
	v_rcp_f32_e32 v51, v10
	v_pk_mul_f32 v[10:11], v[14:15], s[38:39] op_sel_hi:[1,0]
	v_cmp_lt_f32_e64 s[8:9], s84, v53
	v_mul_f32_e64 v13, v13, -v53
	v_fma_f32 v52, -v9, v9, 1.0
	v_pk_mul_f32 v[14:15], v[58:59], v[10:11]
	v_cndmask_b32_e64 v13, v52, v13, s[8:9]
	v_pk_add_f32 v[52:53], v[14:15], v[14:15]
	v_mul_f32_e32 v10, 0x3fb8aa3b, v14
	v_fmamk_f32 v11, v52, 0x3ab60b61, v195
	v_exp_f32_e32 v10, v10
	v_fmaak_f32 v11, v52, v11, 0x3d2aaaab
	v_fmaak_f32 v11, v52, v11, 0x3e2aaaab
	v_fma_f32 v11, v52, v11, 0.5
	v_fma_f32 v11, v52, v11, 1.0
	v_mul_f32_e64 v11, v11, -v52
	v_fma_f32 v14, -v10, v10, 1.0
	v_cmp_lt_f32_e64 s[12:13], s84, v52
	v_cmp_lt_f32_e64 s[8:9], s84, v53
	v_sqrt_f32_e32 v13, v13
	v_cndmask_b32_e64 v11, v14, v11, s[12:13]
	v_sqrt_f32_e32 v14, v11
	v_mul_f32_e32 v11, 0x3fb8aa3b, v15
	v_fmamk_f32 v15, v53, 0x3ab60b61, v195
	v_exp_f32_e32 v11, v11
	v_fmaak_f32 v15, v53, v15, 0x3d2aaaab
	v_fmaak_f32 v15, v53, v15, 0x3e2aaaab
	v_fma_f32 v15, v53, v15, 0.5
	v_fma_f32 v15, v53, v15, 1.0
	v_mul_f32_e64 v15, v15, -v53
	v_fma_f32 v52, -v11, v11, 1.0
	v_cndmask_b32_e64 v15, v52, v15, s[8:9]
	v_sqrt_f32_e32 v15, v15
	v_pk_mul_f32 v[12:13], v[48:49], v[12:13]
	v_cmp_lt_i32_e64 s[8:9], 0, v141
	v_pk_mul_f32 v[12:13], v[12:13], v[62:63]
	v_pk_mul_f32 v[14:15], v[50:51], v[14:15]
	s_nop 0
	v_pk_mul_f32 v[14:15], v[14:15], v[60:61]
	ds_write_b128 v66, v[8:11] offset:8384
	ds_write_b128 v66, v[12:15] offset:24768
	v_and_b32_e32 v9, 63, v162
	v_lshlrev_b32_e32 v64, 2, v9
	v_lshl_or_b32 v8, v141, 12, v64
	v_add_u32_e32 v8, s60, v8
	s_waitcnt lgkmcnt(0)
	s_barrier
	ds_read2st64_b32 v[10:11], v8 offset0:32 offset1:33
	ds_read2st64_b32 v[12:13], v8 offset0:96 offset1:97
	ds_read2st64_b32 v[14:15], v8 offset0:34 offset1:35
	ds_read2st64_b32 v[48:49], v8 offset0:98 offset1:99
	v_lshl_add_u32 v9, v9, 3, s60
	s_waitcnt lgkmcnt(2)
	v_fma_f32 v12, 0, v10, v12
	v_fmac_f32_e32 v13, v12, v11
	v_mul_f32_e32 v10, v10, v11
	s_waitcnt lgkmcnt(0)
	v_fma_f32 v11, v13, v14, v48
	ds_read2st64_b32 v[12:13], v8 offset0:36 offset1:37
	ds_read2st64_b32 v[50:51], v8 offset0:100 offset1:101
	v_fmac_f32_e32 v49, v11, v15
	v_mov_b32_e32 v58, v14
	v_mul_f32_e32 v14, v10, v14
	v_mul_f32_e32 v14, v14, v15
	s_waitcnt lgkmcnt(0)
	v_fma_f32 v11, v49, v12, v50
	ds_read2st64_b32 v[48:49], v8 offset0:38 offset1:39
	ds_read2st64_b32 v[52:53], v8 offset0:102 offset1:103
	v_fmac_f32_e32 v51, v11, v13
	s_waitcnt lgkmcnt(1)
	v_mov_b32_e32 v62, v48
	s_waitcnt lgkmcnt(0)
	v_fma_f32 v11, v51, v48, v52
	ds_read2st64_b32 v[50:51], v8 offset0:40 offset1:41
	ds_read2st64_b32 v[54:55], v8 offset0:104 offset1:105
	v_fmac_f32_e32 v53, v11, v49
	s_waitcnt lgkmcnt(1)
	v_mov_b32_e32 v59, v51
	s_waitcnt lgkmcnt(0)
	v_fmac_f32_e32 v54, v53, v50
	ds_read2st64_b32 v[52:53], v8 offset0:42 offset1:43
	ds_read2st64_b32 v[56:57], v8 offset0:106 offset1:107
	v_mov_b32_e32 v11, v54
	v_mov_b32_e32 v54, v15
	v_pk_fma_f32 v[10:11], v[10:11], v[58:59], v[54:55]
	v_mov_b32_e32 v58, v13
	v_mov_b32_e32 v15, v11
	v_mov_b32_e32 v10, v12
	s_waitcnt lgkmcnt(1)
	v_mov_b32_e32 v11, v52
	v_pk_mul_f32 v[54:55], v[14:15], v[10:11]
	v_mov_b32_e32 v12, v13
	s_waitcnt lgkmcnt(0)
	v_mov_b32_e32 v59, v56
	v_pk_mul_f32 v[12:13], v[54:55], v[12:13]
	v_pk_fma_f32 v[10:11], v[14:15], v[10:11], v[58:59]
	v_and_b32_e32 v56, 0x1fffffc0, v161
	v_mov_b32_e32 v10, v12
	ds_read2st64_b32 v[14:15], v8 offset0:44 offset1:45
	ds_read2st64_b32 v[54:55], v8 offset0:108 offset1:109
	ds_read2st64_b32 v[58:59], v8 offset0:46 offset1:47
	ds_read2st64_b32 v[60:61], v8 offset0:110 offset1:111
	v_lshl_add_u32 v65, v56, 3, v9
	v_mov_b32_e32 v63, v53
	v_pk_mul_f32 v[12:13], v[12:13], v[48:49]
	v_mov_b32_e32 v48, v49
	v_mov_b32_e32 v56, v49
	v_pk_mul_f32 v[12:13], v[12:13], v[48:49]
	v_pk_fma_f32 v[10:11], v[10:11], v[62:63], v[56:57]
	v_mov_b32_e32 v56, v51
	v_mov_b32_e32 v13, v11
	v_mov_b32_e32 v10, v50
	s_waitcnt lgkmcnt(3)
	v_mov_b32_e32 v11, v14
	v_pk_mul_f32 v[48:49], v[12:13], v[10:11]
	v_mov_b32_e32 v50, v51
	s_waitcnt lgkmcnt(2)
	v_mov_b32_e32 v57, v54
	v_pk_mul_f32 v[48:49], v[48:49], v[50:51]
	v_pk_fma_f32 v[10:11], v[12:13], v[10:11], v[56:57]
	v_mov_b32_e32 v12, v52
	v_mov_b32_e32 v10, v48
	v_mov_b32_e32 v13, v15
	v_pk_mul_f32 v[48:49], v[48:49], v[52:53]
	v_mov_b32_e32 v50, v53
	v_mov_b32_e32 v54, v53
	v_pk_mul_f32 v[48:49], v[48:49], v[50:51]
	v_pk_fma_f32 v[10:11], v[10:11], v[12:13], v[54:55]
	v_mov_b32_e32 v50, v15
	v_mov_b32_e32 v49, v11
	v_mov_b32_e32 v10, v14
	s_waitcnt lgkmcnt(1)
	v_mov_b32_e32 v11, v58
	v_pk_mul_f32 v[12:13], v[48:49], v[10:11]
	v_mov_b32_e32 v14, v15
	s_waitcnt lgkmcnt(0)
	v_mov_b32_e32 v51, v60
	v_pk_mul_f32 v[12:13], v[12:13], v[14:15]
	v_pk_fma_f32 v[10:11], v[48:49], v[10:11], v[50:51]
	v_mov_b32_e32 v14, v59
	v_mov_b32_e32 v10, v12
	v_pk_mul_f32 v[12:13], v[12:13], v[58:59]
	v_mov_b32_e32 v60, v59
	v_pk_mul_f32 v[12:13], v[12:13], v[14:15]
	v_pk_fma_f32 v[10:11], v[10:11], v[58:59], v[60:61]
	s_nop 0
	v_mov_b32_e32 v13, v11
	v_sub_u32_e32 v10, v9, v64
	ds_write_b64 v65, v[12:13] offset:40960
	s_waitcnt lgkmcnt(0)
	s_barrier
	ds_read_b32 v10, v10 offset:43008
	s_and_saveexec_b64 s[2:3], s[8:9]
	s_cbranch_execz .LBB0_359
	ds_read_b64 v[12:13], v9 offset:40960
	s_waitcnt lgkmcnt(0)
	v_fmac_f32_e32 v13, v10, v12
	v_mov_b32_e32 v10, v13
	s_or_b64 exec, exec, s[2:3]
	v_cmp_lt_i32_e64 s[8:9], 1, v141
	s_and_saveexec_b64 s[2:3], s[8:9]
	s_cbranch_execnz .LBB0_360

.LBB0_363:
	s_or_b64 exec, exec, s[2:3]
	s_mov_b64 s[2:3], s[74:75]
	ds_read2st64_b32 v[12:13], v8 offset0:32 offset1:33
	ds_read2st64_b32 v[14:15], v8 offset0:96 offset1:97
	v_mov_b32_e32 v162, v191
	v_mov_b32_e32 v163, v191
	s_mov_b64 s[2:3], s[74:75]
	v_mov_b32_e32 v143, v145
	s_waitcnt lgkmcnt(0)
	v_fma_f32 v9, v10, v12, v14
	v_fmac_f32_e32 v15, v9, v13
	ds_write2st64_b32 v8, v9, v15 offset0:176 offset1:177
	ds_read2st64_b32 v[10:11], v8 offset0:34 offset1:35
	ds_read2st64_b32 v[12:13], v8 offset0:98 offset1:99
	v_readlane_b32 s40, v254, 22
	v_readlane_b32 s44, v254, 26
	v_readlane_b32 s45, v254, 27
	v_readlane_b32 s48, v254, 30
	s_waitcnt lgkmcnt(0)
	v_fma_f32 v9, v15, v10, v12
	v_fmac_f32_e32 v13, v9, v11
	ds_write2st64_b32 v8, v9, v13 offset0:178 offset1:179
	ds_read2st64_b32 v[10:11], v8 offset0:36 offset1:37
	ds_read2st64_b32 v[14:15], v8 offset0:100 offset1:101
	v_readlane_b32 s49, v254, 31
	s_mov_b64 s[8:9], s[48:49]
	v_readlane_b32 s41, v254, 23
	v_readlane_b32 s42, v254, 24
	s_waitcnt lgkmcnt(0)
	v_fma_f32 v9, v13, v10, v14
	v_fmac_f32_e32 v15, v9, v11
	ds_write2st64_b32 v8, v9, v15 offset0:180 offset1:181
	ds_read2st64_b32 v[10:11], v8 offset0:38 offset1:39
	ds_read2st64_b32 v[12:13], v8 offset0:102 offset1:103
	v_readlane_b32 s43, v254, 25
	v_readlane_b32 s46, v254, 28
	v_readlane_b32 s47, v254, 29
	v_readlane_b32 s50, v254, 32
	s_waitcnt lgkmcnt(0)
	v_fma_f32 v9, v15, v10, v12
	v_fmac_f32_e32 v13, v9, v11
	ds_write2st64_b32 v8, v9, v13 offset0:182 offset1:183
	ds_read2st64_b32 v[10:11], v8 offset0:40 offset1:41
	ds_read2st64_b32 v[14:15], v8 offset0:104 offset1:105
	v_readlane_b32 s51, v254, 33
	v_readlane_b32 s52, v254, 34
	v_readlane_b32 s53, v254, 35
	v_readlane_b32 s54, v254, 36
	s_waitcnt lgkmcnt(0)
	v_fma_f32 v9, v13, v10, v14
	v_fmac_f32_e32 v15, v9, v11
	ds_write2st64_b32 v8, v9, v15 offset0:184 offset1:185
	ds_read2st64_b32 v[10:11], v8 offset0:42 offset1:43
	ds_read2st64_b32 v[12:13], v8 offset0:106 offset1:107
	v_readlane_b32 s55, v254, 37
	s_waitcnt lgkmcnt(0)
	v_fma_f32 v9, v15, v10, v12
	v_fmac_f32_e32 v13, v9, v11
	ds_write2st64_b32 v8, v9, v13 offset0:186 offset1:187
	ds_read2st64_b32 v[10:11], v8 offset0:44 offset1:45
	ds_read2st64_b32 v[14:15], v8 offset0:108 offset1:109
	s_waitcnt lgkmcnt(0)
	v_fma_f32 v9, v13, v10, v14
	v_fmac_f32_e32 v15, v9, v11
	ds_write2st64_b32 v8, v9, v15 offset0:188 offset1:189
	ds_read2st64_b32 v[10:11], v8 offset0:46 offset1:47
	ds_read2st64_b32 v[12:13], v8 offset0:110 offset1:111
	s_waitcnt lgkmcnt(0)
	v_fma_f32 v9, v15, v10, v12
	v_fmac_f32_e32 v13, v9, v11
	ds_write2st64_b32 v8, v9, v13 offset0:190 offset1:191
	s_waitcnt lgkmcnt(0)
	s_barrier
	s_add_u32 s2, s2, s31
	v_and_b32_e32 v165, 15, v162
	v_lshrrev_b32_e32 v170, 4, v162
	v_bfe_u32 v171, v162, 4, 2
	v_bfe_u32 v164, v162, 1, 3
	v_ashrrev_i32_e32 v161, 6, v162
	v_lshlrev_b32_e32 v142, 7, v165
	v_bitop3_b32 v8, v170, v164, 3 bitop3:0x6c
	v_bitop3_b32 v13, v171, v164, 4 bitop3:0x36
	v_lshl_or_b32 v12, v161, 11, v142
	v_lshlrev_b32_e32 v8, 4, v8
	v_lshlrev_b32_e32 v13, 4, v13
	v_add3_u32 v8, s60, v8, v12
	v_add3_u32 v12, s60, v13, v12
	s_addc_u32 s3, s3, 0
	v_lshlrev_b32_e32 v144, 4, v171
	ds_read_b128 v[8:11], v8
	ds_read_b128 v[72:75], v12
	v_lshl_add_u64 v[12:13], s[2:3], 0, v[144:145]
	s_mov_b64 s[2:3], 0x3980000
	v_lshl_add_u64 v[166:167], v[12:13], 0, s[2:3]
	s_mov_b64 s[2:3], 0x39a0000
	v_lshl_add_u64 v[168:169], v[12:13], 0, s[2:3]
	v_mul_u32_u24_e32 v184, 0xf0, v171
	v_lshl_add_u32 v184, v165, 4, v184
	v_mov_b32_e32 v185, v145
	v_lshl_add_u64 v[60:61], v[166:167], 0, v[184:185]
	v_lshl_add_u64 v[62:63], v[168:169], 0, v[184:185]
	flat_load_dwordx4 v[12:15], v[60:61]
	flat_load_dwordx4 v[48:51], v[62:63]
	flat_load_dwordx4 v[52:55], v[60:61] offset:1024
	flat_load_dwordx4 v[56:59], v[62:63] offset:1024
	v_lshrrev_b32_e32 v172, 1, v162
	v_lshlrev_b32_e32 v141, 4, v161
	s_mov_b64 s[2:3], s[44:45]
	s_waitcnt vmcnt(0) lgkmcnt(0)
	v_mfma_f32_16x16x32_bf16 v[12:15], v[12:15], v[8:11], 0
	v_mfma_f32_16x16x32_bf16 v[48:51], v[48:51], v[8:11], 0
	v_mfma_f32_16x16x32_bf16 v[68:71], v[52:55], v[72:75], v[12:15]
	v_mfma_f32_16x16x32_bf16 v[64:67], v[56:59], v[72:75], v[48:51]
	s_nop 4
	flat_load_dwordx4 v[12:15], v[60:61] offset:2048
	flat_load_dwordx4 v[48:51], v[62:63] offset:2048
	flat_load_dwordx4 v[52:55], v[60:61] offset:3072
	flat_load_dwordx4 v[56:59], v[62:63] offset:3072
	s_waitcnt vmcnt(0) lgkmcnt(0)
	v_mfma_f32_16x16x32_bf16 v[12:15], v[12:15], v[8:11], 0
	v_mfma_f32_16x16x32_bf16 v[48:51], v[48:51], v[8:11], 0
	v_mfma_f32_16x16x32_bf16 v[60:63], v[52:55], v[72:75], v[12:15]
	s_nop 5
	v_or_b32_e32 v12, 0x1000, v184
	v_mov_b32_e32 v13, v145
	v_lshl_add_u64 v[52:53], v[166:167], 0, v[12:13]
	v_mfma_f32_16x16x32_bf16 v[56:59], v[56:59], v[72:75], v[48:51]
	v_lshl_add_u64 v[146:147], v[168:169], 0, v[12:13]
	flat_load_dwordx4 v[12:15], v[52:53]
	s_nop 0
	flat_load_dwordx4 v[48:51], v[146:147]
	s_nop 0
	flat_load_dwordx4 v[52:55], v[52:53] offset:1024
	s_nop 0
	flat_load_dwordx4 v[146:149], v[146:147] offset:1024
	s_waitcnt vmcnt(0) lgkmcnt(0)
	v_mfma_f32_16x16x32_bf16 v[12:15], v[12:15], v[8:11], 0
	v_mfma_f32_16x16x32_bf16 v[48:51], v[48:51], v[8:11], 0
	v_mfma_f32_16x16x32_bf16 v[52:55], v[52:55], v[72:75], v[12:15]
	s_nop 5
	v_or_b32_e32 v12, 0x1800, v184
	v_mov_b32_e32 v13, v145
	v_lshl_add_u64 v[142:143], v[166:167], 0, v[12:13]
	v_mfma_f32_16x16x32_bf16 v[48:51], v[146:149], v[72:75], v[48:51]
	v_lshl_add_u64 v[166:167], v[168:169], 0, v[12:13]
	flat_load_dwordx4 v[12:15], v[142:143]
	flat_load_dwordx4 v[146:149], v[166:167]
	s_waitcnt vmcnt(0) lgkmcnt(0)
	v_mfma_f32_16x16x32_bf16 v[12:15], v[12:15], v[8:11], 0
	v_mfma_f32_16x16x32_bf16 v[8:11], v[146:149], v[8:11], 0
	flat_load_dwordx4 v[146:149], v[142:143] offset:1024
	s_nop 0
	flat_load_dwordx4 v[166:169], v[166:167] offset:1024
	v_lshlrev_b32_e32 v142, 2, v171
	v_mov_b32_e32 v143, v145
	v_or_b32_e32 v180, s22, v142
	v_ashrrev_i32_e32 v181, 31, v180
	v_lshlrev_b64 v[180:181], 2, v[180:181]
	s_add_u32 s98, s74, s30
	s_addc_u32 s99, s75, 0
	s_add_u32 s98, s98, 0x122e6000
	s_addc_u32 s99, s99, 0
	v_lshl_add_u64 v[184:185], s[98:99], 0, v[144:145]
	v_lshl_add_u64 v[178:179], s[44:45], 0, v[180:181]
	v_lshl_add_u64 v[182:183], s[48:49], 0, v[180:181]
	global_load_dwordx4 v[216:219], v[178:179], off offset:2048
	global_load_dwordx4 v[220:223], v[182:183], off offset:2048
	global_load_dwordx4 v[224:227], v[184:185], off offset:2048
	global_load_dwordx4 v[228:231], v[178:179], off offset:2112
	global_load_dwordx4 v[232:235], v[182:183], off offset:2112
	global_load_dwordx4 v[236:239], v[184:185], off offset:2112
	global_load_dwordx4 v[240:243], v[178:179], off offset:2176
	global_load_dwordx4 v[244:247], v[182:183], off offset:2176
	global_load_dwordx4 v[248:251], v[184:185], off offset:2176
	global_load_dwordx4 v[178:181], v[178:179], off offset:2240
	global_load_dwordx4 v[182:185], v[182:183], off offset:2240
	s_waitcnt vmcnt(0) lgkmcnt(0)
	v_mfma_f32_16x16x32_bf16 v[12:15], v[146:149], v[72:75], v[12:15]
	v_mfma_f32_16x16x32_bf16 v[8:11], v[166:169], v[72:75], v[8:11]
	v_or_b32_e32 v72, v141, v165
	v_and_b32_e32 v73, 8, v172
	v_lshlrev_b32_e32 v165, 7, v72
	v_add_u32_e32 v167, s60, v73
	v_lshlrev_b32_e32 v176, 8, v72
	v_lshl_add_u64 v[72:73], v[142:143], 0, s[22:23]
	v_lshlrev_b64 v[146:147], 2, v[72:73]
	v_lshl_add_u64 v[72:73], s[2:3], 0, v[146:147]
	s_mov_b64 s[2:3], s[74:75]
	v_lshl_add_u64 v[146:147], s[8:9], 0, v[146:147]
	s_add_u32 s2, s2, s30
	s_addc_u32 s3, s3, 0
	v_lshl_add_u64 v[168:169], s[2:3], 0, v[144:145]
	v_add_co_u32_e64 v168, s[8:9], s37, v168
	v_bfe_u32 v166, v170, 1, 1
	s_nop 0
	v_addc_co_u32_e64 v169, s[8:9], 0, v169, s[8:9]
	v_bitop3_b32 v172, v166, v172, 7 bitop3:0x78
	v_lshlrev_b32_e32 v172, 4, v172
	v_add3_u32 v172, v167, v172, v165
	ds_read_b64 v[172:173], v172
	s_mov_b64 s[2:3], s[44:45]
	s_waitcnt lgkmcnt(0)
	v_lshlrev_b32_e32 v174, 16, v172
	v_and_b32_e32 v175, 0xffff0000, v172
	v_lshlrev_b32_e32 v172, 16, v173
	v_and_b32_e32 v173, 0xffff0000, v173
	v_add_f32_e32 v68, v68, v216
	v_add_f32_e32 v69, v69, v217
	v_mul_f32_e32 v68, 0xbfb8aa3b, v68
	v_mul_f32_e32 v69, 0xbfb8aa3b, v69
	v_exp_f32_e32 v68, v68
	v_exp_f32_e32 v69, v69
	v_add_f32_e32 v64, v64, v220
	v_add_f32_e32 v65, v65, v221
	v_add_f32_e32 v68, 1.0, v68
	v_add_f32_e32 v69, 1.0, v69
	v_rcp_f32_e32 v68, v68
	v_rcp_f32_e32 v69, v69
	v_add_f32_e32 v70, v70, v218
	v_add_f32_e32 v71, v71, v219
	v_mul_f32_e32 v70, 0xbfb8aa3b, v70
	v_pk_mul_f32 v[68:69], v[68:69], s[38:39] op_sel_hi:[1,0]
	v_mul_f32_e32 v71, 0xbfb8aa3b, v71
	v_pk_mul_f32 v[72:73], v[224:225], v[68:69]
	v_exp_f32_e32 v70, v70
	v_pk_add_f32 v[146:147], v[72:73], v[72:73]
	v_mul_f32_e32 v68, 0x3fb8aa3b, v72
	v_fmamk_f32 v69, v146, 0x3ab60b61, v195
	v_exp_f32_e32 v68, v68
	v_fmaak_f32 v69, v146, v69, 0x3d2aaaab
	v_fmaak_f32 v69, v146, v69, 0x3e2aaaab
	v_exp_f32_e32 v71, v71
	v_fma_f32 v69, v146, v69, 0.5
	v_fma_f32 v69, v146, v69, 1.0
	v_mul_f32_e64 v69, v69, -v146
	v_fma_f32 v72, -v68, v68, 1.0
	v_cmp_lt_f32_e64 s[12:13], s84, v146
	v_add_f32_e32 v70, 1.0, v70
	v_add_f32_e32 v71, 1.0, v71
	v_cndmask_b32_e64 v69, v72, v69, s[12:13]
	v_sqrt_f32_e32 v72, v69
	v_mul_f32_e32 v69, 0x3fb8aa3b, v73
	v_fmamk_f32 v73, v147, 0x3ab60b61, v195
	v_rcp_f32_e32 v70, v70
	v_rcp_f32_e32 v71, v71
	v_exp_f32_e32 v69, v69
	v_fmaak_f32 v73, v147, v73, 0x3d2aaaab
	v_fmaak_f32 v73, v147, v73, 0x3e2aaaab
	v_fma_f32 v73, v147, v73, 0.5
	v_fma_f32 v73, v147, v73, 1.0
	v_pk_mul_f32 v[70:71], v[70:71], s[38:39] op_sel_hi:[1,0]
	v_cmp_lt_f32_e64 s[8:9], s84, v147
	v_mul_f32_e64 v73, v73, -v147
	v_fma_f32 v146, -v69, v69, 1.0
	v_pk_mul_f32 v[74:75], v[226:227], v[70:71]
	v_cndmask_b32_e64 v73, v146, v73, s[8:9]
	v_pk_add_f32 v[146:147], v[74:75], v[74:75]
	v_mul_f32_e32 v70, 0x3fb8aa3b, v74
	v_fmamk_f32 v71, v146, 0x3ab60b61, v195
	v_exp_f32_e32 v70, v70
	v_fmaak_f32 v71, v146, v71, 0x3d2aaaab
	v_fmaak_f32 v71, v146, v71, 0x3e2aaaab
	v_fma_f32 v71, v146, v71, 0.5
	v_fma_f32 v71, v146, v71, 1.0
	v_mul_f32_e64 v71, v71, -v146
	v_fma_f32 v74, -v70, v70, 1.0
	v_cmp_lt_f32_e64 s[12:13], s84, v146
	v_add_f32_e32 v66, v66, v222
	v_add_f32_e32 v67, v67, v223
	v_cndmask_b32_e64 v71, v74, v71, s[12:13]
	v_sqrt_f32_e32 v74, v71
	v_mul_f32_e32 v71, 0x3fb8aa3b, v75
	v_fmamk_f32 v75, v147, 0x3ab60b61, v195
	v_mul_f32_e32 v64, 0xbfb8aa3b, v64
	v_mul_f32_e32 v65, 0xbfb8aa3b, v65
	v_mul_f32_e32 v66, 0xbfb8aa3b, v66
	v_mul_f32_e32 v67, 0xbfb8aa3b, v67
	v_exp_f32_e32 v71, v71
	v_fmaak_f32 v75, v147, v75, 0x3d2aaaab
	v_exp_f32_e32 v64, v64
	v_exp_f32_e32 v65, v65
	v_exp_f32_e32 v66, v66
	v_exp_f32_e32 v67, v67
	v_fmaak_f32 v75, v147, v75, 0x3e2aaaab
	v_fma_f32 v75, v147, v75, 0.5
	v_fma_f32 v75, v147, v75, 1.0
	v_cmp_lt_f32_e64 s[8:9], s84, v147
	v_mul_f32_e64 v75, v75, -v147
	v_fma_f32 v146, -v71, v71, 1.0
	v_add_f32_e32 v64, 1.0, v64
	v_add_f32_e32 v65, 1.0, v65
	v_add_f32_e32 v66, 1.0, v66
	v_add_f32_e32 v67, 1.0, v67
	v_cndmask_b32_e64 v75, v146, v75, s[8:9]
	v_rcp_f32_e32 v64, v64
	v_rcp_f32_e32 v65, v65
	v_sqrt_f32_e32 v73, v73
	v_rcp_f32_e32 v66, v66
	v_rcp_f32_e32 v67, v67
	v_sqrt_f32_e32 v75, v75
	v_pk_mul_f32 v[64:65], v[64:65], v[72:73]
	v_pk_mul_f32 v[66:67], v[66:67], v[74:75]
	v_pk_mul_f32 v[72:73], v[64:65], v[174:175]
	v_pk_mul_f32 v[74:75], v[66:67], v[172:173]
	v_add3_u32 v66, s60, v176, v144
	v_lshl_add_u64 v[64:65], v[142:143], 0, s[24:25]
	ds_write_b128 v66, v[68:71] offset:8192
	ds_write_b128 v66, v[72:75] offset:24576
	v_lshlrev_b64 v[64:65], 2, v[64:65]
	v_lshl_add_u64 v[68:69], s[2:3], 0, v[64:65]
	s_mov_b64 s[2:3], s[48:49]
	v_bitop3_b32 v67, v166, v164, 2 bitop3:0x36
	v_lshl_add_u64 v[72:73], s[2:3], 0, v[64:65]
	s_mov_b64 s[2:3], s[74:75]
	s_add_u32 s2, s2, s30
	s_addc_u32 s3, s3, 0
	v_lshl_add_u64 v[142:143], s[2:3], 0, v[144:145]
	v_add_co_u32_e64 v142, s[8:9], s37, v142
	v_lshlrev_b32_e32 v67, 4, v67
	s_nop 0
	v_addc_co_u32_e64 v143, s[8:9], 0, v143, s[8:9]
	v_add3_u32 v67, v167, v67, v165
	ds_read_b64 v[142:143], v67
	s_mov_b64 s[2:3], s[44:45]
	s_waitcnt lgkmcnt(0)
	v_lshlrev_b32_e32 v168, 16, v142
	v_and_b32_e32 v169, 0xffff0000, v142
	v_lshlrev_b32_e32 v142, 16, v143
	v_and_b32_e32 v143, 0xffff0000, v143
	v_add_f32_e32 v60, v60, v228
	v_mul_f32_e32 v60, 0xbfb8aa3b, v60
	v_exp_f32_e32 v60, v60
	v_add_f32_e32 v62, v62, v230
	v_add_f32_e32 v56, v56, v232
	v_mul_f32_e32 v56, 0xbfb8aa3b, v56
	v_exp_f32_e32 v56, v56
	v_add_f32_e32 v58, v58, v234
	v_mul_f32_e32 v58, 0xbfb8aa3b, v58
	v_exp_f32_e32 v58, v58
	v_add_f32_e32 v56, 1.0, v56
	v_rcp_f32_e32 v68, v56
	v_add_f32_e32 v56, v61, v229
	v_mul_f32_e32 v56, 0xbfb8aa3b, v56
	v_exp_f32_e32 v56, v56
	v_add_f32_e32 v60, 1.0, v60
	v_rcp_f32_e32 v60, v60
	v_add_f32_e32 v58, 1.0, v58
	v_add_f32_e32 v56, 1.0, v56
	v_rcp_f32_e32 v61, v56
	v_add_f32_e32 v56, v57, v233
	v_mul_f32_e32 v56, 0xbfb8aa3b, v56
	v_exp_f32_e32 v56, v56
	v_rcp_f32_e32 v70, v58
	v_add_f32_e32 v58, v63, v231
	v_mul_f32_e32 v58, 0xbfb8aa3b, v58
	v_add_f32_e32 v56, 1.0, v56
	v_rcp_f32_e32 v69, v56
	v_pk_mul_f32 v[56:57], v[60:61], s[38:39] op_sel_hi:[1,0]
	v_exp_f32_e32 v58, v58
	v_pk_mul_f32 v[60:61], v[236:237], v[56:57]
	v_mul_f32_e32 v62, 0xbfb8aa3b, v62
	v_pk_add_f32 v[72:73], v[60:61], v[60:61]
	v_mul_f32_e32 v56, 0x3fb8aa3b, v60
	v_fmamk_f32 v57, v72, 0x3ab60b61, v195
	v_exp_f32_e32 v56, v56
	v_fmaak_f32 v57, v72, v57, 0x3d2aaaab
	v_exp_f32_e32 v62, v62
	v_fmaak_f32 v57, v72, v57, 0x3e2aaaab
	v_add_f32_e32 v58, 1.0, v58
	v_fma_f32 v57, v72, v57, 0.5
	v_rcp_f32_e32 v63, v58
	v_add_f32_e32 v58, v59, v235
	v_fma_f32 v57, v72, v57, 1.0
	v_mul_f32_e32 v58, 0xbfb8aa3b, v58
	v_mul_f32_e64 v57, v57, -v72
	v_fma_f32 v60, -v56, v56, 1.0
	v_cmp_lt_f32_e64 s[12:13], s84, v72
	v_add_f32_e32 v62, 1.0, v62
	v_exp_f32_e32 v58, v58
	v_cndmask_b32_e64 v57, v60, v57, s[12:13]
	v_rcp_f32_e32 v62, v62
	v_sqrt_f32_e32 v60, v57
	v_mul_f32_e32 v57, 0x3fb8aa3b, v61
	v_fmamk_f32 v61, v73, 0x3ab60b61, v195
	v_fmaak_f32 v61, v73, v61, 0x3d2aaaab
	v_fmaak_f32 v61, v73, v61, 0x3e2aaaab
	v_add_f32_e32 v58, 1.0, v58
	v_fma_f32 v61, v73, v61, 0.5
	v_rcp_f32_e32 v71, v58
	v_pk_mul_f32 v[58:59], v[62:63], s[38:39] op_sel_hi:[1,0]
	v_fma_f32 v61, v73, v61, 1.0
	v_pk_mul_f32 v[62:63], v[238:239], v[58:59]
	v_cmp_lt_f32_e64 s[8:9], s84, v73
	v_mul_f32_e64 v61, v61, -v73
	v_pk_add_f32 v[72:73], v[62:63], v[62:63]
	v_mul_f32_e32 v58, 0x3fb8aa3b, v62
	v_fmamk_f32 v59, v72, 0x3ab60b61, v195
	v_exp_f32_e32 v58, v58
	v_fmaak_f32 v59, v72, v59, 0x3d2aaaab
	v_fmaak_f32 v59, v72, v59, 0x3e2aaaab
	v_fma_f32 v59, v72, v59, 0.5
	v_fma_f32 v59, v72, v59, 1.0
	v_mul_f32_e64 v59, v59, -v72
	v_fma_f32 v62, -v58, v58, 1.0
	v_cmp_lt_f32_e64 s[12:13], s84, v72
	v_exp_f32_e32 v57, v57
	s_nop 0
	v_cndmask_b32_e64 v59, v62, v59, s[12:13]
	v_sqrt_f32_e32 v62, v59
	v_mul_f32_e32 v59, 0x3fb8aa3b, v63
	v_fmamk_f32 v63, v73, 0x3ab60b61, v195
	v_exp_f32_e32 v59, v59
	v_fmaak_f32 v63, v73, v63, 0x3d2aaaab
	v_fmaak_f32 v63, v73, v63, 0x3e2aaaab
	v_fma_f32 v63, v73, v63, 0.5
	v_fma_f32 v67, -v57, v57, 1.0
	v_fma_f32 v63, v73, v63, 1.0
	v_cndmask_b32_e64 v61, v67, v61, s[8:9]
	v_cmp_lt_f32_e64 s[8:9], s84, v73
	v_mul_f32_e64 v63, v63, -v73
	v_fma_f32 v67, -v59, v59, 1.0
	v_cndmask_b32_e64 v63, v67, v63, s[8:9]
	v_sqrt_f32_e32 v61, v61
	v_sqrt_f32_e32 v63, v63
	v_bitop3_b32 v67, v166, v164, 4 bitop3:0x36
	v_lshlrev_b32_e32 v67, 4, v67
	v_pk_mul_f32 v[60:61], v[68:69], v[60:61]
	v_pk_mul_f32 v[62:63], v[70:71], v[62:63]
	v_pk_mul_f32 v[60:61], v[60:61], v[168:169]
	v_pk_mul_f32 v[62:63], v[62:63], v[142:143]
	ds_write_b128 v66, v[56:59] offset:8256
	ds_write_b128 v66, v[60:63] offset:24640
	v_add3_u32 v67, v167, v67, v165
	v_lshl_add_u64 v[56:57], s[2:3], 0, v[64:65]
	s_mov_b64 s[2:3], s[48:49]
	s_waitcnt vmcnt(0) lgkmcnt(0)
	v_add_f32_e32 v52, v52, v240
	v_lshl_add_u64 v[60:61], s[2:3], 0, v[64:65]
	s_mov_b64 s[2:3], s[74:75]
	s_add_u32 s2, s2, s30
	s_addc_u32 s3, s3, 0
	v_lshl_add_u64 v[68:69], s[2:3], 0, v[144:145]
	v_add_co_u32_e64 v68, s[8:9], s37, v68
	v_mul_f32_e32 v52, 0xbfb8aa3b, v52
	s_nop 0
	v_addc_co_u32_e64 v69, s[8:9], 0, v69, s[8:9]
	v_exp_f32_e32 v52, v52
	v_add_f32_e32 v54, v54, v242
	v_mul_f32_e32 v54, 0xbfb8aa3b, v54
	v_exp_f32_e32 v54, v54
	v_add_f32_e32 v52, 1.0, v52
	v_rcp_f32_e32 v52, v52
	ds_read_b64 v[72:73], v67
	v_add_f32_e32 v54, 1.0, v54
	v_rcp_f32_e32 v54, v54
	s_mov_b64 s[2:3], s[44:45]
	s_waitcnt lgkmcnt(0)
	v_lshlrev_b32_e32 v74, 16, v72
	v_and_b32_e32 v75, 0xffff0000, v72
	v_lshlrev_b32_e32 v72, 16, v73
	v_and_b32_e32 v73, 0xffff0000, v73
	v_add_f32_e32 v48, v48, v244
	v_mul_f32_e32 v48, 0xbfb8aa3b, v48
	v_exp_f32_e32 v48, v48
	v_add_f32_e32 v50, v50, v246
	v_mul_f32_e32 v50, 0xbfb8aa3b, v50
	v_exp_f32_e32 v50, v50
	v_add_f32_e32 v48, 1.0, v48
	v_rcp_f32_e32 v56, v48
	v_add_f32_e32 v48, v53, v241
	v_mul_f32_e32 v48, 0xbfb8aa3b, v48
	v_exp_f32_e32 v48, v48
	v_add_f32_e32 v50, 1.0, v50
	v_rcp_f32_e32 v58, v50
	v_add_f32_e32 v50, v55, v243
	v_add_f32_e32 v48, 1.0, v48
	v_rcp_f32_e32 v53, v48
	v_add_f32_e32 v48, v49, v245
	v_mul_f32_e32 v48, 0xbfb8aa3b, v48
	v_exp_f32_e32 v48, v48
	v_mul_f32_e32 v50, 0xbfb8aa3b, v50
	v_exp_f32_e32 v50, v50
	v_add_f32_e32 v48, 1.0, v48
	v_rcp_f32_e32 v57, v48
	v_pk_mul_f32 v[48:49], v[52:53], s[38:39] op_sel_hi:[1,0]
	v_add_f32_e32 v50, 1.0, v50
	v_pk_mul_f32 v[52:53], v[248:249], v[48:49]
	v_rcp_f32_e32 v55, v50
	v_pk_add_f32 v[60:61], v[52:53], v[52:53]
	v_mul_f32_e32 v48, 0x3fb8aa3b, v52
	v_fmamk_f32 v49, v60, 0x3ab60b61, v195
	v_exp_f32_e32 v48, v48
	v_fmaak_f32 v49, v60, v49, 0x3d2aaaab
	v_fmaak_f32 v49, v60, v49, 0x3e2aaaab
	v_fma_f32 v49, v60, v49, 0.5
	v_fma_f32 v49, v60, v49, 1.0
	v_add_f32_e32 v50, v51, v247
	v_mul_f32_e64 v49, v49, -v60
	v_fma_f32 v52, -v48, v48, 1.0
	v_cmp_lt_f32_e64 s[12:13], s84, v60
	v_mul_f32_e32 v50, 0xbfb8aa3b, v50
	v_exp_f32_e32 v50, v50
	v_cndmask_b32_e64 v49, v52, v49, s[12:13]
	v_sqrt_f32_e32 v52, v49
	v_mul_f32_e32 v49, 0x3fb8aa3b, v53
	v_fmamk_f32 v53, v61, 0x3ab60b61, v195
	v_exp_f32_e32 v49, v49
	v_fmaak_f32 v53, v61, v53, 0x3d2aaaab
	v_fmaak_f32 v53, v61, v53, 0x3e2aaaab
	v_fma_f32 v53, v61, v53, 0.5
	v_add_f32_e32 v50, 1.0, v50
	v_fma_f32 v53, v61, v53, 1.0
	v_rcp_f32_e32 v59, v50
	v_pk_mul_f32 v[50:51], v[54:55], s[38:39] op_sel_hi:[1,0]
	v_cmp_lt_f32_e64 s[8:9], s84, v61
	v_mul_f32_e64 v53, v53, -v61
	v_fma_f32 v60, -v49, v49, 1.0
	v_pk_mul_f32 v[54:55], v[250:251], v[50:51]
	v_cndmask_b32_e64 v53, v60, v53, s[8:9]
	v_pk_add_f32 v[60:61], v[54:55], v[54:55]
	v_mul_f32_e32 v50, 0x3fb8aa3b, v54
	v_fmamk_f32 v51, v60, 0x3ab60b61, v195
	v_exp_f32_e32 v50, v50
	v_fmaak_f32 v51, v60, v51, 0x3d2aaaab
	v_fmaak_f32 v51, v60, v51, 0x3e2aaaab
	v_fma_f32 v51, v60, v51, 0.5
	v_fma_f32 v51, v60, v51, 1.0
	v_mul_f32_e64 v51, v51, -v60
	v_fma_f32 v54, -v50, v50, 1.0
	v_cmp_lt_f32_e64 s[12:13], s84, v60
	v_cmp_lt_f32_e64 s[8:9], s84, v61
	v_sqrt_f32_e32 v53, v53
	v_cndmask_b32_e64 v51, v54, v51, s[12:13]
	v_sqrt_f32_e32 v54, v51
	v_mul_f32_e32 v51, 0x3fb8aa3b, v55
	v_fmamk_f32 v55, v61, 0x3ab60b61, v195
	v_exp_f32_e32 v51, v51
	v_fmaak_f32 v55, v61, v55, 0x3d2aaaab
	v_fmaak_f32 v55, v61, v55, 0x3e2aaaab
	v_fma_f32 v55, v61, v55, 0.5
	v_fma_f32 v55, v61, v55, 1.0
	v_mul_f32_e64 v55, v55, -v61
	v_fma_f32 v60, -v51, v51, 1.0
	v_cndmask_b32_e64 v55, v60, v55, s[8:9]
	v_sqrt_f32_e32 v55, v55
	v_pk_mul_f32 v[52:53], v[56:57], v[52:53]
	v_bitop3_b32 v60, v166, v164, 6 bitop3:0x36
	v_pk_mul_f32 v[52:53], v[52:53], v[74:75]
	v_pk_mul_f32 v[54:55], v[58:59], v[54:55]
	v_lshlrev_b32_e32 v60, 4, v60
	v_pk_mul_f32 v[54:55], v[54:55], v[72:73]
	ds_write_b128 v66, v[48:51] offset:8320
	ds_write_b128 v66, v[52:55] offset:24704
	v_add3_u32 v60, v167, v60, v165
	v_lshl_add_u64 v[48:49], s[2:3], 0, v[64:65]
	s_mov_b64 s[2:3], s[48:49]
	s_waitcnt vmcnt(0) lgkmcnt(0)
	v_add_f32_e32 v12, v12, v178
	v_lshl_add_u64 v[52:53], s[2:3], 0, v[64:65]
	s_mov_b64 s[2:3], s[74:75]
	s_add_u32 s2, s2, s30
	s_addc_u32 s3, s3, 0
	v_lshl_add_u64 v[56:57], s[2:3], 0, v[144:145]
	v_add_co_u32_e64 v56, s[8:9], s37, v56
	v_mul_f32_e32 v12, 0xbfb8aa3b, v12
	s_nop 0
	v_addc_co_u32_e64 v57, s[8:9], 0, v57, s[8:9]
	flat_load_dwordx4 v[56:59], v[56:57] offset:2240
	v_exp_f32_e32 v12, v12
	v_add_f32_e32 v14, v14, v180
	v_mul_f32_e32 v14, 0xbfb8aa3b, v14
	v_exp_f32_e32 v14, v14
	v_add_f32_e32 v12, 1.0, v12
	v_rcp_f32_e32 v12, v12
	ds_read_b64 v[60:61], v60
	v_add_f32_e32 v14, 1.0, v14
	v_rcp_f32_e32 v14, v14
	s_waitcnt lgkmcnt(0)
	v_lshlrev_b32_e32 v62, 16, v60
	v_and_b32_e32 v63, 0xffff0000, v60
	v_lshlrev_b32_e32 v60, 16, v61
	v_and_b32_e32 v61, 0xffff0000, v61
	s_waitcnt vmcnt(0)
	v_add_f32_e32 v8, v8, v182
	v_mul_f32_e32 v8, 0xbfb8aa3b, v8
	v_exp_f32_e32 v8, v8
	v_add_f32_e32 v10, v10, v184
	v_mul_f32_e32 v10, 0xbfb8aa3b, v10
	v_exp_f32_e32 v10, v10
	v_add_f32_e32 v8, 1.0, v8
	v_rcp_f32_e32 v48, v8
	v_add_f32_e32 v8, v13, v179
	v_mul_f32_e32 v8, 0xbfb8aa3b, v8
	v_exp_f32_e32 v8, v8
	v_add_f32_e32 v10, 1.0, v10
	v_rcp_f32_e32 v50, v10
	v_add_f32_e32 v10, v15, v181
	v_add_f32_e32 v8, 1.0, v8
	v_rcp_f32_e32 v13, v8
	v_add_f32_e32 v8, v9, v183
	v_mul_f32_e32 v8, 0xbfb8aa3b, v8
	v_exp_f32_e32 v8, v8
	v_mul_f32_e32 v10, 0xbfb8aa3b, v10
	v_exp_f32_e32 v10, v10
	v_add_f32_e32 v8, 1.0, v8
	v_rcp_f32_e32 v49, v8
	v_pk_mul_f32 v[8:9], v[12:13], s[38:39] op_sel_hi:[1,0]
	v_add_f32_e32 v10, 1.0, v10
	v_pk_mul_f32 v[12:13], v[56:57], v[8:9]
	v_rcp_f32_e32 v15, v10
	v_pk_add_f32 v[52:53], v[12:13], v[12:13]
	v_mul_f32_e32 v8, 0x3fb8aa3b, v12
	v_fmamk_f32 v9, v52, 0x3ab60b61, v195
	v_exp_f32_e32 v8, v8
	v_fmaak_f32 v9, v52, v9, 0x3d2aaaab
	v_fmaak_f32 v9, v52, v9, 0x3e2aaaab
	v_fma_f32 v9, v52, v9, 0.5
	v_fma_f32 v9, v52, v9, 1.0
	v_add_f32_e32 v10, v11, v185
	v_mul_f32_e64 v9, v9, -v52
	v_fma_f32 v12, -v8, v8, 1.0
	v_cmp_lt_f32_e64 s[12:13], s84, v52
	v_mul_f32_e32 v10, 0xbfb8aa3b, v10
	v_exp_f32_e32 v10, v10
	v_cndmask_b32_e64 v9, v12, v9, s[12:13]
	v_sqrt_f32_e32 v12, v9
	v_mul_f32_e32 v9, 0x3fb8aa3b, v13
	v_fmamk_f32 v13, v53, 0x3ab60b61, v195
	v_exp_f32_e32 v9, v9
	v_fmaak_f32 v13, v53, v13, 0x3d2aaaab
	v_fmaak_f32 v13, v53, v13, 0x3e2aaaab
	v_fma_f32 v13, v53, v13, 0.5
	v_add_f32_e32 v10, 1.0, v10
	v_fma_f32 v13, v53, v13, 1.0
	v_rcp_f32_e32 v51, v10
	v_pk_mul_f32 v[10:11], v[14:15], s[38:39] op_sel_hi:[1,0]
	v_cmp_lt_f32_e64 s[8:9], s84, v53
	v_mul_f32_e64 v13, v13, -v53
	v_fma_f32 v52, -v9, v9, 1.0
	v_pk_mul_f32 v[14:15], v[58:59], v[10:11]
	v_cndmask_b32_e64 v13, v52, v13, s[8:9]
	v_pk_add_f32 v[52:53], v[14:15], v[14:15]
	v_mul_f32_e32 v10, 0x3fb8aa3b, v14
	v_fmamk_f32 v11, v52, 0x3ab60b61, v195
	v_exp_f32_e32 v10, v10
	v_fmaak_f32 v11, v52, v11, 0x3d2aaaab
	v_fmaak_f32 v11, v52, v11, 0x3e2aaaab
	v_fma_f32 v11, v52, v11, 0.5
	v_fma_f32 v11, v52, v11, 1.0
	v_mul_f32_e64 v11, v11, -v52
	v_fma_f32 v14, -v10, v10, 1.0
	v_cmp_lt_f32_e64 s[12:13], s84, v52
	v_cmp_lt_f32_e64 s[8:9], s84, v53
	v_sqrt_f32_e32 v13, v13
	v_cndmask_b32_e64 v11, v14, v11, s[12:13]
	v_sqrt_f32_e32 v14, v11
	v_mul_f32_e32 v11, 0x3fb8aa3b, v15
	v_fmamk_f32 v15, v53, 0x3ab60b61, v195
	v_exp_f32_e32 v11, v11
	v_fmaak_f32 v15, v53, v15, 0x3d2aaaab
	v_fmaak_f32 v15, v53, v15, 0x3e2aaaab
	v_fma_f32 v15, v53, v15, 0.5
	v_fma_f32 v15, v53, v15, 1.0
	v_mul_f32_e64 v15, v15, -v53
	v_fma_f32 v52, -v11, v11, 1.0
	v_cndmask_b32_e64 v15, v52, v15, s[8:9]
	v_sqrt_f32_e32 v15, v15
	v_pk_mul_f32 v[12:13], v[48:49], v[12:13]
	v_cmp_gt_i32_e64 s[8:9], 3, v161
	v_pk_mul_f32 v[12:13], v[12:13], v[62:63]
	v_pk_mul_f32 v[14:15], v[50:51], v[14:15]
	s_nop 0
	v_pk_mul_f32 v[14:15], v[14:15], v[60:61]
	ds_write_b128 v66, v[8:11] offset:8384
	ds_write_b128 v66, v[12:15] offset:24768
	v_and_b32_e32 v8, 63, v163
	v_lshlrev_b32_e32 v10, 2, v8
	v_lshl_or_b32 v9, v161, 12, v10
	v_add_u32_e32 v12, s60, v9
	s_waitcnt lgkmcnt(0)
	s_barrier
	ds_read2st64_b32 v[14:15], v12 offset0:46 offset1:47
	ds_read2st64_b32 v[48:49], v12 offset0:110 offset1:111
	ds_read2st64_b32 v[50:51], v12 offset0:44 offset1:45
	ds_read2st64_b32 v[52:53], v12 offset0:108 offset1:109
	v_and_b32_e32 v11, 0x1fffffc0, v162
	s_waitcnt lgkmcnt(2)
	v_fma_f32 v9, 0, v15, v49
	v_fmac_f32_e32 v48, v9, v14
	s_waitcnt lgkmcnt(0)
	v_fma_f32 v9, v48, v51, v53
	ds_read2st64_b32 v[48:49], v12 offset0:42 offset1:43
	ds_read2st64_b32 v[54:55], v12 offset0:106 offset1:107
	v_fmac_f32_e32 v52, v9, v50
	v_mul_f32_e32 v14, v15, v14
	v_mov_b32_e32 v62, v51
	s_waitcnt lgkmcnt(0)
	v_fma_f32 v9, v52, v49, v55
	ds_read2st64_b32 v[52:53], v12 offset0:40 offset1:41
	ds_read2st64_b32 v[56:57], v12 offset0:104 offset1:105
	v_fmac_f32_e32 v54, v9, v48
	s_waitcnt lgkmcnt(1)
	v_mov_b32_e32 v66, v53
	s_waitcnt lgkmcnt(0)
	v_fma_f32 v9, v54, v53, v57
	ds_read2st64_b32 v[54:55], v12 offset0:38 offset1:39
	ds_read2st64_b32 v[58:59], v12 offset0:102 offset1:103
	v_fmac_f32_e32 v56, v9, v52
	v_mul_f32_e32 v9, v14, v51
	v_mov_b32_e32 v68, v53
	s_waitcnt lgkmcnt(1)
	v_mov_b32_e32 v63, v54
	s_waitcnt lgkmcnt(0)
	v_fmac_f32_e32 v59, v56, v55
	ds_read2st64_b32 v[56:57], v12 offset0:36 offset1:37
	ds_read2st64_b32 v[60:61], v12 offset0:100 offset1:101
	v_mov_b32_e32 v15, v59
	v_mov_b32_e32 v51, v58
	v_pk_fma_f32 v[14:15], v[14:15], v[62:63], v[50:51]
	v_mul_f32_e32 v58, v9, v50
	v_mov_b32_e32 v59, v15
	v_mov_b32_e32 v14, v49
	s_waitcnt lgkmcnt(1)
	v_mov_b32_e32 v15, v57
	v_pk_mul_f32 v[50:51], v[58:59], v[14:15]
	s_waitcnt lgkmcnt(0)
	v_mov_b32_e32 v49, v61
	v_pk_mul_f32 v[50:51], v[50:51], v[48:49]
	v_pk_fma_f32 v[14:15], v[58:59], v[14:15], v[48:49]
	ds_read2st64_b32 v[48:49], v12 offset0:34 offset1:35
	ds_read2st64_b32 v[58:59], v12 offset0:98 offset1:99
	ds_read2st64_b32 v[62:63], v12 offset0:32 offset1:33
	ds_read2st64_b32 v[64:65], v12 offset0:96 offset1:97
	v_mov_b32_e32 v14, v50
	v_mov_b32_e32 v69, v56
	v_pk_mul_f32 v[50:51], v[50:51], v[66:67]
	v_mov_b32_e32 v53, v60
	v_pk_mul_f32 v[50:51], v[50:51], v[52:53]
	v_pk_fma_f32 v[14:15], v[14:15], v[68:69], v[52:53]
	v_lshl_add_u32 v9, v8, 3, s60
	v_mov_b32_e32 v51, v15
	v_mov_b32_e32 v14, v55
	s_waitcnt lgkmcnt(3)
	v_mov_b32_e32 v15, v49
	v_pk_mul_f32 v[52:53], v[50:51], v[14:15]
	s_waitcnt lgkmcnt(2)
	v_mov_b32_e32 v55, v59
	v_pk_mul_f32 v[52:53], v[52:53], v[54:55]
	v_pk_fma_f32 v[14:15], v[50:51], v[14:15], v[54:55]
	v_mov_b32_e32 v50, v57
	v_mov_b32_e32 v14, v52
	v_mov_b32_e32 v54, v57
	v_mov_b32_e32 v55, v48
	v_pk_mul_f32 v[50:51], v[52:53], v[50:51]
	v_mov_b32_e32 v57, v58
	v_pk_mul_f32 v[50:51], v[50:51], v[56:57]
	v_pk_fma_f32 v[14:15], v[14:15], v[54:55], v[56:57]
	v_lshl_add_u32 v11, v11, 3, v9
	v_mov_b32_e32 v51, v15
	v_mov_b32_e32 v14, v49
	s_waitcnt lgkmcnt(1)
	v_mov_b32_e32 v15, v63
	v_pk_mul_f32 v[52:53], v[50:51], v[14:15]
	s_waitcnt lgkmcnt(0)
	v_mov_b32_e32 v49, v65
	v_pk_mul_f32 v[52:53], v[52:53], v[48:49]
	v_pk_fma_f32 v[14:15], v[50:51], v[14:15], v[48:49]
	v_mov_b32_e32 v48, v63
	v_mov_b32_e32 v14, v52
	v_mov_b32_e32 v50, v63
	v_mov_b32_e32 v51, v62
	v_pk_mul_f32 v[48:49], v[52:53], v[48:49]
	v_mov_b32_e32 v63, v64
	v_pk_mul_f32 v[48:49], v[48:49], v[62:63]
	v_pk_fma_f32 v[14:15], v[14:15], v[50:51], v[62:63]
	s_nop 0
	v_mov_b32_e32 v49, v15
	ds_write_b64 v11, v[48:49] offset:40960
	v_sub_u32_e32 v11, v9, v10
	s_waitcnt lgkmcnt(0)
	s_barrier
	ds_read_b32 v11, v11 offset:43264
	s_and_saveexec_b64 s[2:3], s[8:9]
	s_cbranch_execz .LBB0_367
	ds_read_b64 v[14:15], v9 offset:42496
	s_waitcnt lgkmcnt(0)
	v_fmac_f32_e32 v15, v11, v14
	v_mov_b32_e32 v11, v15
	s_or_b64 exec, exec, s[2:3]
	v_cmp_gt_i32_e64 s[8:9], 2, v161
	s_and_saveexec_b64 s[2:3], s[8:9]
	s_cbranch_execnz .LBB0_368

.LBB0_383:
	s_bfe_u32 s25, s0, 0x60003
	s_mov_b64 s[6:7], s[74:75]
	s_waitcnt lgkmcnt(0)
	s_barrier
	s_lshl_b32 s28, s25, 6
	v_lshlrev_b32_e32 v144, 1, v78
	s_add_i32 s29, s28, -2
	v_lshl_add_u64 v[8:9], s[6:7], 0, v[144:145]
	s_mov_b64 s[6:7], 0x91e0000
	s_ashr_i32 s26, s0, 9
	v_lshl_add_u64 v[48:49], v[8:9], 0, s[6:7]
	v_add_u32_e32 v50, s29, v79
	s_waitcnt vmcnt(0)
	v_mov_b64_e32 v[14:15], v[6:7]
	s_lshl_b32 s27, s26, 12
	v_cmp_gt_u32_e32 vcc, s67, v50
	v_mov_b64_e32 v[12:13], v[4:5]
	v_mov_b64_e32 v[10:11], v[2:3]
	v_mov_b64_e32 v[8:9], v[0:1]
	v_mov_b64_e32 v[216:217], 0
	v_mov_b64_e32 v[218:219], 0
	s_and_saveexec_b64 s[6:7], vcc
	v_or_b32_e32 v232, s27, v50
	v_ashrrev_i32_e32 v233, 31, v232
	v_lshlrev_b64 v[232:233], 10, v[232:233]
	v_lshl_add_u64 v[232:233], v[48:49], 0, v[232:233]
	global_load_dwordx4 v[216:219], v[232:233], off
	s_or_b64 exec, exec, s[6:7]
	v_add_u32_e32 v51, 1, v50
	v_cmp_gt_u32_e32 vcc, s67, v51
	v_mov_b64_e32 v[220:221], 0
	v_mov_b64_e32 v[222:223], 0
	s_and_saveexec_b64 s[6:7], vcc
	v_or_b32_e32 v234, s27, v51
	v_ashrrev_i32_e32 v235, 31, v234
	v_lshlrev_b64 v[234:235], 10, v[234:235]
	v_lshl_add_u64 v[234:235], v[48:49], 0, v[234:235]
	global_load_dwordx4 v[220:223], v[234:235], off
	s_or_b64 exec, exec, s[6:7]
	v_add_u32_e32 v51, s28, v79
	v_cmp_gt_u32_e32 vcc, s67, v51
	v_mov_b64_e32 v[224:225], 0
	v_mov_b64_e32 v[226:227], 0
	s_and_saveexec_b64 s[6:7], vcc
	v_or_b32_e32 v236, s27, v51
	v_ashrrev_i32_e32 v237, 31, v236
	v_lshlrev_b64 v[236:237], 10, v[236:237]
	v_lshl_add_u64 v[236:237], v[48:49], 0, v[236:237]
	global_load_dwordx4 v[224:227], v[236:237], off
	s_or_b64 exec, exec, s[6:7]
	v_add_u32_e32 v50, 3, v50
	v_cmp_gt_u32_e32 vcc, s67, v50
	v_mov_b64_e32 v[228:229], 0
	v_mov_b64_e32 v[230:231], 0
	s_and_saveexec_b64 s[6:7], vcc
	v_or_b32_e32 v238, s27, v50
	v_ashrrev_i32_e32 v239, 31, v238
	v_lshlrev_b64 v[238:239], 10, v[238:239]
	v_lshl_add_u64 v[238:239], v[48:49], 0, v[238:239]
	global_load_dwordx4 v[228:231], v[238:239], off
	s_or_b64 exec, exec, s[6:7]
	s_waitcnt vmcnt(0)
	v_lshlrev_b32_e32 v52, 16, v216
	v_and_b32_e32 v53, 0xffff0000, v216
	v_lshlrev_b32_e32 v8, 16, v217
	v_and_b32_e32 v9, 0xffff0000, v217
	v_lshlrev_b32_e32 v12, 16, v218
	v_and_b32_e32 v13, 0xffff0000, v218
	v_lshlrev_b32_e32 v10, 16, v219
	v_and_b32_e32 v11, 0xffff0000, v219
	v_pk_fma_f32 v[14:15], v[22:23], v[10:11], v[6:7]
	v_pk_fma_f32 v[12:13], v[20:21], v[12:13], v[4:5]
	v_pk_fma_f32 v[10:11], v[18:19], v[8:9], v[2:3]
	v_pk_fma_f32 v[8:9], v[16:17], v[52:53], v[0:1]
	v_lshlrev_b32_e32 v56, 16, v220
	v_and_b32_e32 v57, 0xffff0000, v220
	v_lshlrev_b32_e32 v52, 16, v221
	v_and_b32_e32 v53, 0xffff0000, v221
	v_lshlrev_b32_e32 v58, 16, v222
	v_and_b32_e32 v59, 0xffff0000, v222
	v_lshlrev_b32_e32 v54, 16, v223
	v_and_b32_e32 v55, 0xffff0000, v223
	v_pk_fma_f32 v[14:15], v[30:31], v[54:55], v[14:15]
	v_pk_fma_f32 v[12:13], v[28:29], v[58:59], v[12:13]
	v_pk_fma_f32 v[10:11], v[26:27], v[52:53], v[10:11]
	v_pk_fma_f32 v[8:9], v[24:25], v[56:57], v[8:9]
	v_lshlrev_b32_e32 v56, 16, v224
	v_and_b32_e32 v57, 0xffff0000, v224
	v_lshlrev_b32_e32 v52, 16, v225
	v_and_b32_e32 v53, 0xffff0000, v225
	v_lshlrev_b32_e32 v58, 16, v226
	v_and_b32_e32 v59, 0xffff0000, v226
	v_lshlrev_b32_e32 v54, 16, v227
	v_and_b32_e32 v55, 0xffff0000, v227
	v_pk_fma_f32 v[14:15], v[38:39], v[54:55], v[14:15]
	v_pk_fma_f32 v[12:13], v[36:37], v[58:59], v[12:13]
	v_pk_fma_f32 v[10:11], v[34:35], v[52:53], v[10:11]
	v_pk_fma_f32 v[8:9], v[32:33], v[56:57], v[8:9]
	v_lshlrev_b32_e32 v54, 16, v228
	v_and_b32_e32 v55, 0xffff0000, v228
	v_lshlrev_b32_e32 v50, 16, v229
	v_and_b32_e32 v51, 0xffff0000, v229
	v_lshlrev_b32_e32 v56, 16, v230
	v_and_b32_e32 v57, 0xffff0000, v230
	v_lshlrev_b32_e32 v52, 16, v231
	v_and_b32_e32 v53, 0xffff0000, v231
	v_pk_fma_f32 v[14:15], v[46:47], v[52:53], v[14:15]
	v_pk_fma_f32 v[12:13], v[44:45], v[56:57], v[12:13]
	v_pk_fma_f32 v[10:11], v[42:43], v[50:51], v[10:11]
	v_pk_fma_f32 v[8:9], v[40:41], v[54:55], v[8:9]
	v_cvt_pk_bf16_f32 v8, v8, v9
	v_cvt_pk_bf16_f32 v9, v10, v11
	v_cvt_pk_bf16_f32 v10, v12, v13
	v_cvt_pk_bf16_f32 v11, v14, v15
	ds_write_b128 v81, v[8:11]
	v_add_u32_e32 v50, s29, v80
	v_mov_b64_e32 v[14:15], v[6:7]
	v_cmp_gt_u32_e32 vcc, s67, v50
	v_mov_b64_e32 v[12:13], v[4:5]
	v_mov_b64_e32 v[10:11], v[2:3]
	v_mov_b64_e32 v[8:9], v[0:1]
	v_mov_b64_e32 v[216:217], 0
	v_mov_b64_e32 v[218:219], 0
	s_and_saveexec_b64 s[6:7], vcc
	v_or_b32_e32 v232, s27, v50
	v_ashrrev_i32_e32 v233, 31, v232
	v_lshlrev_b64 v[232:233], 10, v[232:233]
	v_lshl_add_u64 v[232:233], v[48:49], 0, v[232:233]
	global_load_dwordx4 v[216:219], v[232:233], off
	s_or_b64 exec, exec, s[6:7]
	v_add_u32_e32 v51, 1, v50
	v_cmp_gt_u32_e32 vcc, s67, v51
	v_mov_b64_e32 v[220:221], 0
	v_mov_b64_e32 v[222:223], 0
	s_and_saveexec_b64 s[6:7], vcc
	v_or_b32_e32 v234, s27, v51
	v_ashrrev_i32_e32 v235, 31, v234
	v_lshlrev_b64 v[234:235], 10, v[234:235]
	v_lshl_add_u64 v[234:235], v[48:49], 0, v[234:235]
	global_load_dwordx4 v[220:223], v[234:235], off
	s_or_b64 exec, exec, s[6:7]
	v_add_u32_e32 v51, s28, v80
	v_cmp_gt_u32_e32 vcc, s67, v51
	v_mov_b64_e32 v[224:225], 0
	v_mov_b64_e32 v[226:227], 0
	s_and_saveexec_b64 s[6:7], vcc
	v_or_b32_e32 v236, s27, v51
	v_ashrrev_i32_e32 v237, 31, v236
	v_lshlrev_b64 v[236:237], 10, v[236:237]
	v_lshl_add_u64 v[236:237], v[48:49], 0, v[236:237]
	global_load_dwordx4 v[224:227], v[236:237], off
	s_or_b64 exec, exec, s[6:7]
	v_add_u32_e32 v50, 3, v50
	v_cmp_gt_u32_e32 vcc, s67, v50
	v_mov_b64_e32 v[228:229], 0
	v_mov_b64_e32 v[230:231], 0
	s_and_saveexec_b64 s[6:7], vcc
	v_or_b32_e32 v238, s27, v50
	v_ashrrev_i32_e32 v239, 31, v238
	v_lshlrev_b64 v[238:239], 10, v[238:239]
	v_lshl_add_u64 v[238:239], v[48:49], 0, v[238:239]
	global_load_dwordx4 v[228:231], v[238:239], off
	s_or_b64 exec, exec, s[6:7]
	s_waitcnt vmcnt(0)
	v_lshlrev_b32_e32 v52, 16, v216
	v_and_b32_e32 v53, 0xffff0000, v216
	v_lshlrev_b32_e32 v8, 16, v217
	v_and_b32_e32 v9, 0xffff0000, v217
	v_lshlrev_b32_e32 v12, 16, v218
	v_and_b32_e32 v13, 0xffff0000, v218
	v_lshlrev_b32_e32 v10, 16, v219
	v_and_b32_e32 v11, 0xffff0000, v219
	v_pk_fma_f32 v[14:15], v[22:23], v[10:11], v[6:7]
	v_pk_fma_f32 v[12:13], v[20:21], v[12:13], v[4:5]
	v_pk_fma_f32 v[10:11], v[18:19], v[8:9], v[2:3]
	v_pk_fma_f32 v[8:9], v[16:17], v[52:53], v[0:1]
	v_lshlrev_b32_e32 v56, 16, v220
	v_and_b32_e32 v57, 0xffff0000, v220
	v_lshlrev_b32_e32 v52, 16, v221
	v_and_b32_e32 v53, 0xffff0000, v221
	v_lshlrev_b32_e32 v58, 16, v222
	v_and_b32_e32 v59, 0xffff0000, v222
	v_lshlrev_b32_e32 v54, 16, v223
	v_and_b32_e32 v55, 0xffff0000, v223
	v_pk_fma_f32 v[14:15], v[30:31], v[54:55], v[14:15]
	v_pk_fma_f32 v[12:13], v[28:29], v[58:59], v[12:13]
	v_pk_fma_f32 v[10:11], v[26:27], v[52:53], v[10:11]
	v_pk_fma_f32 v[8:9], v[24:25], v[56:57], v[8:9]
	v_lshlrev_b32_e32 v56, 16, v224
	v_and_b32_e32 v57, 0xffff0000, v224
	v_lshlrev_b32_e32 v52, 16, v225
	v_and_b32_e32 v53, 0xffff0000, v225
	v_lshlrev_b32_e32 v58, 16, v226
	v_and_b32_e32 v59, 0xffff0000, v226
	v_lshlrev_b32_e32 v54, 16, v227
	v_and_b32_e32 v55, 0xffff0000, v227
	v_pk_fma_f32 v[14:15], v[38:39], v[54:55], v[14:15]
	v_pk_fma_f32 v[12:13], v[36:37], v[58:59], v[12:13]
	v_pk_fma_f32 v[10:11], v[34:35], v[52:53], v[10:11]
	v_pk_fma_f32 v[8:9], v[32:33], v[56:57], v[8:9]
	v_lshlrev_b32_e32 v52, 16, v228
	v_and_b32_e32 v53, 0xffff0000, v228
	v_lshlrev_b32_e32 v48, 16, v229
	v_and_b32_e32 v49, 0xffff0000, v229
	v_lshlrev_b32_e32 v54, 16, v230
	v_and_b32_e32 v55, 0xffff0000, v230
	v_lshlrev_b32_e32 v50, 16, v231
	v_and_b32_e32 v51, 0xffff0000, v231
	v_pk_fma_f32 v[14:15], v[46:47], v[50:51], v[14:15]
	v_pk_fma_f32 v[12:13], v[44:45], v[54:55], v[12:13]
	v_pk_fma_f32 v[10:11], v[42:43], v[48:49], v[10:11]
	v_pk_fma_f32 v[8:9], v[40:41], v[52:53], v[8:9]
	v_mov_b32_e32 v83, v191
	v_cvt_pk_bf16_f32 v8, v8, v9
	v_cvt_pk_bf16_f32 v9, v10, v11
	v_cvt_pk_bf16_f32 v10, v12, v13
	v_cvt_pk_bf16_f32 v11, v14, v15
	ds_write_b128 v82, v[8:11]
	s_waitcnt lgkmcnt(0)
	s_barrier
	v_mov_b32_e32 v85, v191
	v_and_b32_e32 v87, 15, v83
	v_lshrrev_b32_e32 v96, 4, v83
	v_bfe_u32 v97, v83, 4, 2
	s_mov_b64 s[6:7], s[74:75]
	v_bfe_u32 v86, v83, 1, 3
	v_ashrrev_i32_e32 v84, 6, v83
	v_lshlrev_b32_e32 v76, 7, v87
	v_bitop3_b32 v8, v96, v86, 3 bitop3:0x6c
	v_bitop3_b32 v13, v97, v86, 4 bitop3:0x36
	v_lshl_or_b32 v12, v84, 11, v76
	v_lshlrev_b32_e32 v8, 4, v8
	v_lshlrev_b32_e32 v13, 4, v13
	s_add_u32 s6, s6, s2
	v_add3_u32 v8, s60, v8, v12
	v_add3_u32 v12, s60, v13, v12
	s_addc_u32 s7, s7, 0
	v_lshlrev_b32_e32 v144, 4, v97
	ds_read_b128 v[8:11], v8
	ds_read_b128 v[72:75], v12
	v_lshl_add_u64 v[12:13], s[6:7], 0, v[144:145]
	s_mov_b64 s[6:7], 0x3980000
	v_lshl_add_u64 v[92:93], v[12:13], 0, s[6:7]
	s_mov_b64 s[6:7], 0x39a0000
	v_mov_b32_e32 v77, v145
	v_lshl_add_u64 v[94:95], v[12:13], 0, s[6:7]
	v_mul_u32_u24_e32 v184, 0xf0, v97
	v_lshl_add_u32 v184, v87, 4, v184
	v_mov_b32_e32 v185, v145
	v_lshl_add_u64 v[60:61], v[92:93], 0, v[184:185]
	v_lshl_add_u64 v[62:63], v[94:95], 0, v[184:185]
	s_mov_b64 s[98:99], 0x1000
	v_lshl_add_u64 v[180:181], v[60:61], 0, s[98:99]
	v_lshl_add_u64 v[182:183], v[62:63], 0, s[98:99]
	global_load_dwordx4 v[104:107], v[180:181], off offset:-4096
	global_load_dwordx4 v[108:111], v[182:183], off offset:-4096
	global_load_dwordx4 v[112:115], v[180:181], off offset:-3072
	global_load_dwordx4 v[116:119], v[182:183], off offset:-3072
	global_load_dwordx4 v[120:123], v[180:181], off offset:-2048
	global_load_dwordx4 v[124:127], v[182:183], off offset:-2048
	global_load_dwordx4 v[128:131], v[180:181], off offset:-1024
	global_load_dwordx4 v[132:135], v[182:183], off offset:-1024
	global_load_dwordx4 v[136:139], v[180:181], off
	global_load_dwordx4 v[140:143], v[182:183], off
	global_load_dwordx4 v[156:159], v[180:181], off offset:1024
	global_load_dwordx4 v[160:163], v[182:183], off offset:1024
	global_load_dwordx4 v[164:167], v[180:181], off offset:2048
	global_load_dwordx4 v[168:171], v[182:183], off offset:2048
	global_load_dwordx4 v[172:175], v[180:181], off offset:3072
	global_load_dwordx4 v[176:179], v[182:183], off offset:3072
	v_lshrrev_b32_e32 v98, 1, v83
	v_readlane_b32 s36, v254, 22
	v_readlane_b32 s40, v254, 26
	v_readlane_b32 s41, v254, 27
	s_mov_b64 s[6:7], s[40:41]
	v_readlane_b32 s44, v254, 30
	v_readlane_b32 s45, v254, 31
	s_mov_b32 s27, 0x122e6000
	s_mov_b32 s28, 0xc1000000
	v_readlane_b32 s37, v254, 23
	v_readlane_b32 s38, v254, 24
	v_readlane_b32 s39, v254, 25
	v_readlane_b32 s42, v254, 28
	v_readlane_b32 s43, v254, 29
	v_readlane_b32 s46, v254, 32
	v_readlane_b32 s47, v254, 33
	v_readlane_b32 s48, v254, 34
	v_readlane_b32 s49, v254, 35
	v_readlane_b32 s50, v254, 36
	v_readlane_b32 s51, v254, 37
	v_lshlrev_b32_e32 v154, 2, v97
	v_or_b32_e32 v154, s8, v154
	v_ashrrev_i32_e32 v155, 31, v154
	v_lshlrev_b64 v[154:155], 2, v[154:155]
	s_add_u32 s98, s74, s3
	s_addc_u32 s99, s75, 0
	s_add_u32 s98, s98, 0x122e6000
	s_addc_u32 s99, s99, 0
	v_lshl_add_u64 v[184:185], s[98:99], 0, v[144:145]
	v_lshl_add_u64 v[180:181], s[40:41], 0, v[154:155]
	v_lshl_add_u64 v[146:147], s[44:45], 0, v[154:155]
	global_load_dwordx4 v[216:219], v[180:181], off
	global_load_dwordx4 v[220:223], v[146:147], off
	global_load_dwordx4 v[224:227], v[184:185], off
	global_load_dwordx4 v[228:231], v[180:181], off offset:64
	global_load_dwordx4 v[232:235], v[146:147], off offset:64
	global_load_dwordx4 v[236:239], v[184:185], off offset:64
	global_load_dwordx4 v[240:243], v[180:181], off offset:128
	global_load_dwordx4 v[244:247], v[146:147], off offset:128
	global_load_dwordx4 v[248:251], v[184:185], off offset:128
	global_load_dwordx4 v[180:183], v[180:181], off offset:192
	global_load_dwordx4 v[146:149], v[146:147], off offset:192
	s_waitcnt vmcnt(0) lgkmcnt(0)
	v_mfma_f32_16x16x32_bf16 v[12:15], v[104:107], v[8:11], 0
	v_mfma_f32_16x16x32_bf16 v[48:51], v[108:111], v[8:11], 0
	v_mfma_f32_16x16x32_bf16 v[68:71], v[112:115], v[72:75], v[12:15]
	v_mfma_f32_16x16x32_bf16 v[64:67], v[116:119], v[72:75], v[48:51]
	s_nop 4
	v_mfma_f32_16x16x32_bf16 v[12:15], v[120:123], v[8:11], 0
	v_mfma_f32_16x16x32_bf16 v[48:51], v[124:127], v[8:11], 0
	v_mfma_f32_16x16x32_bf16 v[60:63], v[128:131], v[72:75], v[12:15]
	s_nop 5
	v_or_b32_e32 v12, 0x1000, v76
	v_mov_b32_e32 v13, v145
	v_lshl_add_u64 v[52:53], v[92:93], 0, v[12:13]
	v_mfma_f32_16x16x32_bf16 v[56:59], v[132:135], v[72:75], v[48:51]
	v_lshl_add_u64 v[88:89], v[94:95], 0, v[12:13]
	s_nop 0
	s_nop 0
	s_nop 0
	v_mfma_f32_16x16x32_bf16 v[12:15], v[136:139], v[8:11], 0
	v_mfma_f32_16x16x32_bf16 v[48:51], v[140:143], v[8:11], 0
	v_mfma_f32_16x16x32_bf16 v[52:55], v[156:159], v[72:75], v[12:15]
	s_nop 5
	v_or_b32_e32 v12, 0x1800, v76
	v_mov_b32_e32 v13, v145
	v_lshl_add_u64 v[76:77], v[92:93], 0, v[12:13]
	v_mfma_f32_16x16x32_bf16 v[48:51], v[160:163], v[72:75], v[48:51]
	v_lshl_add_u64 v[92:93], v[94:95], 0, v[12:13]
	v_mfma_f32_16x16x32_bf16 v[12:15], v[164:167], v[8:11], 0
	v_mfma_f32_16x16x32_bf16 v[8:11], v[168:171], v[8:11], 0
	s_nop 0
	v_lshlrev_b32_e32 v76, 2, v97
	v_mov_b32_e32 v77, v145
	v_mfma_f32_16x16x32_bf16 v[12:15], v[172:175], v[72:75], v[12:15]
	v_bfe_u32 v88, v96, 1, 1
	v_mfma_f32_16x16x32_bf16 v[8:11], v[176:179], v[72:75], v[8:11]
	global_load_dwordx4 v[104:107], v[184:185], off offset:192
	v_lshl_or_b32 v72, v84, 4, v87
	v_lshlrev_b32_e32 v87, 7, v72
	v_and_b32_e32 v73, 8, v98
	v_lshlrev_b32_e32 v102, 8, v72
	v_or_b32_e32 v72, s8, v76
	v_add_u32_e32 v89, s60, v73
	v_ashrrev_i32_e32 v73, 31, v72
	v_lshlrev_b64 v[90:91], 2, v[72:73]
	v_lshl_add_u64 v[72:73], s[6:7], 0, v[90:91]
	s_mov_b64 s[6:7], s[44:45]
	v_bitop3_b32 v98, v88, v98, 7 bitop3:0x78
	v_lshl_add_u64 v[90:91], s[6:7], 0, v[90:91]
	s_mov_b64 s[6:7], s[74:75]
	s_add_u32 s6, s6, s3
	s_addc_u32 s7, s7, 0
	v_lshl_add_u64 v[94:95], s[6:7], 0, v[144:145]
	v_add_co_u32_e32 v94, vcc, s27, v94
	v_lshlrev_b32_e32 v98, 4, v98
	s_nop 0
	v_addc_co_u32_e32 v95, vcc, 0, v95, vcc
	v_add3_u32 v98, v89, v98, v87
	ds_read_b64 v[98:99], v98
	s_waitcnt lgkmcnt(0)
	v_lshlrev_b32_e32 v100, 16, v98
	v_and_b32_e32 v101, 0xffff0000, v98
	v_lshlrev_b32_e32 v98, 16, v99
	v_and_b32_e32 v99, 0xffff0000, v99
	v_add_f32_e32 v68, v68, v216
	v_add_f32_e32 v69, v69, v217
	v_mul_f32_e32 v68, 0xbfb8aa3b, v68
	v_mul_f32_e32 v69, 0xbfb8aa3b, v69
	v_exp_f32_e32 v68, v68
	v_exp_f32_e32 v69, v69
	v_add_f32_e32 v64, v64, v220
	v_add_f32_e32 v65, v65, v221
	v_add_f32_e32 v68, 1.0, v68
	v_add_f32_e32 v69, 1.0, v69
	v_rcp_f32_e32 v68, v68
	v_rcp_f32_e32 v69, v69
	v_add_f32_e32 v70, v70, v218
	v_add_f32_e32 v71, v71, v219
	v_mul_f32_e32 v70, 0xbfb8aa3b, v70
	v_pk_mul_f32 v[68:69], v[68:69], s[28:29] op_sel_hi:[1,0]
	v_mul_f32_e32 v71, 0xbfb8aa3b, v71
	v_pk_mul_f32 v[72:73], v[224:225], v[68:69]
	v_exp_f32_e32 v70, v70
	v_pk_add_f32 v[90:91], v[72:73], v[72:73]
	v_mul_f32_e32 v68, 0x3fb8aa3b, v72
	v_fmamk_f32 v69, v90, 0x3ab60b61, v195
	v_exp_f32_e32 v68, v68
	v_fmaak_f32 v69, v90, v69, 0x3d2aaaab
	v_fmaak_f32 v69, v90, v69, 0x3e2aaaab
	v_exp_f32_e32 v71, v71
	v_fma_f32 v69, v90, v69, 0.5
	v_fma_f32 v69, v90, v69, 1.0
	v_mul_f32_e64 v69, v69, -v90
	v_fma_f32 v72, -v68, v68, 1.0
	v_cmp_lt_f32_e64 s[6:7], s84, v90
	v_add_f32_e32 v70, 1.0, v70
	v_add_f32_e32 v71, 1.0, v71
	v_cndmask_b32_e64 v69, v72, v69, s[6:7]
	v_sqrt_f32_e32 v72, v69
	v_mul_f32_e32 v69, 0x3fb8aa3b, v73
	v_fmamk_f32 v73, v91, 0x3ab60b61, v195
	v_rcp_f32_e32 v70, v70
	v_rcp_f32_e32 v71, v71
	v_exp_f32_e32 v69, v69
	v_fmaak_f32 v73, v91, v73, 0x3d2aaaab
	v_fmaak_f32 v73, v91, v73, 0x3e2aaaab
	v_fma_f32 v73, v91, v73, 0.5
	v_fma_f32 v73, v91, v73, 1.0
	v_pk_mul_f32 v[70:71], v[70:71], s[28:29] op_sel_hi:[1,0]
	v_cmp_lt_f32_e32 vcc, s84, v91
	v_mul_f32_e64 v73, v73, -v91
	v_fma_f32 v90, -v69, v69, 1.0
	v_pk_mul_f32 v[74:75], v[226:227], v[70:71]
	v_cndmask_b32_e32 v73, v90, v73, vcc
	v_pk_add_f32 v[90:91], v[74:75], v[74:75]
	v_mul_f32_e32 v70, 0x3fb8aa3b, v74
	v_fmamk_f32 v71, v90, 0x3ab60b61, v195
	v_exp_f32_e32 v70, v70
	v_fmaak_f32 v71, v90, v71, 0x3d2aaaab
	v_fmaak_f32 v71, v90, v71, 0x3e2aaaab
	v_fma_f32 v71, v90, v71, 0.5
	v_fma_f32 v71, v90, v71, 1.0
	v_mul_f32_e64 v71, v71, -v90
	v_fma_f32 v74, -v70, v70, 1.0
	v_cmp_lt_f32_e64 s[6:7], s84, v90
	v_add_f32_e32 v66, v66, v222
	v_add_f32_e32 v67, v67, v223
	v_cndmask_b32_e64 v71, v74, v71, s[6:7]
	v_sqrt_f32_e32 v74, v71
	v_mul_f32_e32 v71, 0x3fb8aa3b, v75
	v_fmamk_f32 v75, v91, 0x3ab60b61, v195
	v_mul_f32_e32 v64, 0xbfb8aa3b, v64
	v_mul_f32_e32 v65, 0xbfb8aa3b, v65
	v_mul_f32_e32 v66, 0xbfb8aa3b, v66
	v_mul_f32_e32 v67, 0xbfb8aa3b, v67
	v_exp_f32_e32 v71, v71
	v_fmaak_f32 v75, v91, v75, 0x3d2aaaab
	v_exp_f32_e32 v64, v64
	v_exp_f32_e32 v65, v65
	v_exp_f32_e32 v66, v66
	v_exp_f32_e32 v67, v67
	v_fmaak_f32 v75, v91, v75, 0x3e2aaaab
	v_fma_f32 v75, v91, v75, 0.5
	v_fma_f32 v75, v91, v75, 1.0
	v_cmp_lt_f32_e32 vcc, s84, v91
	v_mul_f32_e64 v75, v75, -v91
	v_fma_f32 v90, -v71, v71, 1.0
	v_add_f32_e32 v64, 1.0, v64
	v_add_f32_e32 v65, 1.0, v65
	v_add_f32_e32 v66, 1.0, v66
	v_add_f32_e32 v67, 1.0, v67
	v_cndmask_b32_e32 v75, v90, v75, vcc
	v_rcp_f32_e32 v64, v64
	v_rcp_f32_e32 v65, v65
	v_sqrt_f32_e32 v73, v73
	v_rcp_f32_e32 v66, v66
	v_rcp_f32_e32 v67, v67
	v_sqrt_f32_e32 v75, v75
	v_pk_mul_f32 v[64:65], v[64:65], v[72:73]
	s_mov_b64 s[6:7], s[40:41]
	v_pk_mul_f32 v[72:73], v[64:65], v[100:101]
	v_pk_mul_f32 v[66:67], v[66:67], v[74:75]
	v_lshl_add_u64 v[64:65], v[76:77], 0, s[8:9]
	v_pk_mul_f32 v[74:75], v[66:67], v[98:99]
	v_add3_u32 v66, s60, v102, v144
	ds_write_b128 v66, v[68:71] offset:8192
	ds_write_b128 v66, v[72:75] offset:24576
	v_lshlrev_b64 v[64:65], 2, v[64:65]
	v_lshl_add_u64 v[68:69], s[6:7], 0, v[64:65]
	s_mov_b64 s[6:7], s[44:45]
	v_bitop3_b32 v67, v88, v86, 2 bitop3:0x36
	v_lshl_add_u64 v[72:73], s[6:7], 0, v[64:65]
	s_mov_b64 s[6:7], s[74:75]
	s_add_u32 s6, s6, s3
	s_addc_u32 s7, s7, 0
	v_lshl_add_u64 v[76:77], s[6:7], 0, v[144:145]
	v_add_co_u32_e32 v76, vcc, s27, v76
	v_lshlrev_b32_e32 v67, 4, v67
	s_nop 0
	v_addc_co_u32_e32 v77, vcc, 0, v77, vcc
	v_add3_u32 v67, v89, v67, v87
	ds_read_b64 v[76:77], v67
	s_waitcnt lgkmcnt(0)
	v_lshlrev_b32_e32 v94, 16, v76
	v_and_b32_e32 v95, 0xffff0000, v76
	v_lshlrev_b32_e32 v76, 16, v77
	v_and_b32_e32 v77, 0xffff0000, v77
	v_add_f32_e32 v60, v60, v228
	v_mul_f32_e32 v60, 0xbfb8aa3b, v60
	v_exp_f32_e32 v60, v60
	v_add_f32_e32 v62, v62, v230
	v_add_f32_e32 v56, v56, v232
	v_mul_f32_e32 v56, 0xbfb8aa3b, v56
	v_exp_f32_e32 v56, v56
	v_add_f32_e32 v58, v58, v234
	v_mul_f32_e32 v58, 0xbfb8aa3b, v58
	v_exp_f32_e32 v58, v58
	v_add_f32_e32 v56, 1.0, v56
	v_rcp_f32_e32 v68, v56
	v_add_f32_e32 v56, v61, v229
	v_mul_f32_e32 v56, 0xbfb8aa3b, v56
	v_exp_f32_e32 v56, v56
	v_add_f32_e32 v60, 1.0, v60
	v_rcp_f32_e32 v60, v60
	v_add_f32_e32 v58, 1.0, v58
	v_add_f32_e32 v56, 1.0, v56
	v_rcp_f32_e32 v61, v56
	v_add_f32_e32 v56, v57, v233
	v_mul_f32_e32 v56, 0xbfb8aa3b, v56
	v_exp_f32_e32 v56, v56
	v_rcp_f32_e32 v70, v58
	v_add_f32_e32 v58, v63, v231
	v_mul_f32_e32 v58, 0xbfb8aa3b, v58
	v_add_f32_e32 v56, 1.0, v56
	v_rcp_f32_e32 v69, v56
	v_pk_mul_f32 v[56:57], v[60:61], s[28:29] op_sel_hi:[1,0]
	v_exp_f32_e32 v58, v58
	v_pk_mul_f32 v[60:61], v[236:237], v[56:57]
	v_mul_f32_e32 v62, 0xbfb8aa3b, v62
	v_pk_add_f32 v[72:73], v[60:61], v[60:61]
	v_mul_f32_e32 v56, 0x3fb8aa3b, v60
	v_fmamk_f32 v57, v72, 0x3ab60b61, v195
	v_exp_f32_e32 v56, v56
	v_fmaak_f32 v57, v72, v57, 0x3d2aaaab
	v_exp_f32_e32 v62, v62
	v_fmaak_f32 v57, v72, v57, 0x3e2aaaab
	v_add_f32_e32 v58, 1.0, v58
	v_fma_f32 v57, v72, v57, 0.5
	v_rcp_f32_e32 v63, v58
	v_add_f32_e32 v58, v59, v235
	v_fma_f32 v57, v72, v57, 1.0
	v_mul_f32_e32 v58, 0xbfb8aa3b, v58
	v_mul_f32_e64 v57, v57, -v72
	v_fma_f32 v60, -v56, v56, 1.0
	v_cmp_lt_f32_e64 s[6:7], s84, v72
	v_add_f32_e32 v62, 1.0, v62
	v_exp_f32_e32 v58, v58
	v_cndmask_b32_e64 v57, v60, v57, s[6:7]
	v_rcp_f32_e32 v62, v62
	v_sqrt_f32_e32 v60, v57
	v_mul_f32_e32 v57, 0x3fb8aa3b, v61
	v_fmamk_f32 v61, v73, 0x3ab60b61, v195
	v_fmaak_f32 v61, v73, v61, 0x3d2aaaab
	v_fmaak_f32 v61, v73, v61, 0x3e2aaaab
	v_add_f32_e32 v58, 1.0, v58
	v_fma_f32 v61, v73, v61, 0.5
	v_rcp_f32_e32 v71, v58
	v_pk_mul_f32 v[58:59], v[62:63], s[28:29] op_sel_hi:[1,0]
	v_fma_f32 v61, v73, v61, 1.0
	v_pk_mul_f32 v[62:63], v[238:239], v[58:59]
	v_cmp_lt_f32_e32 vcc, s84, v73
	v_mul_f32_e64 v61, v61, -v73
	v_pk_add_f32 v[72:73], v[62:63], v[62:63]
	v_mul_f32_e32 v58, 0x3fb8aa3b, v62
	v_fmamk_f32 v59, v72, 0x3ab60b61, v195
	v_exp_f32_e32 v58, v58
	v_fmaak_f32 v59, v72, v59, 0x3d2aaaab
	v_fmaak_f32 v59, v72, v59, 0x3e2aaaab
	v_fma_f32 v59, v72, v59, 0.5
	v_fma_f32 v59, v72, v59, 1.0
	v_mul_f32_e64 v59, v59, -v72
	v_fma_f32 v62, -v58, v58, 1.0
	v_cmp_lt_f32_e64 s[6:7], s84, v72
	v_exp_f32_e32 v57, v57
	s_nop 0
	v_cndmask_b32_e64 v59, v62, v59, s[6:7]
	v_sqrt_f32_e32 v62, v59
	v_mul_f32_e32 v59, 0x3fb8aa3b, v63
	v_fmamk_f32 v63, v73, 0x3ab60b61, v195
	v_exp_f32_e32 v59, v59
	v_fmaak_f32 v63, v73, v63, 0x3d2aaaab
	v_fmaak_f32 v63, v73, v63, 0x3e2aaaab
	v_fma_f32 v63, v73, v63, 0.5
	v_fma_f32 v67, -v57, v57, 1.0
	v_fma_f32 v63, v73, v63, 1.0
	v_cndmask_b32_e32 v61, v67, v61, vcc
	v_cmp_lt_f32_e32 vcc, s84, v73
	v_mul_f32_e64 v63, v63, -v73
	v_fma_f32 v67, -v59, v59, 1.0
	v_cndmask_b32_e32 v63, v67, v63, vcc
	v_sqrt_f32_e32 v61, v61
	v_sqrt_f32_e32 v63, v63
	s_mov_b64 s[6:7], s[40:41]
	v_bitop3_b32 v67, v88, v86, 4 bitop3:0x36
	v_pk_mul_f32 v[60:61], v[68:69], v[60:61]
	v_pk_mul_f32 v[62:63], v[70:71], v[62:63]
	v_pk_mul_f32 v[60:61], v[60:61], v[94:95]
	v_pk_mul_f32 v[62:63], v[62:63], v[76:77]
	ds_write_b128 v66, v[56:59] offset:8256
	ds_write_b128 v66, v[60:63] offset:24640
	v_lshlrev_b32_e32 v67, 4, v67
	v_lshl_add_u64 v[56:57], s[6:7], 0, v[64:65]
	s_mov_b64 s[6:7], s[44:45]
	v_add3_u32 v67, v89, v67, v87
	v_lshl_add_u64 v[60:61], s[6:7], 0, v[64:65]
	s_mov_b64 s[6:7], s[74:75]
	s_add_u32 s6, s6, s3
	s_addc_u32 s7, s7, 0
	v_lshl_add_u64 v[68:69], s[6:7], 0, v[144:145]
	v_add_co_u32_e32 v68, vcc, s27, v68
	ds_read_b64 v[72:73], v67
	s_nop 0
	v_addc_co_u32_e32 v69, vcc, 0, v69, vcc
	s_waitcnt lgkmcnt(0)
	v_lshlrev_b32_e32 v74, 16, v72
	v_and_b32_e32 v75, 0xffff0000, v72
	v_lshlrev_b32_e32 v72, 16, v73
	v_and_b32_e32 v73, 0xffff0000, v73
	v_add_f32_e32 v52, v52, v240
	v_mul_f32_e32 v52, 0xbfb8aa3b, v52
	v_exp_f32_e32 v52, v52
	v_add_f32_e32 v54, v54, v242
	v_add_f32_e32 v48, v48, v244
	v_mul_f32_e32 v48, 0xbfb8aa3b, v48
	v_exp_f32_e32 v48, v48
	v_add_f32_e32 v50, v50, v246
	v_mul_f32_e32 v50, 0xbfb8aa3b, v50
	v_add_f32_e32 v52, 1.0, v52
	v_add_f32_e32 v48, 1.0, v48
	v_rcp_f32_e32 v56, v48
	v_add_f32_e32 v48, v53, v241
	v_mul_f32_e32 v48, 0xbfb8aa3b, v48
	v_exp_f32_e32 v48, v48
	v_exp_f32_e32 v50, v50
	v_rcp_f32_e32 v52, v52
	v_mul_f32_e32 v54, 0xbfb8aa3b, v54
	v_add_f32_e32 v48, 1.0, v48
	v_rcp_f32_e32 v53, v48
	v_add_f32_e32 v48, v49, v245
	v_mul_f32_e32 v48, 0xbfb8aa3b, v48
	v_exp_f32_e32 v48, v48
	v_add_f32_e32 v50, 1.0, v50
	v_rcp_f32_e32 v58, v50
	v_add_f32_e32 v50, v55, v243
	v_add_f32_e32 v48, 1.0, v48
	v_rcp_f32_e32 v57, v48
	v_pk_mul_f32 v[48:49], v[52:53], s[28:29] op_sel_hi:[1,0]
	v_mul_f32_e32 v50, 0xbfb8aa3b, v50
	v_pk_mul_f32 v[52:53], v[248:249], v[48:49]
	v_exp_f32_e32 v50, v50
	v_pk_add_f32 v[60:61], v[52:53], v[52:53]
	v_mul_f32_e32 v48, 0x3fb8aa3b, v52
	v_fmamk_f32 v49, v60, 0x3ab60b61, v195
	v_exp_f32_e32 v48, v48
	v_fmaak_f32 v49, v60, v49, 0x3d2aaaab
	v_fmaak_f32 v49, v60, v49, 0x3e2aaaab
	v_exp_f32_e32 v54, v54
	v_fma_f32 v49, v60, v49, 0.5
	v_add_f32_e32 v50, 1.0, v50
	v_fma_f32 v49, v60, v49, 1.0
	v_rcp_f32_e32 v55, v50
	v_add_f32_e32 v50, v51, v247
	v_mul_f32_e64 v49, v49, -v60
	v_fma_f32 v52, -v48, v48, 1.0
	v_cmp_lt_f32_e64 s[6:7], s84, v60
	v_mul_f32_e32 v50, 0xbfb8aa3b, v50
	v_add_f32_e32 v54, 1.0, v54
	v_cndmask_b32_e64 v49, v52, v49, s[6:7]
	v_exp_f32_e32 v50, v50
	v_sqrt_f32_e32 v52, v49
	v_mul_f32_e32 v49, 0x3fb8aa3b, v53
	v_fmamk_f32 v53, v61, 0x3ab60b61, v195
	v_rcp_f32_e32 v54, v54
	v_exp_f32_e32 v49, v49
	v_fmaak_f32 v53, v61, v53, 0x3d2aaaab
	v_fmaak_f32 v53, v61, v53, 0x3e2aaaab
	v_fma_f32 v53, v61, v53, 0.5
	v_add_f32_e32 v50, 1.0, v50
	v_fma_f32 v53, v61, v53, 1.0
	v_rcp_f32_e32 v59, v50
	v_pk_mul_f32 v[50:51], v[54:55], s[28:29] op_sel_hi:[1,0]
	v_cmp_lt_f32_e32 vcc, s84, v61
	v_mul_f32_e64 v53, v53, -v61
	v_fma_f32 v60, -v49, v49, 1.0
	v_pk_mul_f32 v[54:55], v[250:251], v[50:51]
	v_cndmask_b32_e32 v53, v60, v53, vcc
	v_pk_add_f32 v[60:61], v[54:55], v[54:55]
	v_mul_f32_e32 v50, 0x3fb8aa3b, v54
	v_fmamk_f32 v51, v60, 0x3ab60b61, v195
	v_exp_f32_e32 v50, v50
	v_fmaak_f32 v51, v60, v51, 0x3d2aaaab
	v_fmaak_f32 v51, v60, v51, 0x3e2aaaab
	v_fma_f32 v51, v60, v51, 0.5
	v_fma_f32 v51, v60, v51, 1.0
	v_mul_f32_e64 v51, v51, -v60
	v_fma_f32 v54, -v50, v50, 1.0
	v_cmp_lt_f32_e64 s[6:7], s84, v60
	v_cmp_lt_f32_e32 vcc, s84, v61
	v_sqrt_f32_e32 v53, v53
	v_cndmask_b32_e64 v51, v54, v51, s[6:7]
	v_sqrt_f32_e32 v54, v51
	v_mul_f32_e32 v51, 0x3fb8aa3b, v55
	v_fmamk_f32 v55, v61, 0x3ab60b61, v195
	v_exp_f32_e32 v51, v51
	v_fmaak_f32 v55, v61, v55, 0x3d2aaaab
	v_fmaak_f32 v55, v61, v55, 0x3e2aaaab
	v_fma_f32 v55, v61, v55, 0.5
	v_fma_f32 v55, v61, v55, 1.0
	v_mul_f32_e64 v55, v55, -v61
	v_fma_f32 v60, -v51, v51, 1.0
	v_cndmask_b32_e32 v55, v60, v55, vcc
	v_sqrt_f32_e32 v55, v55
	v_pk_mul_f32 v[52:53], v[56:57], v[52:53]
	s_mov_b64 s[6:7], s[40:41]
	v_pk_mul_f32 v[52:53], v[52:53], v[74:75]
	v_pk_mul_f32 v[54:55], v[58:59], v[54:55]
	v_bitop3_b32 v60, v88, v86, 6 bitop3:0x36
	v_pk_mul_f32 v[54:55], v[54:55], v[72:73]
	ds_write_b128 v66, v[48:51] offset:8320
	ds_write_b128 v66, v[52:55] offset:24704
	v_lshlrev_b32_e32 v60, 4, v60
	v_lshl_add_u64 v[48:49], s[6:7], 0, v[64:65]
	s_mov_b64 s[6:7], s[44:45]
	v_add3_u32 v60, v89, v60, v87
	v_lshl_add_u64 v[52:53], s[6:7], 0, v[64:65]
	s_mov_b64 s[6:7], s[74:75]
	s_add_u32 s6, s6, s3
	s_addc_u32 s7, s7, 0
	v_lshl_add_u64 v[56:57], s[6:7], 0, v[144:145]
	v_add_co_u32_e32 v56, vcc, s27, v56
	ds_read_b64 v[60:61], v60
	s_nop 0
	v_addc_co_u32_e32 v57, vcc, 0, v57, vcc
	s_waitcnt lgkmcnt(0)
	v_lshlrev_b32_e32 v62, 16, v60
	v_and_b32_e32 v63, 0xffff0000, v60
	v_lshlrev_b32_e32 v60, 16, v61
	v_and_b32_e32 v61, 0xffff0000, v61
	s_waitcnt vmcnt(0)
	v_add_f32_e32 v12, v12, v180
	v_mul_f32_e32 v12, 0xbfb8aa3b, v12
	v_exp_f32_e32 v12, v12
	v_add_f32_e32 v14, v14, v182
	v_add_f32_e32 v8, v8, v146
	v_mul_f32_e32 v8, 0xbfb8aa3b, v8
	v_exp_f32_e32 v8, v8
	v_add_f32_e32 v10, v10, v148
	v_mul_f32_e32 v10, 0xbfb8aa3b, v10
	v_add_f32_e32 v12, 1.0, v12
	v_add_f32_e32 v8, 1.0, v8
	v_rcp_f32_e32 v48, v8
	v_add_f32_e32 v8, v13, v181
	v_mul_f32_e32 v8, 0xbfb8aa3b, v8
	v_exp_f32_e32 v8, v8
	v_exp_f32_e32 v10, v10
	v_rcp_f32_e32 v12, v12
	v_mul_f32_e32 v14, 0xbfb8aa3b, v14
	v_add_f32_e32 v8, 1.0, v8
	v_rcp_f32_e32 v13, v8
	v_add_f32_e32 v8, v9, v147
	v_mul_f32_e32 v8, 0xbfb8aa3b, v8
	v_exp_f32_e32 v8, v8
	v_add_f32_e32 v10, 1.0, v10
	v_rcp_f32_e32 v50, v10
	v_add_f32_e32 v10, v15, v183
	v_add_f32_e32 v8, 1.0, v8
	v_rcp_f32_e32 v49, v8
	v_pk_mul_f32 v[8:9], v[12:13], s[28:29] op_sel_hi:[1,0]
	v_mul_f32_e32 v10, 0xbfb8aa3b, v10
	v_pk_mul_f32 v[12:13], v[104:105], v[8:9]
	v_exp_f32_e32 v10, v10
	v_pk_add_f32 v[52:53], v[12:13], v[12:13]
	v_mul_f32_e32 v8, 0x3fb8aa3b, v12
	v_fmamk_f32 v9, v52, 0x3ab60b61, v195
	v_exp_f32_e32 v8, v8
	v_fmaak_f32 v9, v52, v9, 0x3d2aaaab
	v_fmaak_f32 v9, v52, v9, 0x3e2aaaab
	v_exp_f32_e32 v14, v14
	v_fma_f32 v9, v52, v9, 0.5
	v_add_f32_e32 v10, 1.0, v10
	v_fma_f32 v9, v52, v9, 1.0
	v_rcp_f32_e32 v15, v10
	v_add_f32_e32 v10, v11, v149
	v_mul_f32_e64 v9, v9, -v52
	v_fma_f32 v12, -v8, v8, 1.0
	v_cmp_lt_f32_e64 s[6:7], s84, v52
	v_mul_f32_e32 v10, 0xbfb8aa3b, v10
	v_add_f32_e32 v14, 1.0, v14
	v_cndmask_b32_e64 v9, v12, v9, s[6:7]
	v_exp_f32_e32 v10, v10
	v_sqrt_f32_e32 v12, v9
	v_mul_f32_e32 v9, 0x3fb8aa3b, v13
	v_fmamk_f32 v13, v53, 0x3ab60b61, v195
	v_rcp_f32_e32 v14, v14
	v_exp_f32_e32 v9, v9
	v_fmaak_f32 v13, v53, v13, 0x3d2aaaab
	v_fmaak_f32 v13, v53, v13, 0x3e2aaaab
	v_fma_f32 v13, v53, v13, 0.5
	v_add_f32_e32 v10, 1.0, v10
	v_fma_f32 v13, v53, v13, 1.0
	v_rcp_f32_e32 v51, v10
	v_pk_mul_f32 v[10:11], v[14:15], s[28:29] op_sel_hi:[1,0]
	v_cmp_lt_f32_e32 vcc, s84, v53
	v_mul_f32_e64 v13, v13, -v53
	v_fma_f32 v52, -v9, v9, 1.0
	v_pk_mul_f32 v[14:15], v[106:107], v[10:11]
	v_cndmask_b32_e32 v13, v52, v13, vcc
	v_pk_add_f32 v[52:53], v[14:15], v[14:15]
	v_mul_f32_e32 v10, 0x3fb8aa3b, v14
	v_fmamk_f32 v11, v52, 0x3ab60b61, v195
	v_exp_f32_e32 v10, v10
	v_fmaak_f32 v11, v52, v11, 0x3d2aaaab
	v_fmaak_f32 v11, v52, v11, 0x3e2aaaab
	v_fma_f32 v11, v52, v11, 0.5
	v_fma_f32 v11, v52, v11, 1.0
	v_mul_f32_e64 v11, v11, -v52
	v_fma_f32 v14, -v10, v10, 1.0
	v_cmp_lt_f32_e64 s[6:7], s84, v52
	v_cmp_lt_f32_e32 vcc, s84, v53
	v_sqrt_f32_e32 v13, v13
	v_cndmask_b32_e64 v11, v14, v11, s[6:7]
	v_sqrt_f32_e32 v14, v11
	v_mul_f32_e32 v11, 0x3fb8aa3b, v15
	v_fmamk_f32 v15, v53, 0x3ab60b61, v195
	v_exp_f32_e32 v11, v11
	v_fmaak_f32 v15, v53, v15, 0x3d2aaaab
	v_fmaak_f32 v15, v53, v15, 0x3e2aaaab
	v_fma_f32 v15, v53, v15, 0.5
	v_fma_f32 v15, v53, v15, 1.0
	v_mul_f32_e64 v15, v15, -v53
	v_fma_f32 v52, -v11, v11, 1.0
	v_cndmask_b32_e32 v15, v52, v15, vcc
	v_sqrt_f32_e32 v15, v15
	v_pk_mul_f32 v[12:13], v[48:49], v[12:13]
	v_cmp_gt_u32_e32 vcc, 64, v83
	v_pk_mul_f32 v[12:13], v[12:13], v[62:63]
	v_pk_mul_f32 v[14:15], v[50:51], v[14:15]
	s_nop 0
	v_pk_mul_f32 v[14:15], v[14:15], v[60:61]
	ds_write_b128 v66, v[8:11] offset:8384
	ds_write_b128 v66, v[12:15] offset:24768
	v_and_b32_e32 v8, 63, v85
	v_lshlrev_b32_e32 v9, 2, v8
	v_lshl_or_b32 v9, v84, 12, v9
	v_add_u32_e32 v9, s60, v9
	s_waitcnt lgkmcnt(0)
	s_barrier
	ds_read2st64_b32 v[10:11], v9 offset0:32 offset1:33
	ds_read2st64_b32 v[12:13], v9 offset0:96 offset1:97
	ds_read2st64_b32 v[14:15], v9 offset0:34 offset1:35
	ds_read2st64_b32 v[48:49], v9 offset0:98 offset1:99
	s_waitcnt lgkmcnt(2)
	v_fma_f32 v12, 0, v10, v12
	v_fmac_f32_e32 v13, v12, v11
	v_mul_f32_e32 v10, v10, v11
	s_waitcnt lgkmcnt(0)
	v_fma_f32 v11, v13, v14, v48
	ds_read2st64_b32 v[12:13], v9 offset0:36 offset1:37
	ds_read2st64_b32 v[50:51], v9 offset0:100 offset1:101
	v_fmac_f32_e32 v49, v11, v15
	v_mov_b32_e32 v58, v14
	v_mul_f32_e32 v14, v10, v14
	v_mul_f32_e32 v14, v14, v15
	s_waitcnt lgkmcnt(0)
	v_fma_f32 v11, v49, v12, v50
	ds_read2st64_b32 v[48:49], v9 offset0:38 offset1:39
	ds_read2st64_b32 v[52:53], v9 offset0:102 offset1:103
	v_fmac_f32_e32 v51, v11, v13
	s_waitcnt lgkmcnt(1)
	v_mov_b32_e32 v62, v48
	s_waitcnt lgkmcnt(0)
	v_fma_f32 v11, v51, v48, v52
	ds_read2st64_b32 v[50:51], v9 offset0:40 offset1:41
	ds_read2st64_b32 v[54:55], v9 offset0:104 offset1:105
	v_fmac_f32_e32 v53, v11, v49
	s_waitcnt lgkmcnt(1)
	v_mov_b32_e32 v59, v51
	s_waitcnt lgkmcnt(0)
	v_fmac_f32_e32 v54, v53, v50
	ds_read2st64_b32 v[52:53], v9 offset0:42 offset1:43
	ds_read2st64_b32 v[56:57], v9 offset0:106 offset1:107
	v_mov_b32_e32 v11, v54
	v_mov_b32_e32 v54, v15
	v_pk_fma_f32 v[10:11], v[10:11], v[58:59], v[54:55]
	v_mov_b32_e32 v58, v13
	v_mov_b32_e32 v15, v11
	v_mov_b32_e32 v10, v12
	s_waitcnt lgkmcnt(1)
	v_mov_b32_e32 v11, v52
	v_pk_mul_f32 v[54:55], v[14:15], v[10:11]
	v_mov_b32_e32 v12, v13
	s_waitcnt lgkmcnt(0)
	v_mov_b32_e32 v59, v56
	v_pk_mul_f32 v[12:13], v[54:55], v[12:13]
	v_pk_fma_f32 v[10:11], v[14:15], v[10:11], v[58:59]
	ds_read2st64_b32 v[14:15], v9 offset0:44 offset1:45
	ds_read2st64_b32 v[54:55], v9 offset0:108 offset1:109
	ds_read2st64_b32 v[58:59], v9 offset0:46 offset1:47
	ds_read2st64_b32 v[60:61], v9 offset0:110 offset1:111
	v_and_b32_e32 v56, 0x1fffffc0, v83
	v_lshl_add_u32 v9, v8, 3, s60
	v_mov_b32_e32 v10, v12
	v_lshl_add_u32 v64, v56, 3, v9
	v_mov_b32_e32 v63, v53
	v_pk_mul_f32 v[12:13], v[12:13], v[48:49]
	v_mov_b32_e32 v48, v49
	v_mov_b32_e32 v56, v49
	v_pk_mul_f32 v[12:13], v[12:13], v[48:49]
	v_pk_fma_f32 v[10:11], v[10:11], v[62:63], v[56:57]
	v_mov_b32_e32 v56, v51
	v_mov_b32_e32 v13, v11
	v_mov_b32_e32 v10, v50
	s_waitcnt lgkmcnt(3)
	v_mov_b32_e32 v11, v14
	v_pk_mul_f32 v[48:49], v[12:13], v[10:11]
	v_mov_b32_e32 v50, v51
	s_waitcnt lgkmcnt(2)
	v_mov_b32_e32 v57, v54
	v_pk_mul_f32 v[48:49], v[48:49], v[50:51]
	v_pk_fma_f32 v[10:11], v[12:13], v[10:11], v[56:57]
	v_mov_b32_e32 v12, v52
	v_mov_b32_e32 v10, v48
	v_mov_b32_e32 v13, v15
	v_pk_mul_f32 v[48:49], v[48:49], v[52:53]
	v_mov_b32_e32 v50, v53
	v_mov_b32_e32 v54, v53
	v_pk_mul_f32 v[48:49], v[48:49], v[50:51]
	v_pk_fma_f32 v[10:11], v[10:11], v[12:13], v[54:55]
	v_mov_b32_e32 v50, v15
	v_mov_b32_e32 v49, v11
	v_mov_b32_e32 v10, v14
	s_waitcnt lgkmcnt(1)
	v_mov_b32_e32 v11, v58
	v_pk_mul_f32 v[12:13], v[48:49], v[10:11]
	v_mov_b32_e32 v14, v15
	s_waitcnt lgkmcnt(0)
	v_mov_b32_e32 v51, v60
	v_pk_mul_f32 v[12:13], v[12:13], v[14:15]
	v_pk_fma_f32 v[10:11], v[48:49], v[10:11], v[50:51]
	v_mov_b32_e32 v14, v59
	v_mov_b32_e32 v10, v12
	v_pk_mul_f32 v[12:13], v[12:13], v[58:59]
	v_mov_b32_e32 v60, v59
	v_pk_mul_f32 v[12:13], v[12:13], v[14:15]
	v_pk_fma_f32 v[10:11], v[10:11], v[58:59], v[60:61]
	s_nop 0
	v_mov_b32_e32 v13, v11
	ds_write_b64 v64, v[12:13] offset:40960
	s_waitcnt lgkmcnt(0)
	s_barrier
	s_and_saveexec_b64 s[6:7], vcc
	s_xor_b64 s[6:7], exec, s[6:7]
	s_cbranch_execz .LBB0_401
	s_lshl_b32 s27, s26, 7
	ds_read2st64_b64 v[10:13], v9 offset0:80 offset1:81
	ds_read2st64_b64 v[48:51], v9 offset0:82 offset1:83
	s_or_b32 s28, s27, s25
	s_ashr_i32 s29, s28, 31
	s_lshl_b64 s[28:29], s[28:29], 12
	s_mov_b64 s[30:31], s[74:75]
	s_add_u32 s27, s30, s28
	s_waitcnt lgkmcnt(1)
	v_fma_f32 v9, 0, v10, v11
	s_addc_u32 s29, s31, s29
	s_lshl_b32 s28, s23, 3
	v_fmac_f32_e32 v13, v9, v12
	s_add_u32 s28, s27, s28
	v_mul_f32_e32 v10, v10, v12
	s_waitcnt lgkmcnt(0)
	v_fma_f32 v11, v13, v48, v49
	v_mov_b32_e32 v49, v50
	s_addc_u32 s29, s29, 0
	v_lshlrev_b32_e32 v144, 3, v8
	v_pk_mul_f32 v[12:13], v[10:11], v[48:49]
	v_lshl_add_u64 v[8:9], s[28:29], 0, v[144:145]
	v_pk_mul_f32 v[12:13], v[12:13], v[50:51]
	v_pk_fma_f32 v[10:11], v[10:11], v[48:49], v[50:51]
	v_add_co_u32_e32 v8, vcc, 0x115e0000, v8
	v_mov_b32_e32 v13, v11
	s_nop 0
	v_addc_co_u32_e32 v9, vcc, 0, v9, vcc
	flat_store_dwordx2 v[8:9], v[12:13]
.LBB0_401:
	s_or_b64 exec, exec, s[6:7]
	v_mov_b32_e32 v75, v191
	s_waitcnt lgkmcnt(0)
	s_barrier
	v_mov_b32_e32 v74, v191
	v_and_b32_e32 v83, 15, v75
	v_lshrrev_b32_e32 v96, 4, v75
	v_bfe_u32 v97, v75, 4, 2
	s_mov_b64 s[6:7], s[74:75]
	v_bfe_u32 v77, v75, 1, 3
	v_ashrrev_i32_e32 v76, 6, v75
	v_lshlrev_b32_e32 v72, 7, v83
	v_bitop3_b32 v8, v96, v77, 3 bitop3:0x6c
	v_bitop3_b32 v13, v97, v77, 4 bitop3:0x36
	v_lshl_or_b32 v12, v76, 11, v72
	v_lshlrev_b32_e32 v8, 4, v8
	v_lshlrev_b32_e32 v13, 4, v13
	s_add_u32 s6, s6, s24
	v_add3_u32 v8, s60, v8, v12
	v_add3_u32 v12, s60, v13, v12
	s_addc_u32 s7, s7, 0
	v_lshlrev_b32_e32 v144, 4, v97
	ds_read_b128 v[8:11], v8
	ds_read_b128 v[84:87], v12
	v_lshl_add_u64 v[12:13], s[6:7], 0, v[144:145]
	s_mov_b64 s[6:7], 0x3980000
	v_lshl_add_u64 v[92:93], v[12:13], 0, s[6:7]
	s_mov_b64 s[6:7], 0x39a0000
	v_mov_b32_e32 v73, v145
	v_lshl_add_u64 v[94:95], v[12:13], 0, s[6:7]
	v_mul_u32_u24_e32 v184, 0xf0, v97
	v_lshl_add_u32 v184, v83, 4, v184
	v_mov_b32_e32 v185, v145
	v_lshl_add_u64 v[60:61], v[92:93], 0, v[184:185]
	v_lshl_add_u64 v[62:63], v[94:95], 0, v[184:185]
	s_mov_b64 s[98:99], 0x1000
	v_lshl_add_u64 v[180:181], v[60:61], 0, s[98:99]
	v_lshl_add_u64 v[182:183], v[62:63], 0, s[98:99]
	global_load_dwordx4 v[104:107], v[180:181], off offset:-4096
	global_load_dwordx4 v[108:111], v[182:183], off offset:-4096
	global_load_dwordx4 v[112:115], v[180:181], off offset:-3072
	global_load_dwordx4 v[116:119], v[182:183], off offset:-3072
	global_load_dwordx4 v[120:123], v[180:181], off offset:-2048
	global_load_dwordx4 v[124:127], v[182:183], off offset:-2048
	global_load_dwordx4 v[128:131], v[180:181], off offset:-1024
	global_load_dwordx4 v[132:135], v[182:183], off offset:-1024
	global_load_dwordx4 v[136:139], v[180:181], off
	global_load_dwordx4 v[140:143], v[182:183], off
	global_load_dwordx4 v[156:159], v[180:181], off offset:1024
	global_load_dwordx4 v[160:163], v[182:183], off offset:1024
	global_load_dwordx4 v[164:167], v[180:181], off offset:2048
	global_load_dwordx4 v[168:171], v[182:183], off offset:2048
	global_load_dwordx4 v[172:175], v[180:181], off offset:3072
	global_load_dwordx4 v[176:179], v[182:183], off offset:3072
	v_readlane_b32 s36, v254, 22
	v_readlane_b32 s40, v254, 26
	v_readlane_b32 s41, v254, 27
	s_mov_b64 s[6:7], s[40:41]
	v_readlane_b32 s44, v254, 30
	v_readlane_b32 s45, v254, 31
	s_mov_b32 s27, 0x122e6000
	s_mov_b32 s28, 0xc1000000
	v_lshrrev_b32_e32 v98, 1, v75
	v_readlane_b32 s37, v254, 23
	v_readlane_b32 s38, v254, 24
	v_readlane_b32 s39, v254, 25
	v_readlane_b32 s42, v254, 28
	v_readlane_b32 s43, v254, 29
	v_readlane_b32 s46, v254, 32
	v_readlane_b32 s47, v254, 33
	v_readlane_b32 s48, v254, 34
	v_readlane_b32 s49, v254, 35
	v_readlane_b32 s50, v254, 36
	v_readlane_b32 s51, v254, 37
	v_lshlrev_b32_e32 v154, 2, v97
	v_or_b32_e32 v154, s8, v154
	v_ashrrev_i32_e32 v155, 31, v154
	v_lshlrev_b64 v[154:155], 2, v[154:155]
	s_add_u32 s98, s74, s3
	s_addc_u32 s99, s75, 0
	s_add_u32 s98, s98, 0x122e6000
	s_addc_u32 s99, s99, 0
	v_lshl_add_u64 v[184:185], s[98:99], 0, v[144:145]
	v_lshl_add_u64 v[180:181], s[40:41], 0, v[154:155]
	v_lshl_add_u64 v[146:147], s[44:45], 0, v[154:155]
	global_load_dwordx4 v[216:219], v[180:181], off offset:2048
	global_load_dwordx4 v[220:223], v[146:147], off offset:2048
	global_load_dwordx4 v[224:227], v[184:185], off offset:2048
	global_load_dwordx4 v[228:231], v[180:181], off offset:2112
	global_load_dwordx4 v[232:235], v[146:147], off offset:2112
	global_load_dwordx4 v[236:239], v[184:185], off offset:2112
	global_load_dwordx4 v[240:243], v[180:181], off offset:2176
	global_load_dwordx4 v[244:247], v[146:147], off offset:2176
	global_load_dwordx4 v[248:251], v[184:185], off offset:2176
	global_load_dwordx4 v[180:183], v[180:181], off offset:2240
	global_load_dwordx4 v[146:149], v[146:147], off offset:2240
	s_waitcnt vmcnt(0) lgkmcnt(0)
	v_mfma_f32_16x16x32_bf16 v[12:15], v[104:107], v[8:11], 0
	v_mfma_f32_16x16x32_bf16 v[48:51], v[108:111], v[8:11], 0
	v_mfma_f32_16x16x32_bf16 v[68:71], v[112:115], v[84:87], v[12:15]
	v_mfma_f32_16x16x32_bf16 v[64:67], v[116:119], v[84:87], v[48:51]
	s_nop 4
	v_mfma_f32_16x16x32_bf16 v[12:15], v[120:123], v[8:11], 0
	v_mfma_f32_16x16x32_bf16 v[48:51], v[124:127], v[8:11], 0
	v_mfma_f32_16x16x32_bf16 v[60:63], v[128:131], v[84:87], v[12:15]
	s_nop 5
	v_or_b32_e32 v12, 0x1000, v72
	v_mov_b32_e32 v13, v145
	v_lshl_add_u64 v[52:53], v[92:93], 0, v[12:13]
	v_mfma_f32_16x16x32_bf16 v[56:59], v[132:135], v[84:87], v[48:51]
	v_lshl_add_u64 v[88:89], v[94:95], 0, v[12:13]
	s_nop 0
	s_nop 0
	s_nop 0
	v_mfma_f32_16x16x32_bf16 v[12:15], v[136:139], v[8:11], 0
	v_mfma_f32_16x16x32_bf16 v[48:51], v[140:143], v[8:11], 0
	v_mfma_f32_16x16x32_bf16 v[52:55], v[156:159], v[84:87], v[12:15]
	s_nop 5
	v_or_b32_e32 v12, 0x1800, v72
	v_mov_b32_e32 v13, v145
	v_lshl_add_u64 v[72:73], v[92:93], 0, v[12:13]
	v_mfma_f32_16x16x32_bf16 v[48:51], v[160:163], v[84:87], v[48:51]
	v_lshl_add_u64 v[92:93], v[94:95], 0, v[12:13]
	v_mfma_f32_16x16x32_bf16 v[12:15], v[164:167], v[8:11], 0
	v_mfma_f32_16x16x32_bf16 v[8:11], v[168:171], v[8:11], 0
	s_nop 0
	v_lshl_or_b32 v73, v76, 4, v83
	v_lshlrev_b32_e32 v72, 2, v97
	v_lshlrev_b32_e32 v83, 7, v73
	v_lshlrev_b32_e32 v102, 8, v73
	v_mov_b32_e32 v73, v145
	v_mfma_f32_16x16x32_bf16 v[12:15], v[172:175], v[84:87], v[12:15]
	v_mfma_f32_16x16x32_bf16 v[8:11], v[176:179], v[84:87], v[8:11]
	global_load_dwordx4 v[104:107], v[184:185], off offset:2240
	v_lshl_add_u64 v[86:87], v[72:73], 0, s[8:9]
	v_lshlrev_b64 v[90:91], 2, v[86:87]
	v_lshl_add_u64 v[86:87], s[6:7], 0, v[90:91]
	s_mov_b64 s[6:7], s[44:45]
	v_bfe_u32 v84, v96, 1, 1
	v_lshl_add_u64 v[90:91], s[6:7], 0, v[90:91]
	s_mov_b64 s[6:7], s[74:75]
	s_add_u32 s6, s6, s3
	s_addc_u32 s7, s7, 0
	v_lshl_add_u64 v[94:95], s[6:7], 0, v[144:145]
	v_add_co_u32_e32 v94, vcc, s27, v94
	v_and_b32_e32 v85, 8, v98
	s_nop 0
	v_addc_co_u32_e32 v95, vcc, 0, v95, vcc
	v_bitop3_b32 v98, v84, v98, 7 bitop3:0x78
	v_add_u32_e32 v85, s60, v85
	v_lshlrev_b32_e32 v98, 4, v98
	v_add3_u32 v98, v85, v98, v83
	ds_read_b64 v[98:99], v98
	s_waitcnt lgkmcnt(0)
	v_lshlrev_b32_e32 v100, 16, v98
	v_and_b32_e32 v101, 0xffff0000, v98
	v_lshlrev_b32_e32 v98, 16, v99
	v_and_b32_e32 v99, 0xffff0000, v99
	v_add_f32_e32 v68, v68, v216
	v_add_f32_e32 v69, v69, v217
	v_mul_f32_e32 v68, 0xbfb8aa3b, v68
	v_mul_f32_e32 v69, 0xbfb8aa3b, v69
	v_exp_f32_e32 v68, v68
	v_exp_f32_e32 v69, v69
	v_add_f32_e32 v64, v64, v220
	v_add_f32_e32 v65, v65, v221
	v_add_f32_e32 v68, 1.0, v68
	v_add_f32_e32 v69, 1.0, v69
	v_rcp_f32_e32 v68, v68
	v_rcp_f32_e32 v69, v69
	v_add_f32_e32 v70, v70, v218
	v_add_f32_e32 v71, v71, v219
	v_mul_f32_e32 v70, 0xbfb8aa3b, v70
	v_pk_mul_f32 v[68:69], v[68:69], s[28:29] op_sel_hi:[1,0]
	v_mul_f32_e32 v71, 0xbfb8aa3b, v71
	v_pk_mul_f32 v[86:87], v[224:225], v[68:69]
	v_exp_f32_e32 v70, v70
	v_pk_add_f32 v[90:91], v[86:87], v[86:87]
	v_mul_f32_e32 v68, 0x3fb8aa3b, v86
	v_fmamk_f32 v69, v90, 0x3ab60b61, v195
	v_exp_f32_e32 v68, v68
	v_fmaak_f32 v69, v90, v69, 0x3d2aaaab
	v_fmaak_f32 v69, v90, v69, 0x3e2aaaab
	v_exp_f32_e32 v71, v71
	v_fma_f32 v69, v90, v69, 0.5
	v_fma_f32 v69, v90, v69, 1.0
	v_mul_f32_e64 v69, v69, -v90
	v_fma_f32 v86, -v68, v68, 1.0
	v_cmp_lt_f32_e64 s[6:7], s84, v90
	v_add_f32_e32 v70, 1.0, v70
	v_add_f32_e32 v71, 1.0, v71
	v_cndmask_b32_e64 v69, v86, v69, s[6:7]
	v_sqrt_f32_e32 v86, v69
	v_mul_f32_e32 v69, 0x3fb8aa3b, v87
	v_fmamk_f32 v87, v91, 0x3ab60b61, v195
	v_rcp_f32_e32 v70, v70
	v_rcp_f32_e32 v71, v71
	v_exp_f32_e32 v69, v69
	v_fmaak_f32 v87, v91, v87, 0x3d2aaaab
	v_fmaak_f32 v87, v91, v87, 0x3e2aaaab
	v_fma_f32 v87, v91, v87, 0.5
	v_fma_f32 v87, v91, v87, 1.0
	v_pk_mul_f32 v[70:71], v[70:71], s[28:29] op_sel_hi:[1,0]
	v_cmp_lt_f32_e32 vcc, s84, v91
	v_mul_f32_e64 v87, v87, -v91
	v_fma_f32 v90, -v69, v69, 1.0
	v_pk_mul_f32 v[88:89], v[226:227], v[70:71]
	v_cndmask_b32_e32 v87, v90, v87, vcc
	v_pk_add_f32 v[90:91], v[88:89], v[88:89]
	v_mul_f32_e32 v70, 0x3fb8aa3b, v88
	v_fmamk_f32 v71, v90, 0x3ab60b61, v195
	v_exp_f32_e32 v70, v70
	v_fmaak_f32 v71, v90, v71, 0x3d2aaaab
	v_fmaak_f32 v71, v90, v71, 0x3e2aaaab
	v_fma_f32 v71, v90, v71, 0.5
	v_fma_f32 v71, v90, v71, 1.0
	v_mul_f32_e64 v71, v71, -v90
	v_fma_f32 v88, -v70, v70, 1.0
	v_cmp_lt_f32_e64 s[6:7], s84, v90
	v_add_f32_e32 v66, v66, v222
	v_add_f32_e32 v67, v67, v223
	v_cndmask_b32_e64 v71, v88, v71, s[6:7]
	v_sqrt_f32_e32 v88, v71
	v_mul_f32_e32 v71, 0x3fb8aa3b, v89
	v_fmamk_f32 v89, v91, 0x3ab60b61, v195
	v_mul_f32_e32 v64, 0xbfb8aa3b, v64
	v_mul_f32_e32 v65, 0xbfb8aa3b, v65
	v_mul_f32_e32 v66, 0xbfb8aa3b, v66
	v_mul_f32_e32 v67, 0xbfb8aa3b, v67
	v_exp_f32_e32 v71, v71
	v_fmaak_f32 v89, v91, v89, 0x3d2aaaab
	v_exp_f32_e32 v64, v64
	v_exp_f32_e32 v65, v65
	v_exp_f32_e32 v66, v66
	v_exp_f32_e32 v67, v67
	v_fmaak_f32 v89, v91, v89, 0x3e2aaaab
	v_fma_f32 v89, v91, v89, 0.5
	v_fma_f32 v89, v91, v89, 1.0
	v_cmp_lt_f32_e32 vcc, s84, v91
	v_mul_f32_e64 v89, v89, -v91
	v_fma_f32 v90, -v71, v71, 1.0
	v_add_f32_e32 v64, 1.0, v64
	v_add_f32_e32 v65, 1.0, v65
	v_add_f32_e32 v66, 1.0, v66
	v_add_f32_e32 v67, 1.0, v67
	v_cndmask_b32_e32 v89, v90, v89, vcc
	v_rcp_f32_e32 v64, v64
	v_rcp_f32_e32 v65, v65
	v_sqrt_f32_e32 v87, v87
	v_rcp_f32_e32 v66, v66
	v_rcp_f32_e32 v67, v67
	v_sqrt_f32_e32 v89, v89
	v_pk_mul_f32 v[64:65], v[64:65], v[86:87]
	s_mov_b64 s[6:7], s[40:41]
	v_pk_mul_f32 v[86:87], v[64:65], v[100:101]
	v_pk_mul_f32 v[66:67], v[66:67], v[88:89]
	v_lshl_add_u64 v[64:65], v[72:73], 0, s[12:13]
	v_pk_mul_f32 v[88:89], v[66:67], v[98:99]
	v_add3_u32 v66, s60, v102, v144
	ds_write_b128 v66, v[68:71] offset:8192
	ds_write_b128 v66, v[86:89] offset:24576
	v_lshlrev_b64 v[64:65], 2, v[64:65]
	v_lshl_add_u64 v[68:69], s[6:7], 0, v[64:65]
	s_mov_b64 s[6:7], s[44:45]
	v_bitop3_b32 v67, v84, v77, 2 bitop3:0x36
	v_lshl_add_u64 v[72:73], s[6:7], 0, v[64:65]
	s_mov_b64 s[6:7], s[74:75]
	s_add_u32 s6, s6, s3
	s_addc_u32 s7, s7, 0
	v_lshl_add_u64 v[72:73], s[6:7], 0, v[144:145]
	v_add_co_u32_e32 v72, vcc, s27, v72
	v_lshlrev_b32_e32 v67, 4, v67
	s_nop 0
	v_addc_co_u32_e32 v73, vcc, 0, v73, vcc
	v_add3_u32 v67, v85, v67, v83
	ds_read_b64 v[72:73], v67
	s_waitcnt lgkmcnt(0)
	v_lshlrev_b32_e32 v94, 16, v72
	v_and_b32_e32 v95, 0xffff0000, v72
	v_lshlrev_b32_e32 v72, 16, v73
	v_and_b32_e32 v73, 0xffff0000, v73
	v_add_f32_e32 v60, v60, v228
	v_mul_f32_e32 v60, 0xbfb8aa3b, v60
	v_exp_f32_e32 v60, v60
	v_add_f32_e32 v62, v62, v230
	v_add_f32_e32 v56, v56, v232
	v_mul_f32_e32 v56, 0xbfb8aa3b, v56
	v_exp_f32_e32 v56, v56
	v_add_f32_e32 v58, v58, v234
	v_mul_f32_e32 v58, 0xbfb8aa3b, v58
	v_exp_f32_e32 v58, v58
	v_add_f32_e32 v56, 1.0, v56
	v_rcp_f32_e32 v68, v56
	v_add_f32_e32 v56, v61, v229
	v_mul_f32_e32 v56, 0xbfb8aa3b, v56
	v_exp_f32_e32 v56, v56
	v_add_f32_e32 v60, 1.0, v60
	v_rcp_f32_e32 v60, v60
	v_add_f32_e32 v58, 1.0, v58
	v_add_f32_e32 v56, 1.0, v56
	v_rcp_f32_e32 v61, v56
	v_add_f32_e32 v56, v57, v233
	v_mul_f32_e32 v56, 0xbfb8aa3b, v56
	v_exp_f32_e32 v56, v56
	v_rcp_f32_e32 v70, v58
	v_add_f32_e32 v58, v63, v231
	v_mul_f32_e32 v58, 0xbfb8aa3b, v58
	v_add_f32_e32 v56, 1.0, v56
	v_rcp_f32_e32 v69, v56
	v_pk_mul_f32 v[56:57], v[60:61], s[28:29] op_sel_hi:[1,0]
	v_exp_f32_e32 v58, v58
	v_pk_mul_f32 v[60:61], v[236:237], v[56:57]
	v_mul_f32_e32 v62, 0xbfb8aa3b, v62
	v_pk_add_f32 v[86:87], v[60:61], v[60:61]
	v_mul_f32_e32 v56, 0x3fb8aa3b, v60
	v_fmamk_f32 v57, v86, 0x3ab60b61, v195
	v_exp_f32_e32 v56, v56
	v_fmaak_f32 v57, v86, v57, 0x3d2aaaab
	v_exp_f32_e32 v62, v62
	v_fmaak_f32 v57, v86, v57, 0x3e2aaaab
	v_add_f32_e32 v58, 1.0, v58
	v_fma_f32 v57, v86, v57, 0.5
	v_rcp_f32_e32 v63, v58
	v_add_f32_e32 v58, v59, v235
	v_fma_f32 v57, v86, v57, 1.0
	v_mul_f32_e32 v58, 0xbfb8aa3b, v58
	v_mul_f32_e64 v57, v57, -v86
	v_fma_f32 v60, -v56, v56, 1.0
	v_cmp_lt_f32_e64 s[6:7], s84, v86
	v_add_f32_e32 v62, 1.0, v62
	v_exp_f32_e32 v58, v58
	v_cndmask_b32_e64 v57, v60, v57, s[6:7]
	v_rcp_f32_e32 v62, v62
	v_sqrt_f32_e32 v60, v57
	v_mul_f32_e32 v57, 0x3fb8aa3b, v61
	v_fmamk_f32 v61, v87, 0x3ab60b61, v195
	v_fmaak_f32 v61, v87, v61, 0x3d2aaaab
	v_fmaak_f32 v61, v87, v61, 0x3e2aaaab
	v_add_f32_e32 v58, 1.0, v58
	v_fma_f32 v61, v87, v61, 0.5
	v_rcp_f32_e32 v71, v58
	v_pk_mul_f32 v[58:59], v[62:63], s[28:29] op_sel_hi:[1,0]
	v_fma_f32 v61, v87, v61, 1.0
	v_pk_mul_f32 v[62:63], v[238:239], v[58:59]
	v_cmp_lt_f32_e32 vcc, s84, v87
	v_mul_f32_e64 v61, v61, -v87
	v_pk_add_f32 v[86:87], v[62:63], v[62:63]
	v_mul_f32_e32 v58, 0x3fb8aa3b, v62
	v_fmamk_f32 v59, v86, 0x3ab60b61, v195
	v_exp_f32_e32 v58, v58
	v_fmaak_f32 v59, v86, v59, 0x3d2aaaab
	v_fmaak_f32 v59, v86, v59, 0x3e2aaaab
	v_fma_f32 v59, v86, v59, 0.5
	v_fma_f32 v59, v86, v59, 1.0
	v_mul_f32_e64 v59, v59, -v86
	v_fma_f32 v62, -v58, v58, 1.0
	v_cmp_lt_f32_e64 s[6:7], s84, v86
	v_exp_f32_e32 v57, v57
	s_nop 0
	v_cndmask_b32_e64 v59, v62, v59, s[6:7]
	v_sqrt_f32_e32 v62, v59
	v_mul_f32_e32 v59, 0x3fb8aa3b, v63
	v_fmamk_f32 v63, v87, 0x3ab60b61, v195
	v_exp_f32_e32 v59, v59
	v_fmaak_f32 v63, v87, v63, 0x3d2aaaab
	v_fmaak_f32 v63, v87, v63, 0x3e2aaaab
	v_fma_f32 v63, v87, v63, 0.5
	v_fma_f32 v67, -v57, v57, 1.0
	v_fma_f32 v63, v87, v63, 1.0
	v_cndmask_b32_e32 v61, v67, v61, vcc
	v_cmp_lt_f32_e32 vcc, s84, v87
	v_mul_f32_e64 v63, v63, -v87
	v_fma_f32 v67, -v59, v59, 1.0
	v_cndmask_b32_e32 v63, v67, v63, vcc
	v_sqrt_f32_e32 v61, v61
	v_sqrt_f32_e32 v63, v63
	s_mov_b64 s[6:7], s[40:41]
	v_bitop3_b32 v67, v84, v77, 4 bitop3:0x36
	v_pk_mul_f32 v[60:61], v[68:69], v[60:61]
	v_pk_mul_f32 v[62:63], v[70:71], v[62:63]
	v_pk_mul_f32 v[60:61], v[60:61], v[94:95]
	v_pk_mul_f32 v[62:63], v[62:63], v[72:73]
	ds_write_b128 v66, v[56:59] offset:8256
	ds_write_b128 v66, v[60:63] offset:24640
	v_lshlrev_b32_e32 v67, 4, v67
	v_lshl_add_u64 v[56:57], s[6:7], 0, v[64:65]
	s_mov_b64 s[6:7], s[44:45]
	v_add3_u32 v67, v85, v67, v83
	v_lshl_add_u64 v[60:61], s[6:7], 0, v[64:65]
	s_mov_b64 s[6:7], s[74:75]
	s_add_u32 s6, s6, s3
	s_addc_u32 s7, s7, 0
	v_lshl_add_u64 v[68:69], s[6:7], 0, v[144:145]
	v_add_co_u32_e32 v68, vcc, s27, v68
	ds_read_b64 v[72:73], v67
	s_nop 0
	v_addc_co_u32_e32 v69, vcc, 0, v69, vcc
	s_waitcnt lgkmcnt(0)
	v_lshlrev_b32_e32 v86, 16, v72
	v_and_b32_e32 v87, 0xffff0000, v72
	v_lshlrev_b32_e32 v72, 16, v73
	v_and_b32_e32 v73, 0xffff0000, v73
	v_add_f32_e32 v52, v52, v240
	v_mul_f32_e32 v52, 0xbfb8aa3b, v52
	v_exp_f32_e32 v52, v52
	v_add_f32_e32 v54, v54, v242
	v_add_f32_e32 v48, v48, v244
	v_mul_f32_e32 v48, 0xbfb8aa3b, v48
	v_exp_f32_e32 v48, v48
	v_add_f32_e32 v50, v50, v246
	v_mul_f32_e32 v50, 0xbfb8aa3b, v50
	v_add_f32_e32 v52, 1.0, v52
	v_add_f32_e32 v48, 1.0, v48
	v_rcp_f32_e32 v56, v48
	v_add_f32_e32 v48, v53, v241
	v_mul_f32_e32 v48, 0xbfb8aa3b, v48
	v_exp_f32_e32 v48, v48
	v_exp_f32_e32 v50, v50
	v_rcp_f32_e32 v52, v52
	v_mul_f32_e32 v54, 0xbfb8aa3b, v54
	v_add_f32_e32 v48, 1.0, v48
	v_rcp_f32_e32 v53, v48
	v_add_f32_e32 v48, v49, v245
	v_mul_f32_e32 v48, 0xbfb8aa3b, v48
	v_exp_f32_e32 v48, v48
	v_add_f32_e32 v50, 1.0, v50
	v_rcp_f32_e32 v58, v50
	v_add_f32_e32 v50, v55, v243
	v_add_f32_e32 v48, 1.0, v48
	v_rcp_f32_e32 v57, v48
	v_pk_mul_f32 v[48:49], v[52:53], s[28:29] op_sel_hi:[1,0]
	v_mul_f32_e32 v50, 0xbfb8aa3b, v50
	v_pk_mul_f32 v[52:53], v[248:249], v[48:49]
	v_exp_f32_e32 v50, v50
	v_pk_add_f32 v[60:61], v[52:53], v[52:53]
	v_mul_f32_e32 v48, 0x3fb8aa3b, v52
	v_fmamk_f32 v49, v60, 0x3ab60b61, v195
	v_exp_f32_e32 v48, v48
	v_fmaak_f32 v49, v60, v49, 0x3d2aaaab
	v_fmaak_f32 v49, v60, v49, 0x3e2aaaab
	v_exp_f32_e32 v54, v54
	v_fma_f32 v49, v60, v49, 0.5
	v_add_f32_e32 v50, 1.0, v50
	v_fma_f32 v49, v60, v49, 1.0
	v_rcp_f32_e32 v55, v50
	v_add_f32_e32 v50, v51, v247
	v_mul_f32_e64 v49, v49, -v60
	v_fma_f32 v52, -v48, v48, 1.0
	v_cmp_lt_f32_e64 s[6:7], s84, v60
	v_mul_f32_e32 v50, 0xbfb8aa3b, v50
	v_add_f32_e32 v54, 1.0, v54
	v_cndmask_b32_e64 v49, v52, v49, s[6:7]
	v_exp_f32_e32 v50, v50
	v_sqrt_f32_e32 v52, v49
	v_mul_f32_e32 v49, 0x3fb8aa3b, v53
	v_fmamk_f32 v53, v61, 0x3ab60b61, v195
	v_rcp_f32_e32 v54, v54
	v_exp_f32_e32 v49, v49
	v_fmaak_f32 v53, v61, v53, 0x3d2aaaab
	v_fmaak_f32 v53, v61, v53, 0x3e2aaaab
	v_fma_f32 v53, v61, v53, 0.5
	v_add_f32_e32 v50, 1.0, v50
	v_fma_f32 v53, v61, v53, 1.0
	v_rcp_f32_e32 v59, v50
	v_pk_mul_f32 v[50:51], v[54:55], s[28:29] op_sel_hi:[1,0]
	v_cmp_lt_f32_e32 vcc, s84, v61
	v_mul_f32_e64 v53, v53, -v61
	v_fma_f32 v60, -v49, v49, 1.0
	v_pk_mul_f32 v[54:55], v[250:251], v[50:51]
	v_cndmask_b32_e32 v53, v60, v53, vcc
	v_pk_add_f32 v[60:61], v[54:55], v[54:55]
	v_mul_f32_e32 v50, 0x3fb8aa3b, v54
	v_fmamk_f32 v51, v60, 0x3ab60b61, v195
	v_exp_f32_e32 v50, v50
	v_fmaak_f32 v51, v60, v51, 0x3d2aaaab
	v_fmaak_f32 v51, v60, v51, 0x3e2aaaab
	v_fma_f32 v51, v60, v51, 0.5
	v_fma_f32 v51, v60, v51, 1.0
	v_mul_f32_e64 v51, v51, -v60
	v_fma_f32 v54, -v50, v50, 1.0
	v_cmp_lt_f32_e64 s[6:7], s84, v60
	v_cmp_lt_f32_e32 vcc, s84, v61
	v_sqrt_f32_e32 v53, v53
	v_cndmask_b32_e64 v51, v54, v51, s[6:7]
	v_sqrt_f32_e32 v54, v51
	v_mul_f32_e32 v51, 0x3fb8aa3b, v55
	v_fmamk_f32 v55, v61, 0x3ab60b61, v195
	v_exp_f32_e32 v51, v51
	v_fmaak_f32 v55, v61, v55, 0x3d2aaaab
	v_fmaak_f32 v55, v61, v55, 0x3e2aaaab
	v_fma_f32 v55, v61, v55, 0.5
	v_fma_f32 v55, v61, v55, 1.0
	v_mul_f32_e64 v55, v55, -v61
	v_fma_f32 v60, -v51, v51, 1.0
	v_cndmask_b32_e32 v55, v60, v55, vcc
	v_sqrt_f32_e32 v55, v55
	v_pk_mul_f32 v[52:53], v[56:57], v[52:53]
	s_mov_b64 s[6:7], s[40:41]
	v_pk_mul_f32 v[52:53], v[52:53], v[86:87]
	v_pk_mul_f32 v[54:55], v[58:59], v[54:55]
	v_bitop3_b32 v60, v84, v77, 6 bitop3:0x36
	v_pk_mul_f32 v[54:55], v[54:55], v[72:73]
	ds_write_b128 v66, v[48:51] offset:8320
	ds_write_b128 v66, v[52:55] offset:24704
	v_lshlrev_b32_e32 v60, 4, v60
	v_lshl_add_u64 v[48:49], s[6:7], 0, v[64:65]
	s_mov_b64 s[6:7], s[44:45]
	v_add3_u32 v60, v85, v60, v83
	v_lshl_add_u64 v[52:53], s[6:7], 0, v[64:65]
	s_mov_b64 s[6:7], s[74:75]
	s_add_u32 s6, s6, s3
	s_addc_u32 s7, s7, 0
	v_lshl_add_u64 v[56:57], s[6:7], 0, v[144:145]
	v_add_co_u32_e32 v56, vcc, s27, v56
	ds_read_b64 v[60:61], v60
	s_nop 0
	v_addc_co_u32_e32 v57, vcc, 0, v57, vcc
	s_waitcnt lgkmcnt(0)
	v_lshlrev_b32_e32 v62, 16, v60
	v_and_b32_e32 v63, 0xffff0000, v60
	v_lshlrev_b32_e32 v60, 16, v61
	v_and_b32_e32 v61, 0xffff0000, v61
	s_waitcnt vmcnt(0)
	v_add_f32_e32 v12, v12, v180
	v_mul_f32_e32 v12, 0xbfb8aa3b, v12
	v_exp_f32_e32 v12, v12
	v_add_f32_e32 v14, v14, v182
	v_add_f32_e32 v8, v8, v146
	v_mul_f32_e32 v8, 0xbfb8aa3b, v8
	v_exp_f32_e32 v8, v8
	v_add_f32_e32 v10, v10, v148
	v_mul_f32_e32 v10, 0xbfb8aa3b, v10
	v_add_f32_e32 v12, 1.0, v12
	v_add_f32_e32 v8, 1.0, v8
	v_rcp_f32_e32 v48, v8
	v_add_f32_e32 v8, v13, v181
	v_mul_f32_e32 v8, 0xbfb8aa3b, v8
	v_exp_f32_e32 v8, v8
	v_exp_f32_e32 v10, v10
	v_rcp_f32_e32 v12, v12
	v_mul_f32_e32 v14, 0xbfb8aa3b, v14
	v_add_f32_e32 v8, 1.0, v8
	v_rcp_f32_e32 v13, v8
	v_add_f32_e32 v8, v9, v147
	v_mul_f32_e32 v8, 0xbfb8aa3b, v8
	v_exp_f32_e32 v8, v8
	v_add_f32_e32 v10, 1.0, v10
	v_rcp_f32_e32 v50, v10
	v_add_f32_e32 v10, v15, v183
	v_add_f32_e32 v8, 1.0, v8
	v_rcp_f32_e32 v49, v8
	v_pk_mul_f32 v[8:9], v[12:13], s[28:29] op_sel_hi:[1,0]
	v_mul_f32_e32 v10, 0xbfb8aa3b, v10
	v_pk_mul_f32 v[12:13], v[104:105], v[8:9]
	v_exp_f32_e32 v10, v10
	v_pk_add_f32 v[52:53], v[12:13], v[12:13]
	v_mul_f32_e32 v8, 0x3fb8aa3b, v12
	v_fmamk_f32 v9, v52, 0x3ab60b61, v195
	v_exp_f32_e32 v8, v8
	v_fmaak_f32 v9, v52, v9, 0x3d2aaaab
	v_fmaak_f32 v9, v52, v9, 0x3e2aaaab
	v_exp_f32_e32 v14, v14
	v_fma_f32 v9, v52, v9, 0.5
	v_add_f32_e32 v10, 1.0, v10
	v_fma_f32 v9, v52, v9, 1.0
	v_rcp_f32_e32 v15, v10
	v_add_f32_e32 v10, v11, v149
	v_mul_f32_e64 v9, v9, -v52
	v_fma_f32 v12, -v8, v8, 1.0
	v_cmp_lt_f32_e64 s[6:7], s84, v52
	v_mul_f32_e32 v10, 0xbfb8aa3b, v10
	v_add_f32_e32 v14, 1.0, v14
	v_cndmask_b32_e64 v9, v12, v9, s[6:7]
	v_exp_f32_e32 v10, v10
	v_sqrt_f32_e32 v12, v9
	v_mul_f32_e32 v9, 0x3fb8aa3b, v13
	v_fmamk_f32 v13, v53, 0x3ab60b61, v195
	v_rcp_f32_e32 v14, v14
	v_exp_f32_e32 v9, v9
	v_fmaak_f32 v13, v53, v13, 0x3d2aaaab
	v_fmaak_f32 v13, v53, v13, 0x3e2aaaab
	v_fma_f32 v13, v53, v13, 0.5
	v_add_f32_e32 v10, 1.0, v10
	v_fma_f32 v13, v53, v13, 1.0
	v_rcp_f32_e32 v51, v10
	v_pk_mul_f32 v[10:11], v[14:15], s[28:29] op_sel_hi:[1,0]
	v_cmp_lt_f32_e32 vcc, s84, v53
	v_mul_f32_e64 v13, v13, -v53
	v_fma_f32 v52, -v9, v9, 1.0
	v_pk_mul_f32 v[14:15], v[106:107], v[10:11]
	v_cndmask_b32_e32 v13, v52, v13, vcc
	v_pk_add_f32 v[52:53], v[14:15], v[14:15]
	v_mul_f32_e32 v10, 0x3fb8aa3b, v14
	v_fmamk_f32 v11, v52, 0x3ab60b61, v195
	v_exp_f32_e32 v10, v10
	v_fmaak_f32 v11, v52, v11, 0x3d2aaaab
	v_fmaak_f32 v11, v52, v11, 0x3e2aaaab
	v_fma_f32 v11, v52, v11, 0.5
	v_fma_f32 v11, v52, v11, 1.0
	v_mul_f32_e64 v11, v11, -v52
	v_fma_f32 v14, -v10, v10, 1.0
	v_cmp_lt_f32_e64 s[6:7], s84, v52
	v_cmp_lt_f32_e32 vcc, s84, v53
	v_sqrt_f32_e32 v13, v13
	v_cndmask_b32_e64 v11, v14, v11, s[6:7]
	v_sqrt_f32_e32 v14, v11
	v_mul_f32_e32 v11, 0x3fb8aa3b, v15
	v_fmamk_f32 v15, v53, 0x3ab60b61, v195
	v_exp_f32_e32 v11, v11
	v_fmaak_f32 v15, v53, v15, 0x3d2aaaab
	v_fmaak_f32 v15, v53, v15, 0x3e2aaaab
	v_fma_f32 v15, v53, v15, 0.5
	v_fma_f32 v15, v53, v15, 1.0
	v_mul_f32_e64 v15, v15, -v53
	v_fma_f32 v52, -v11, v11, 1.0
	v_cndmask_b32_e32 v15, v52, v15, vcc
	v_sqrt_f32_e32 v15, v15
	v_pk_mul_f32 v[12:13], v[48:49], v[12:13]
	v_cmp_gt_u32_e32 vcc, 64, v75
	v_pk_mul_f32 v[12:13], v[12:13], v[62:63]
	v_pk_mul_f32 v[14:15], v[50:51], v[14:15]
	s_nop 0
	v_pk_mul_f32 v[14:15], v[14:15], v[60:61]
	ds_write_b128 v66, v[8:11] offset:8384
	ds_write_b128 v66, v[12:15] offset:24768
	v_and_b32_e32 v8, 63, v74
	v_lshlrev_b32_e32 v9, 2, v8
	v_lshl_or_b32 v9, v76, 12, v9
	v_add_u32_e32 v9, s60, v9
	s_waitcnt lgkmcnt(0)
	s_barrier
	ds_read2st64_b32 v[10:11], v9 offset0:46 offset1:47
	ds_read2st64_b32 v[12:13], v9 offset0:110 offset1:111
	ds_read2st64_b32 v[14:15], v9 offset0:44 offset1:45
	ds_read2st64_b32 v[48:49], v9 offset0:108 offset1:109
	s_waitcnt lgkmcnt(2)
	v_fma_f32 v13, 0, v11, v13
	v_fmac_f32_e32 v12, v13, v10
	v_mul_f32_e32 v10, v11, v10
	s_waitcnt lgkmcnt(0)
	v_fma_f32 v11, v12, v15, v49
	ds_read2st64_b32 v[12:13], v9 offset0:42 offset1:43
	ds_read2st64_b32 v[50:51], v9 offset0:106 offset1:107
	v_fmac_f32_e32 v48, v11, v14
	v_mov_b32_e32 v58, v15
	s_waitcnt lgkmcnt(0)
	v_fma_f32 v11, v48, v13, v51
	ds_read2st64_b32 v[48:49], v9 offset0:40 offset1:41
	ds_read2st64_b32 v[52:53], v9 offset0:104 offset1:105
	v_fmac_f32_e32 v50, v11, v12
	s_waitcnt lgkmcnt(1)
	v_mov_b32_e32 v62, v49
	s_waitcnt lgkmcnt(0)
	v_fma_f32 v11, v50, v49, v53
	ds_read2st64_b32 v[50:51], v9 offset0:38 offset1:39
	ds_read2st64_b32 v[54:55], v9 offset0:102 offset1:103
	v_fmac_f32_e32 v52, v11, v48
	v_mov_b32_e32 v64, v49
	s_waitcnt lgkmcnt(1)
	v_mov_b32_e32 v59, v50
	s_waitcnt lgkmcnt(0)
	v_fmac_f32_e32 v55, v52, v51
	ds_read2st64_b32 v[52:53], v9 offset0:36 offset1:37
	ds_read2st64_b32 v[56:57], v9 offset0:100 offset1:101
	v_mov_b32_e32 v11, v55
	v_mul_f32_e32 v55, v10, v15
	v_mov_b32_e32 v15, v54
	v_pk_fma_f32 v[10:11], v[10:11], v[58:59], v[14:15]
	v_mul_f32_e32 v54, v55, v14
	v_mov_b32_e32 v55, v11
	v_mov_b32_e32 v10, v13
	s_waitcnt lgkmcnt(1)
	v_mov_b32_e32 v11, v53
	v_pk_mul_f32 v[14:15], v[54:55], v[10:11]
	s_waitcnt lgkmcnt(0)
	v_mov_b32_e32 v13, v57
	v_pk_mul_f32 v[14:15], v[14:15], v[12:13]
	v_pk_fma_f32 v[10:11], v[54:55], v[10:11], v[12:13]
	ds_read2st64_b32 v[12:13], v9 offset0:34 offset1:35
	ds_read2st64_b32 v[54:55], v9 offset0:98 offset1:99
	ds_read2st64_b32 v[58:59], v9 offset0:32 offset1:33
	ds_read2st64_b32 v[60:61], v9 offset0:96 offset1:97
	v_mov_b32_e32 v10, v14
	v_mov_b32_e32 v65, v52
	v_pk_mul_f32 v[14:15], v[14:15], v[62:63]
	v_mov_b32_e32 v49, v56
	v_pk_mul_f32 v[14:15], v[14:15], v[48:49]
	v_pk_fma_f32 v[10:11], v[10:11], v[64:65], v[48:49]
	v_and_b32_e32 v57, 0x1fffffc0, v75
	v_mov_b32_e32 v15, v11
	v_mov_b32_e32 v10, v51
	s_waitcnt lgkmcnt(3)
	v_mov_b32_e32 v11, v13
	v_pk_mul_f32 v[48:49], v[14:15], v[10:11]
	s_waitcnt lgkmcnt(2)
	v_mov_b32_e32 v51, v55
	v_pk_mul_f32 v[48:49], v[48:49], v[50:51]
	v_pk_fma_f32 v[10:11], v[14:15], v[10:11], v[50:51]
	v_mov_b32_e32 v14, v53
	v_mov_b32_e32 v10, v48
	v_mov_b32_e32 v50, v53
	v_mov_b32_e32 v51, v12
	v_pk_mul_f32 v[14:15], v[48:49], v[14:15]
	v_mov_b32_e32 v53, v54
	v_pk_mul_f32 v[14:15], v[14:15], v[52:53]
	v_pk_fma_f32 v[10:11], v[10:11], v[50:51], v[52:53]
	v_lshl_add_u32 v9, v8, 3, s60
	v_mov_b32_e32 v15, v11
	v_mov_b32_e32 v10, v13
	s_waitcnt lgkmcnt(1)
	v_mov_b32_e32 v11, v59
	v_pk_mul_f32 v[48:49], v[14:15], v[10:11]
	s_waitcnt lgkmcnt(0)
	v_mov_b32_e32 v13, v61
	v_pk_mul_f32 v[48:49], v[48:49], v[12:13]
	v_pk_fma_f32 v[10:11], v[14:15], v[10:11], v[12:13]
	v_mov_b32_e32 v12, v59
	v_mov_b32_e32 v10, v48
	v_mov_b32_e32 v14, v59
	v_mov_b32_e32 v15, v58
	v_pk_mul_f32 v[12:13], v[48:49], v[12:13]
	v_mov_b32_e32 v59, v60
	v_pk_mul_f32 v[12:13], v[12:13], v[58:59]
	v_pk_fma_f32 v[10:11], v[10:11], v[14:15], v[58:59]
	v_lshl_add_u32 v57, v57, 3, v9
	v_mov_b32_e32 v13, v11
	ds_write_b64 v57, v[12:13] offset:40960
	s_waitcnt lgkmcnt(0)
	s_barrier
	s_and_saveexec_b64 s[6:7], vcc
	s_cbranch_execz .LBB0_382
	s_lshl_b32 s26, s26, 7
	ds_read_b64 v[14:15], v9 offset:42496
	v_lshl_or_b32 v10, v74, 3, v196
	s_or_b32 s25, s26, s25
	v_add_u32_e32 v10, s60, v10
	s_or_b32 s26, s25, 64
	ds_read_b64 v[48:49], v10 offset:42496
	ds_read2st64_b64 v[10:13], v9 offset0:80 offset1:81
	s_ashr_i32 s27, s26, 31
	s_lshl_b64 s[26:27], s[26:27], 12
	s_mov_b64 s[28:29], s[74:75]
	s_add_u32 s25, s28, s26
	s_waitcnt lgkmcnt(2)
	v_fma_f32 v9, 0, v14, v15
	s_addc_u32 s27, s29, s27
	s_lshl_b32 s26, s23, 3
	s_waitcnt lgkmcnt(1)
	v_fmac_f32_e32 v49, v9, v48
	s_add_u32 s26, s25, s26
	v_mul_f32_e32 v14, v14, v48
	s_waitcnt lgkmcnt(0)
	v_fma_f32 v15, v49, v12, v13
	v_mov_b32_e32 v13, v10
	s_addc_u32 s27, s27, 0
	v_lshlrev_b32_e32 v144, 3, v8
	v_pk_mul_f32 v[48:49], v[14:15], v[12:13]
	v_lshl_add_u64 v[8:9], s[26:27], 0, v[144:145]
	v_pk_mul_f32 v[48:49], v[48:49], v[10:11]
	v_pk_fma_f32 v[10:11], v[14:15], v[12:13], v[10:11]
	v_add_co_u32_e32 v8, vcc, 0x115e0000, v8
	v_mov_b32_e32 v49, v11
	s_nop 0
	v_addc_co_u32_e32 v9, vcc, 0, v9, vcc
	flat_store_dwordx2 v[8:9], v[48:49]
	s_branch .LBB0_382

.LBB0_900:
	v_bfe_u32 v13, v7, 5, 1
	v_bfe_u32 v14, v7, 3, 2
	v_lshlrev_b32_e32 v13, 9, v13
	v_lshl_or_b32 v13, v14, 7, v13
	v_bfe_u32 v14, v7, 6, 4
	v_lshl_or_b32 v13, v14, 3, v13
	v_and_b32_e32 v14, 0xfffffc07, v7
	v_or_b32_e32 v13, v13, v14
	v_sub_u32_e32 v13, v13, v7
	v_lshlrev_b32_e32 v14, 1, v13
	v_ashrrev_i32_e32 v15, 31, v14
	v_bfe_u32 v8, v7, 6, 6
	v_and_b32_e32 v10, 0xfffff000, v7
	v_and_b32_e32 v11, 0xfc0, v6
	v_ashrrev_i32_e32 v9, 31, v10
	v_or3_b32 v8, v10, v11, v8
	s_mov_b64 s[22:23], s[38:39]
	v_lshlrev_b64 v[8:9], 2, v[8:9]
	v_add_u32_e32 v7, s6, v7
	v_lshl_add_u64 v[10:11], s[22:23], 0, v[8:9]
	flat_load_dword v10, v[10:11]
	s_mov_b64 s[22:23], s[42:43]
	v_add_u32_e32 v6, s2, v6
	s_waitcnt vmcnt(0) lgkmcnt(0)
	v_bfe_u32 v11, v10, 16, 1
	v_add3_u32 v12, v10, v11, s83
	v_add_co_u32_e32 v10, vcc, s69, v4
	s_nop 1
	v_addc_co_u32_e32 v11, vcc, -1, v5, vcc
	v_lshl_add_u64 v[10:11], v[10:11], 0, v[14:15]
	flat_store_short_d16_hi v[10:11], v12
	s_nop 0
	v_lshl_add_u64 v[8:9], s[22:23], 0, v[8:9]
	flat_load_dword v8, v[8:9]
	s_mov_b64 s[22:23], s[64:65]
	s_waitcnt vmcnt(0) lgkmcnt(0)
	v_bfe_u32 v9, v8, 16, 1
	v_add3_u32 v10, v8, v9, s83
	v_add_co_u32_e32 v8, vcc, s24, v4
	s_nop 1
	v_addc_co_u32_e32 v9, vcc, -1, v5, vcc
	v_lshl_add_u64 v[8:9], v[8:9], 0, v[14:15]
	flat_store_short_d16_hi v[8:9], v10
	v_cmp_lt_i32_e32 vcc, s25, v7
	v_lshl_add_u64 v[8:9], s[22:23], 0, v[2:3]
	flat_load_dword v8, v[8:9]
	v_lshl_add_u64 v[2:3], v[2:3], 0, s[18:19]
	s_or_b64 s[20:21], vcc, s[20:21]
	s_waitcnt vmcnt(0) lgkmcnt(0)
	v_bfe_u32 v9, v8, 16, 1
	v_add3_u32 v8, v8, v9, s83
	flat_store_short_d16_hi v[4:5], v8
	v_lshl_add_u64 v[4:5], v[4:5], 0, s[12:13]
	s_andn2_b64 exec, exec, s[20:21]
	s_cbranch_execnz .LBB0_900
